# variant: priority raised during load segments instead of MFMA segments, loader VALU removed
# baseline (speedup 1.0000x reference)
; #define PG8_STAGE(bufoff, gbase, voff) do { _Pragma("unroll") for (int _i = 0; _i < 2; ++_i) \
;         __builtin_amdgcn_global_load_lds((const unsigned*)((const char*)(gbase) + (voff)[_i]), (PG8_LAS unsigned*)(lds + (bufoff) + ldsw + _i * 8192), 16, 0, 0); } while (0)
; #define PG8_LDA(dst, b, h) do { _Pragma("unroll") for (int m = 0; m < 4; ++m) _Pragma("unroll") for (int k = 0; k < 2; ++k) dst[m][k] = *(const PG8_LAS bf16x8*)(lds + PG8_SA(b, h) + aoff + m * 2048 + k * 1024); } while (0)
; #define PG8_LDB(dst, b, h) do { _Pragma("unroll") for (int n = 0; n < 2; ++n) _Pragma("unroll") for (int k = 0; k < 2; ++k) dst[n][k] = *(const PG8_LAS bf16x8*)(lds + PG8_SB(b, h) + boff + n * 2048 + k * 1024); } while (0)
; #define PG8_MMA(ai, bj, At, Bt) do { __builtin_amdgcn_s_setprio(1); _Pragma("unroll") for (int m = 0; m < 4; ++m) _Pragma("unroll") for (int n = 0; n < 2; ++n) _Pragma("unroll") for (int k = 0; k < 2; ++k) \
;         acc[ai][bj][m][n] = __builtin_amdgcn_mfma_f32_16x16x32_bf16(Bt[n][k], At[m][k], acc[ai][bj][m][n], 0, 0, 0); __builtin_amdgcn_s_setprio(0); } while (0)
; #define PG8_WAIT_V(n) asm volatile("s_waitcnt vmcnt(" #n ")" ::: "memory")
; #define PG8_BAR __builtin_amdgcn_s_barrier()
; template <class Epi, class Sched, bool ALIGN_EPI = false, bool SP2 = false>
; __device__ __forceinline__ void gemm_phase(PG8_LAS unsigned char* lds, const Gemm g, const Sched& S, const Epi& E) {
;     ...
;         for (int t = 0; t < nt; t += 2) {
;             const bool last = (t == nt - 2);
;             const char* a1 = cA + (size_t)(t + 1) * kstep;
;             const char* a2 = last ? nA : cA + (size_t)(t + 2) * kstep; const char* b2 = last ? nB : cB + (size_t)(t + 2) * kstep;
;             const char* a3 = a2 + kstep; const char* b3 = b2 + kstep;
;             if (last && has_next) S.a_ready(nxt);
;             if constexpr (SP2) {
;             PG8_LDB(B0, 0, 0); PG8_LDB(B1, 0, 1); PG8_SCHED; PG8_LDA(At, 0, 0); PG8_STAGE(PG8_SA(1, 1), a1 + hstep, voffA);
;             PG8_WAIT_V(8); PG8_WAIT_L(0); PG8_BAR; PG8_MMA(0, 0, At, B0); PG8_MMA(0, 1, At, B1); PG8_BAR; PG8_SCHED;
;             PG8_LDA(At, 0, 1); PG8_STAGE(PG8_SB(0, 0), b2, voffB); PG8_STAGE(PG8_SB(0, 1), b2 + hstep, voffB); PG8_STAGE(PG8_SA(0, 0), a2, voffA);
;             PG8_WAIT_V(8); PG8_WAIT_L(0); PG8_BAR; PG8_MMA(1, 0, At, B0); PG8_MMA(1, 1, At, B1); PG8_BAR; PG8_SCHED;
.LBB0_673:
	ds_read_b128 v[148:151], v241 offset:0
	ds_read_b128 v[156:159], v241 offset:1024
	ds_read_b128 v[166:169], v241 offset:2048
	ds_read_b128 v[170:173], v241 offset:3072
	ds_read_b128 v[174:177], v241 offset:16384
	ds_read_b128 v[178:181], v241 offset:17408
	ds_read_b128 v[182:185], v241 offset:18432
	ds_read_b128 v[186:189], v241 offset:19456
	s_add_u32 s20, s22, 0xfff00080
	s_addc_u32 s21, s23, -1
	s_cmp_eq_u32 s35, 60
	s_cselect_b32 s25, s11, s21
	s_cselect_b32 s24, s52, s20
	s_cselect_b32 s21, s13, s34
	s_cselect_b32 s20, s53, s62
	s_add_i32 m0, s19, 0xc000
	ds_read_b128 v[190:193], v161
	ds_read_b128 v[194:197], v161 offset:1024
	ds_read_b128 v[198:201], v161 offset:2048
	ds_read_b128 v[202:205], v161 offset:3072
	ds_read_b128 v[206:209], v161 offset:4096
	ds_read_b128 v[210:213], v161 offset:5120
	ds_read_b128 v[214:217], v161 offset:6144
	ds_read_b128 v[218:221], v161 offset:7168
	global_load_lds_dwordx4 v138, s[22:23]
	s_add_i32 m0, s19, 0xe000
	s_nop 0
	global_load_lds_dwordx4 v140, s[22:23]
	s_waitcnt vmcnt(8)
	s_waitcnt lgkmcnt(0)
	s_barrier
	s_setprio 0
	s_waitcnt lgkmcnt(0)
	v_mfma_f32_16x16x32_bf16 v[118:121], v[148:151], v[190:193], v[118:121]
	v_mfma_f32_16x16x32_bf16 v[114:117], v[166:169], v[190:193], v[114:117]
	v_mfma_f32_16x16x32_bf16 v[102:105], v[148:151], v[198:201], v[102:105]
	v_mfma_f32_16x16x32_bf16 v[98:101], v[166:169], v[198:201], v[98:101]
	v_mfma_f32_16x16x32_bf16 v[86:89], v[148:151], v[206:209], v[86:89]
	v_mfma_f32_16x16x32_bf16 v[82:85], v[166:169], v[206:209], v[82:85]
	v_mfma_f32_16x16x32_bf16 v[70:73], v[148:151], v[214:217], v[70:73]
	v_mfma_f32_16x16x32_bf16 v[66:69], v[166:169], v[214:217], v[66:69]
	v_mfma_f32_16x16x32_bf16 v[118:121], v[156:159], v[194:197], v[118:121]
	v_mfma_f32_16x16x32_bf16 v[114:117], v[170:173], v[194:197], v[114:117]
	v_mfma_f32_16x16x32_bf16 v[102:105], v[156:159], v[202:205], v[102:105]
	v_mfma_f32_16x16x32_bf16 v[98:101], v[170:173], v[202:205], v[98:101]
	v_mfma_f32_16x16x32_bf16 v[86:89], v[156:159], v[210:213], v[86:89]
	v_mfma_f32_16x16x32_bf16 v[82:85], v[170:173], v[210:213], v[82:85]
	v_mfma_f32_16x16x32_bf16 v[70:73], v[156:159], v[218:221], v[70:73]
	v_mfma_f32_16x16x32_bf16 v[66:69], v[170:173], v[218:221], v[66:69]
	v_mfma_f32_16x16x32_bf16 v[126:129], v[174:177], v[190:193], v[126:129]
	v_mfma_f32_16x16x32_bf16 v[122:125], v[182:185], v[190:193], v[122:125]
	v_mfma_f32_16x16x32_bf16 v[110:113], v[174:177], v[198:201], v[110:113]
	v_mfma_f32_16x16x32_bf16 v[106:109], v[182:185], v[198:201], v[106:109]
	v_mfma_f32_16x16x32_bf16 v[94:97], v[174:177], v[206:209], v[94:97]
	v_mfma_f32_16x16x32_bf16 v[90:93], v[182:185], v[206:209], v[90:93]
	v_mfma_f32_16x16x32_bf16 v[78:81], v[174:177], v[214:217], v[78:81]
	v_mfma_f32_16x16x32_bf16 v[74:77], v[182:185], v[214:217], v[74:77]
	v_mfma_f32_16x16x32_bf16 v[126:129], v[178:181], v[194:197], v[126:129]
	v_mfma_f32_16x16x32_bf16 v[122:125], v[186:189], v[194:197], v[122:125]
	v_mfma_f32_16x16x32_bf16 v[110:113], v[178:181], v[202:205], v[110:113]
	v_mfma_f32_16x16x32_bf16 v[106:109], v[186:189], v[202:205], v[106:109]
	v_mfma_f32_16x16x32_bf16 v[94:97], v[178:181], v[210:213], v[94:97]
	v_mfma_f32_16x16x32_bf16 v[90:93], v[186:189], v[210:213], v[90:93]
	v_mfma_f32_16x16x32_bf16 v[78:81], v[178:181], v[218:221], v[78:81]
	v_mfma_f32_16x16x32_bf16 v[74:77], v[186:189], v[218:221], v[74:77]
	s_setprio 1
	s_barrier
	s_add_i32 s63, s43, s26
	s_mov_b32 m0, s63
	ds_read_b128 v[190:193], v161 offset:16384
	ds_read_b128 v[194:197], v161 offset:17408
	ds_read_b128 v[198:201], v161 offset:18432
	ds_read_b128 v[202:205], v161 offset:19456
	ds_read_b128 v[206:209], v161 offset:20480
	ds_read_b128 v[210:213], v161 offset:21504
	ds_read_b128 v[214:217], v161 offset:22528
	ds_read_b128 v[218:221], v161 offset:23552
	global_load_lds_dwordx4 v132, s[20:21]
	s_add_i32 m0, s63, 0x2000
	s_add_u32 s64, s20, 0x100000
	s_addc_u32 s65, s21, 0
	s_add_i32 s63, s46, s26
	global_load_lds_dwordx4 v136, s[20:21]
	s_mov_b32 m0, s63
	s_add_u32 s100, s24, 0x80
	s_addc_u32 s101, s25, 0
	global_load_lds_dwordx4 v132, s[64:65]
	s_add_i32 m0, s63, 0x2000
	s_nop 0
	global_load_lds_dwordx4 v136, s[64:65]
	s_mov_b32 m0, s19
	s_nop 0
	global_load_lds_dwordx4 v130, s[24:25]
	s_mov_b32 m0, s29
	s_nop 0
	global_load_lds_dwordx4 v134, s[24:25]
	s_waitcnt vmcnt(8)
	s_waitcnt lgkmcnt(0)
	s_barrier
	s_setprio 0
	s_waitcnt lgkmcnt(0)
	v_mfma_f32_16x16x32_bf16 v[54:57], v[148:151], v[190:193], v[54:57]
	v_mfma_f32_16x16x32_bf16 v[50:53], v[166:169], v[190:193], v[50:53]
	v_mfma_f32_16x16x32_bf16 v[38:41], v[148:151], v[198:201], v[38:41]
	v_mfma_f32_16x16x32_bf16 v[34:37], v[166:169], v[198:201], v[34:37]
	v_mfma_f32_16x16x32_bf16 v[22:25], v[148:151], v[206:209], v[22:25]
	v_mfma_f32_16x16x32_bf16 v[18:21], v[166:169], v[206:209], v[18:21]
	v_mfma_f32_16x16x32_bf16 v[6:9], v[148:151], v[214:217], v[6:9]
	v_mfma_f32_16x16x32_bf16 v[2:5], v[166:169], v[214:217], v[2:5]
	v_mfma_f32_16x16x32_bf16 v[54:57], v[156:159], v[194:197], v[54:57]
	v_mfma_f32_16x16x32_bf16 v[50:53], v[170:173], v[194:197], v[50:53]
	v_mfma_f32_16x16x32_bf16 v[38:41], v[156:159], v[202:205], v[38:41]
	v_mfma_f32_16x16x32_bf16 v[34:37], v[170:173], v[202:205], v[34:37]
	v_mfma_f32_16x16x32_bf16 v[22:25], v[156:159], v[210:213], v[22:25]
	v_mfma_f32_16x16x32_bf16 v[18:21], v[170:173], v[210:213], v[18:21]
	v_mfma_f32_16x16x32_bf16 v[6:9], v[156:159], v[218:221], v[6:9]
	v_mfma_f32_16x16x32_bf16 v[2:5], v[170:173], v[218:221], v[2:5]
	v_mfma_f32_16x16x32_bf16 v[62:65], v[174:177], v[190:193], v[62:65]
	v_mfma_f32_16x16x32_bf16 v[58:61], v[182:185], v[190:193], v[58:61]
	v_mfma_f32_16x16x32_bf16 v[46:49], v[174:177], v[198:201], v[46:49]
	v_mfma_f32_16x16x32_bf16 v[42:45], v[182:185], v[198:201], v[42:45]
	v_mfma_f32_16x16x32_bf16 v[30:33], v[174:177], v[206:209], v[30:33]
	v_mfma_f32_16x16x32_bf16 v[26:29], v[182:185], v[206:209], v[26:29]
	v_mfma_f32_16x16x32_bf16 v[10:13], v[174:177], v[214:217], v[10:13]
	v_mfma_f32_16x16x32_bf16 v[14:17], v[182:185], v[214:217], v[14:17]
	v_mfma_f32_16x16x32_bf16 v[62:65], v[178:181], v[194:197], v[62:65]
	v_mfma_f32_16x16x32_bf16 v[58:61], v[186:189], v[194:197], v[58:61]
	v_mfma_f32_16x16x32_bf16 v[46:49], v[178:181], v[202:205], v[46:49]
	v_mfma_f32_16x16x32_bf16 v[42:45], v[186:189], v[202:205], v[42:45]
	v_mfma_f32_16x16x32_bf16 v[30:33], v[178:181], v[210:213], v[30:33]
	v_mfma_f32_16x16x32_bf16 v[26:29], v[186:189], v[210:213], v[26:29]
	v_mfma_f32_16x16x32_bf16 v[10:13], v[178:181], v[218:221], v[10:13]
	v_mfma_f32_16x16x32_bf16 v[14:17], v[186:189], v[218:221], v[14:17]
	s_setprio 1
	s_barrier
; #define PG8_STAGE(bufoff, gbase, voff) do { _Pragma("unroll") for (int _i = 0; _i < 2; ++_i) \
;         __builtin_amdgcn_global_load_lds((const unsigned*)((const char*)(gbase) + (voff)[_i]), (PG8_LAS unsigned*)(lds + (bufoff) + ldsw + _i * 8192), 16, 0, 0); } while (0)
; #define PG8_LDA(dst, b, h) do { _Pragma("unroll") for (int m = 0; m < 4; ++m) _Pragma("unroll") for (int k = 0; k < 2; ++k) dst[m][k] = *(const PG8_LAS bf16x8*)(lds + PG8_SA(b, h) + aoff + m * 2048 + k * 1024); } while (0)
; #define PG8_LDB(dst, b, h) do { _Pragma("unroll") for (int n = 0; n < 2; ++n) _Pragma("unroll") for (int k = 0; k < 2; ++k) dst[n][k] = *(const PG8_LAS bf16x8*)(lds + PG8_SB(b, h) + boff + n * 2048 + k * 1024); } while (0)
; #define PG8_MMA(ai, bj, At, Bt) do { __builtin_amdgcn_s_setprio(1); _Pragma("unroll") for (int m = 0; m < 4; ++m) _Pragma("unroll") for (int n = 0; n < 2; ++n) _Pragma("unroll") for (int k = 0; k < 2; ++k) \
;         acc[ai][bj][m][n] = __builtin_amdgcn_mfma_f32_16x16x32_bf16(Bt[n][k], At[m][k], acc[ai][bj][m][n], 0, 0, 0); __builtin_amdgcn_s_setprio(0); } while (0)
; #define PG8_WAIT_V(n) asm volatile("s_waitcnt vmcnt(" #n ")" ::: "memory")
; #define PG8_WAIT_L(n) asm volatile("s_waitcnt lgkmcnt(" #n ")" ::: "memory")
; #define PG8_BAR __builtin_amdgcn_s_barrier()
; #define PG8_SCHED __builtin_amdgcn_sched_barrier(0)
; template <class Epi, class Sched, bool ALIGN_EPI = false, bool SP2 = false>
; __device__ __forceinline__ void gemm_phase(PG8_LAS unsigned char* lds, const Gemm g, const Sched& S, const Epi& E) {
;     ...
;             PG8_LDB(B0, 1, 0); PG8_LDB(B1, 1, 1); PG8_SCHED; PG8_LDA(At, 1, 0); PG8_STAGE(PG8_SA(0, 1), a2 + hstep, voffA);
;             PG8_WAIT_V(8); PG8_WAIT_L(0); PG8_BAR; PG8_MMA(0, 0, At, B0); PG8_MMA(0, 1, At, B1); PG8_BAR; PG8_SCHED;
;             PG8_LDA(At, 1, 1); PG8_STAGE(PG8_SB(1, 0), b3, voffB); PG8_STAGE(PG8_SB(1, 1), b3 + hstep, voffB); PG8_STAGE(PG8_SA(1, 0), a3, voffA);
;             PG8_WAIT_V(8); PG8_WAIT_L(0); PG8_BAR; PG8_MMA(1, 0, At, B0); PG8_MMA(1, 1, At, B1); PG8_BAR; PG8_SCHED;
	s_add_i32 s63, 0, 0x18000
	s_add_i32 s64, 0, 0x1c000
	ds_read_b128 v[148:151], v241 offset:32768
	ds_read_b128 v[156:159], v241 offset:33792
	ds_read_b128 v[166:169], v241 offset:34816
	ds_read_b128 v[170:173], v241 offset:35840
	ds_read_b128 v[174:177], v241 offset:49152
	ds_read_b128 v[178:181], v241 offset:50176
	ds_read_b128 v[182:185], v241 offset:51200
	ds_read_b128 v[186:189], v241 offset:52224
	s_add_u32 s24, s24, 0x100000
	s_addc_u32 s25, s25, 0
	s_mov_b32 m0, s30
	ds_read_b128 v[190:193], v161 offset:32768
	ds_read_b128 v[194:197], v161 offset:33792
	ds_read_b128 v[198:201], v161 offset:34816
	ds_read_b128 v[202:205], v161 offset:35840
	ds_read_b128 v[206:209], v161 offset:36864
	ds_read_b128 v[210:213], v161 offset:37888
	ds_read_b128 v[214:217], v161 offset:38912
	ds_read_b128 v[218:221], v161 offset:39936
	global_load_lds_dwordx4 v130, s[24:25]
	s_mov_b32 m0, s31
	s_nop 0
	global_load_lds_dwordx4 v134, s[24:25]
	s_waitcnt vmcnt(8)
	s_waitcnt lgkmcnt(0)
	s_barrier
	s_setprio 0
	s_waitcnt lgkmcnt(0)
	v_mfma_f32_16x16x32_bf16 v[118:121], v[148:151], v[190:193], v[118:121]
	v_mfma_f32_16x16x32_bf16 v[114:117], v[166:169], v[190:193], v[114:117]
	v_mfma_f32_16x16x32_bf16 v[102:105], v[148:151], v[198:201], v[102:105]
	v_mfma_f32_16x16x32_bf16 v[98:101], v[166:169], v[198:201], v[98:101]
	v_mfma_f32_16x16x32_bf16 v[86:89], v[148:151], v[206:209], v[86:89]
	v_mfma_f32_16x16x32_bf16 v[82:85], v[166:169], v[206:209], v[82:85]
	v_mfma_f32_16x16x32_bf16 v[70:73], v[148:151], v[214:217], v[70:73]
	v_mfma_f32_16x16x32_bf16 v[66:69], v[166:169], v[214:217], v[66:69]
	v_mfma_f32_16x16x32_bf16 v[118:121], v[156:159], v[194:197], v[118:121]
	v_mfma_f32_16x16x32_bf16 v[114:117], v[170:173], v[194:197], v[114:117]
	v_mfma_f32_16x16x32_bf16 v[102:105], v[156:159], v[202:205], v[102:105]
	v_mfma_f32_16x16x32_bf16 v[98:101], v[170:173], v[202:205], v[98:101]
	v_mfma_f32_16x16x32_bf16 v[86:89], v[156:159], v[210:213], v[86:89]
	v_mfma_f32_16x16x32_bf16 v[82:85], v[170:173], v[210:213], v[82:85]
	v_mfma_f32_16x16x32_bf16 v[70:73], v[156:159], v[218:221], v[70:73]
	v_mfma_f32_16x16x32_bf16 v[66:69], v[170:173], v[218:221], v[66:69]
	v_mfma_f32_16x16x32_bf16 v[126:129], v[174:177], v[190:193], v[126:129]
	v_mfma_f32_16x16x32_bf16 v[122:125], v[182:185], v[190:193], v[122:125]
	v_mfma_f32_16x16x32_bf16 v[110:113], v[174:177], v[198:201], v[110:113]
	v_mfma_f32_16x16x32_bf16 v[106:109], v[182:185], v[198:201], v[106:109]
	v_mfma_f32_16x16x32_bf16 v[94:97], v[174:177], v[206:209], v[94:97]
	v_mfma_f32_16x16x32_bf16 v[90:93], v[182:185], v[206:209], v[90:93]
	v_mfma_f32_16x16x32_bf16 v[78:81], v[174:177], v[214:217], v[78:81]
	v_mfma_f32_16x16x32_bf16 v[74:77], v[182:185], v[214:217], v[74:77]
	v_mfma_f32_16x16x32_bf16 v[126:129], v[178:181], v[194:197], v[126:129]
	v_mfma_f32_16x16x32_bf16 v[122:125], v[186:189], v[194:197], v[122:125]
	v_mfma_f32_16x16x32_bf16 v[110:113], v[178:181], v[202:205], v[110:113]
	v_mfma_f32_16x16x32_bf16 v[106:109], v[186:189], v[202:205], v[106:109]
	v_mfma_f32_16x16x32_bf16 v[94:97], v[178:181], v[210:213], v[94:97]
	v_mfma_f32_16x16x32_bf16 v[90:93], v[186:189], v[210:213], v[90:93]
	v_mfma_f32_16x16x32_bf16 v[78:81], v[178:181], v[218:221], v[78:81]
	v_mfma_f32_16x16x32_bf16 v[74:77], v[186:189], v[218:221], v[74:77]
	s_setprio 1
	s_barrier
	s_add_i32 s24, s63, s26
	s_add_i32 m0, s24, 0xffffff80
	ds_read_b128 v[190:193], v161 offset:49152
	ds_read_b128 v[194:197], v161 offset:50176
	ds_read_b128 v[198:201], v161 offset:51200
	ds_read_b128 v[202:205], v161 offset:52224
	ds_read_b128 v[206:209], v161 offset:53248
	ds_read_b128 v[210:213], v161 offset:54272
	ds_read_b128 v[214:217], v161 offset:55296
	ds_read_b128 v[218:221], v161 offset:56320
	global_load_lds_dwordx4 v132, s[20:21] offset:128
	s_add_i32 m0, s24, 0x1f80
	s_add_i32 s24, s64, s26
	global_load_lds_dwordx4 v136, s[20:21] offset:128
	s_add_u32 s20, s20, 0x100080
	s_addc_u32 s21, s21, 0
	s_mov_b32 m0, s24
	s_nop 0
	global_load_lds_dwordx4 v132, s[20:21]
	s_add_i32 m0, s24, 0x2000
	s_nop 0
	global_load_lds_dwordx4 v136, s[20:21]
	s_mov_b32 m0, s40
	s_nop 0
	global_load_lds_dwordx4 v130, s[100:101]
	s_mov_b32 m0, s41
	s_nop 0
	global_load_lds_dwordx4 v134, s[100:101]
	s_waitcnt vmcnt(8)
	s_waitcnt lgkmcnt(0)
	s_barrier
	s_setprio 0
	s_waitcnt lgkmcnt(0)
	v_mfma_f32_16x16x32_bf16 v[54:57], v[148:151], v[190:193], v[54:57]
	v_mfma_f32_16x16x32_bf16 v[50:53], v[166:169], v[190:193], v[50:53]
	v_mfma_f32_16x16x32_bf16 v[38:41], v[148:151], v[198:201], v[38:41]
	v_mfma_f32_16x16x32_bf16 v[34:37], v[166:169], v[198:201], v[34:37]
	v_mfma_f32_16x16x32_bf16 v[22:25], v[148:151], v[206:209], v[22:25]
	v_mfma_f32_16x16x32_bf16 v[18:21], v[166:169], v[206:209], v[18:21]
	v_mfma_f32_16x16x32_bf16 v[6:9], v[148:151], v[214:217], v[6:9]
	v_mfma_f32_16x16x32_bf16 v[2:5], v[166:169], v[214:217], v[2:5]
	v_mfma_f32_16x16x32_bf16 v[54:57], v[156:159], v[194:197], v[54:57]
	v_mfma_f32_16x16x32_bf16 v[50:53], v[170:173], v[194:197], v[50:53]
	v_mfma_f32_16x16x32_bf16 v[38:41], v[156:159], v[202:205], v[38:41]
	v_mfma_f32_16x16x32_bf16 v[34:37], v[170:173], v[202:205], v[34:37]
	v_mfma_f32_16x16x32_bf16 v[22:25], v[156:159], v[210:213], v[22:25]
	v_mfma_f32_16x16x32_bf16 v[18:21], v[170:173], v[210:213], v[18:21]
	v_mfma_f32_16x16x32_bf16 v[6:9], v[156:159], v[218:221], v[6:9]
	v_mfma_f32_16x16x32_bf16 v[2:5], v[170:173], v[218:221], v[2:5]
	v_mfma_f32_16x16x32_bf16 v[62:65], v[174:177], v[190:193], v[62:65]
	v_mfma_f32_16x16x32_bf16 v[58:61], v[182:185], v[190:193], v[58:61]
	v_mfma_f32_16x16x32_bf16 v[46:49], v[174:177], v[198:201], v[46:49]
	v_mfma_f32_16x16x32_bf16 v[42:45], v[182:185], v[198:201], v[42:45]
	v_mfma_f32_16x16x32_bf16 v[30:33], v[174:177], v[206:209], v[30:33]
	v_mfma_f32_16x16x32_bf16 v[26:29], v[182:185], v[206:209], v[26:29]
	v_mfma_f32_16x16x32_bf16 v[10:13], v[174:177], v[214:217], v[10:13]
	v_mfma_f32_16x16x32_bf16 v[14:17], v[182:185], v[214:217], v[14:17]
	v_mfma_f32_16x16x32_bf16 v[62:65], v[178:181], v[194:197], v[62:65]
	v_mfma_f32_16x16x32_bf16 v[58:61], v[186:189], v[194:197], v[58:61]
	v_mfma_f32_16x16x32_bf16 v[46:49], v[178:181], v[202:205], v[46:49]
	v_mfma_f32_16x16x32_bf16 v[42:45], v[186:189], v[202:205], v[42:45]
	v_mfma_f32_16x16x32_bf16 v[30:33], v[178:181], v[210:213], v[30:33]
	v_mfma_f32_16x16x32_bf16 v[26:29], v[186:189], v[210:213], v[26:29]
	v_mfma_f32_16x16x32_bf16 v[10:13], v[178:181], v[218:221], v[10:13]
	v_mfma_f32_16x16x32_bf16 v[14:17], v[186:189], v[218:221], v[14:17]
	s_setprio 1
	s_barrier
	s_add_i32 s35, s35, 2
	s_add_u32 s22, s22, 0x100
	s_addc_u32 s23, s23, 0
	s_add_u32 s62, s62, 0x100
	s_addc_u32 s34, s34, 0
	s_cmp_gt_u32 s35, 61
	s_cbranch_scc0 .LBB0_673
	s_and_b64 vcc, exec, s[8:9]
	s_cbranch_vccz .LBB0_676
	s_barrier

; #define PG8_STAGE(bufoff, gbase, voff) do { _Pragma("unroll") for (int _i = 0; _i < 2; ++_i) \
;         __builtin_amdgcn_global_load_lds((const unsigned*)((const char*)(gbase) + (voff)[_i]), (PG8_LAS unsigned*)(lds + (bufoff) + ldsw + _i * 8192), 16, 0, 0); } while (0)
; #define PG8_LDA(dst, b, h) do { _Pragma("unroll") for (int m = 0; m < 4; ++m) _Pragma("unroll") for (int k = 0; k < 2; ++k) dst[m][k] = *(const PG8_LAS bf16x8*)(lds + PG8_SA(b, h) + aoff + m * 2048 + k * 1024); } while (0)
; #define PG8_LDB(dst, b, h) do { _Pragma("unroll") for (int n = 0; n < 2; ++n) _Pragma("unroll") for (int k = 0; k < 2; ++k) dst[n][k] = *(const PG8_LAS bf16x8*)(lds + PG8_SB(b, h) + boff + n * 2048 + k * 1024); } while (0)
; #define PG8_MMA(ai, bj, At, Bt) do { __builtin_amdgcn_s_setprio(1); _Pragma("unroll") for (int m = 0; m < 4; ++m) _Pragma("unroll") for (int n = 0; n < 2; ++n) _Pragma("unroll") for (int k = 0; k < 2; ++k) \
;         acc[ai][bj][m][n] = __builtin_amdgcn_mfma_f32_16x16x32_bf16(Bt[n][k], At[m][k], acc[ai][bj][m][n], 0, 0, 0); __builtin_amdgcn_s_setprio(0); } while (0)
; #define PG8_WAIT_V(n) asm volatile("s_waitcnt vmcnt(" #n ")" ::: "memory")
; #define PG8_BAR __builtin_amdgcn_s_barrier()
; template <class Epi, class Sched, bool ALIGN_EPI = false, bool SP2 = false>
; __device__ __forceinline__ void gemm_phase(PG8_LAS unsigned char* lds, const Gemm g, const Sched& S, const Epi& E) {
;     ...
;         for (int t = 0; t < nt; t += 2) {
;             const bool last = (t == nt - 2);
;             const char* a1 = cA + (size_t)(t + 1) * kstep;
;             const char* a2 = last ? nA : cA + (size_t)(t + 2) * kstep; const char* b2 = last ? nB : cB + (size_t)(t + 2) * kstep;
;             const char* a3 = a2 + kstep; const char* b3 = b2 + kstep;
;             if (last && has_next) S.a_ready(nxt);
;             if constexpr (SP2) {
;             PG8_LDB(B0, 0, 0); PG8_LDB(B1, 0, 1); PG8_SCHED; PG8_LDA(At, 0, 0); PG8_STAGE(PG8_SA(1, 1), a1 + hstep, voffA);
;             PG8_WAIT_V(8); PG8_WAIT_L(0); PG8_BAR; PG8_MMA(0, 0, At, B0); PG8_MMA(0, 1, At, B1); PG8_BAR; PG8_SCHED;
;             PG8_LDA(At, 0, 1); PG8_STAGE(PG8_SB(0, 0), b2, voffB); PG8_STAGE(PG8_SB(0, 1), b2 + hstep, voffB); PG8_STAGE(PG8_SA(0, 0), a2, voffA);
;             PG8_WAIT_V(8); PG8_WAIT_L(0); PG8_BAR; PG8_MMA(1, 0, At, B0); PG8_MMA(1, 1, At, B1); PG8_BAR; PG8_SCHED;
.LBB0_1039:
	ds_read_b128 v[130:133], v241 offset:0
	ds_read_b128 v[134:137], v241 offset:1024
	ds_read_b128 v[138:141], v241 offset:2048
	ds_read_b128 v[142:145], v241 offset:3072
	ds_read_b128 v[146:149], v241 offset:16384
	ds_read_b128 v[150:153], v241 offset:17408
	ds_read_b128 v[172:175], v241 offset:18432
	ds_read_b128 v[176:179], v241 offset:19456
	s_add_u32 s24, s26, 0xfff00080
	s_addc_u32 s25, s27, -1
	s_cmp_eq_u32 s68, 60
	s_cselect_b32 s29, s15, s25
	s_cselect_b32 s28, s21, s24
	s_cselect_b32 s25, s13, s67
	s_cselect_b32 s24, s65, s66
	s_add_i32 m0, s23, 0xc000
	ds_read_b128 v[180:183], v185
	ds_read_b128 v[188:191], v185 offset:1024
	ds_read_b128 v[192:195], v185 offset:2048
	ds_read_b128 v[196:199], v185 offset:3072
	ds_read_b128 v[200:203], v185 offset:4096
	ds_read_b128 v[204:207], v185 offset:5120
	ds_read_b128 v[208:211], v185 offset:6144
	ds_read_b128 v[212:215], v185 offset:7168
	global_load_lds_dwordx4 v162, s[26:27]
	s_add_i32 m0, s23, 0xe000
	s_nop 0
	global_load_lds_dwordx4 v166, s[26:27]
	s_waitcnt vmcnt(8)
	s_waitcnt lgkmcnt(0)
	s_barrier
	s_setprio 0
	s_waitcnt lgkmcnt(0)
	v_mfma_f32_16x16x32_bf16 v[114:117], v[130:133], v[180:183], v[114:117]
	v_mfma_f32_16x16x32_bf16 v[118:121], v[138:141], v[180:183], v[118:121]
	v_mfma_f32_16x16x32_bf16 v[106:109], v[130:133], v[192:195], v[106:109]
	v_mfma_f32_16x16x32_bf16 v[98:101], v[138:141], v[192:195], v[98:101]
	v_mfma_f32_16x16x32_bf16 v[90:93], v[130:133], v[200:203], v[90:93]
	v_mfma_f32_16x16x32_bf16 v[82:85], v[138:141], v[200:203], v[82:85]
	v_mfma_f32_16x16x32_bf16 v[74:77], v[130:133], v[208:211], v[74:77]
	v_mfma_f32_16x16x32_bf16 v[66:69], v[138:141], v[208:211], v[66:69]
	v_mfma_f32_16x16x32_bf16 v[114:117], v[134:137], v[188:191], v[114:117]
	v_mfma_f32_16x16x32_bf16 v[118:121], v[142:145], v[188:191], v[118:121]
	v_mfma_f32_16x16x32_bf16 v[106:109], v[134:137], v[196:199], v[106:109]
	v_mfma_f32_16x16x32_bf16 v[98:101], v[142:145], v[196:199], v[98:101]
	v_mfma_f32_16x16x32_bf16 v[90:93], v[134:137], v[204:207], v[90:93]
	v_mfma_f32_16x16x32_bf16 v[82:85], v[142:145], v[204:207], v[82:85]
	v_mfma_f32_16x16x32_bf16 v[74:77], v[134:137], v[212:215], v[74:77]
	v_mfma_f32_16x16x32_bf16 v[66:69], v[142:145], v[212:215], v[66:69]
	v_mfma_f32_16x16x32_bf16 v[122:125], v[146:149], v[180:183], v[122:125]
	v_mfma_f32_16x16x32_bf16 v[126:129], v[172:175], v[180:183], v[126:129]
	v_mfma_f32_16x16x32_bf16 v[110:113], v[146:149], v[192:195], v[110:113]
	v_mfma_f32_16x16x32_bf16 v[102:105], v[172:175], v[192:195], v[102:105]
	v_mfma_f32_16x16x32_bf16 v[94:97], v[146:149], v[200:203], v[94:97]
	v_mfma_f32_16x16x32_bf16 v[86:89], v[172:175], v[200:203], v[86:89]
	v_mfma_f32_16x16x32_bf16 v[78:81], v[146:149], v[208:211], v[78:81]
	v_mfma_f32_16x16x32_bf16 v[70:73], v[172:175], v[208:211], v[70:73]
	v_mfma_f32_16x16x32_bf16 v[122:125], v[150:153], v[188:191], v[122:125]
	v_mfma_f32_16x16x32_bf16 v[126:129], v[176:179], v[188:191], v[126:129]
	v_mfma_f32_16x16x32_bf16 v[110:113], v[150:153], v[196:199], v[110:113]
	v_mfma_f32_16x16x32_bf16 v[102:105], v[176:179], v[196:199], v[102:105]
	v_mfma_f32_16x16x32_bf16 v[94:97], v[150:153], v[204:207], v[94:97]
	v_mfma_f32_16x16x32_bf16 v[86:89], v[176:179], v[204:207], v[86:89]
	v_mfma_f32_16x16x32_bf16 v[78:81], v[150:153], v[212:215], v[78:81]
	v_mfma_f32_16x16x32_bf16 v[70:73], v[176:179], v[212:215], v[70:73]
	s_setprio 1
	s_barrier
	s_add_i32 s33, s62, s36
	s_mov_b32 m0, s33
	ds_read_b128 v[180:183], v185 offset:16384
	ds_read_b128 v[188:191], v185 offset:17408
	ds_read_b128 v[192:195], v185 offset:18432
	ds_read_b128 v[196:199], v185 offset:19456
	ds_read_b128 v[200:203], v185 offset:20480
	ds_read_b128 v[204:207], v185 offset:21504
	ds_read_b128 v[208:211], v185 offset:22528
	ds_read_b128 v[212:215], v185 offset:23552
	global_load_lds_dwordx4 v156, s[24:25]
	s_add_i32 m0, s33, 0x2000
	s_add_u32 s72, s24, 0x100000
	s_addc_u32 s73, s25, 0
	s_add_i32 s33, s63, s36
	global_load_lds_dwordx4 v160, s[24:25]
	s_mov_b32 m0, s33
	s_add_u32 s100, s28, 0x80
	s_addc_u32 s101, s29, 0
	global_load_lds_dwordx4 v156, s[72:73]
	s_add_i32 m0, s33, 0x2000
	s_nop 0
	global_load_lds_dwordx4 v160, s[72:73]
	s_mov_b32 m0, s23
	s_nop 0
	global_load_lds_dwordx4 v154, s[28:29]
	s_mov_b32 m0, s37
	s_nop 0
	global_load_lds_dwordx4 v158, s[28:29]
	s_waitcnt vmcnt(8)
	s_waitcnt lgkmcnt(0)
	s_barrier
	s_setprio 0
	s_waitcnt lgkmcnt(0)
	v_mfma_f32_16x16x32_bf16 v[58:61], v[130:133], v[180:183], v[58:61]
	v_mfma_f32_16x16x32_bf16 v[54:57], v[138:141], v[180:183], v[54:57]
	v_mfma_f32_16x16x32_bf16 v[42:45], v[130:133], v[192:195], v[42:45]
	v_mfma_f32_16x16x32_bf16 v[34:37], v[138:141], v[192:195], v[34:37]
	v_mfma_f32_16x16x32_bf16 v[26:29], v[130:133], v[200:203], v[26:29]
	v_mfma_f32_16x16x32_bf16 v[18:21], v[138:141], v[200:203], v[18:21]
	v_mfma_f32_16x16x32_bf16 v[6:9], v[130:133], v[208:211], v[6:9]
	v_mfma_f32_16x16x32_bf16 v[2:5], v[138:141], v[208:211], v[2:5]
	v_mfma_f32_16x16x32_bf16 v[58:61], v[134:137], v[188:191], v[58:61]
	v_mfma_f32_16x16x32_bf16 v[54:57], v[142:145], v[188:191], v[54:57]
	v_mfma_f32_16x16x32_bf16 v[42:45], v[134:137], v[196:199], v[42:45]
	v_mfma_f32_16x16x32_bf16 v[34:37], v[142:145], v[196:199], v[34:37]
	v_mfma_f32_16x16x32_bf16 v[26:29], v[134:137], v[204:207], v[26:29]
	v_mfma_f32_16x16x32_bf16 v[18:21], v[142:145], v[204:207], v[18:21]
	v_mfma_f32_16x16x32_bf16 v[6:9], v[134:137], v[212:215], v[6:9]
	v_mfma_f32_16x16x32_bf16 v[2:5], v[142:145], v[212:215], v[2:5]
	v_mfma_f32_16x16x32_bf16 v[62:65], v[146:149], v[180:183], v[62:65]
	v_mfma_f32_16x16x32_bf16 v[50:53], v[172:175], v[180:183], v[50:53]
	v_mfma_f32_16x16x32_bf16 v[46:49], v[146:149], v[192:195], v[46:49]
	v_mfma_f32_16x16x32_bf16 v[38:41], v[172:175], v[192:195], v[38:41]
	v_mfma_f32_16x16x32_bf16 v[30:33], v[146:149], v[200:203], v[30:33]
	v_mfma_f32_16x16x32_bf16 v[22:25], v[172:175], v[200:203], v[22:25]
	v_mfma_f32_16x16x32_bf16 v[10:13], v[146:149], v[208:211], v[10:13]
	v_mfma_f32_16x16x32_bf16 v[14:17], v[172:175], v[208:211], v[14:17]
	v_mfma_f32_16x16x32_bf16 v[62:65], v[150:153], v[188:191], v[62:65]
	v_mfma_f32_16x16x32_bf16 v[50:53], v[176:179], v[188:191], v[50:53]
	v_mfma_f32_16x16x32_bf16 v[46:49], v[150:153], v[196:199], v[46:49]
	v_mfma_f32_16x16x32_bf16 v[38:41], v[176:179], v[196:199], v[38:41]
	v_mfma_f32_16x16x32_bf16 v[30:33], v[150:153], v[204:207], v[30:33]
	v_mfma_f32_16x16x32_bf16 v[22:25], v[176:179], v[204:207], v[22:25]
	v_mfma_f32_16x16x32_bf16 v[10:13], v[150:153], v[212:215], v[10:13]
	v_mfma_f32_16x16x32_bf16 v[14:17], v[176:179], v[212:215], v[14:17]
	s_setprio 1
	s_barrier
; #define PG8_STAGE(bufoff, gbase, voff) do { _Pragma("unroll") for (int _i = 0; _i < 2; ++_i) \
;         __builtin_amdgcn_global_load_lds((const unsigned*)((const char*)(gbase) + (voff)[_i]), (PG8_LAS unsigned*)(lds + (bufoff) + ldsw + _i * 8192), 16, 0, 0); } while (0)
; #define PG8_LDA(dst, b, h) do { _Pragma("unroll") for (int m = 0; m < 4; ++m) _Pragma("unroll") for (int k = 0; k < 2; ++k) dst[m][k] = *(const PG8_LAS bf16x8*)(lds + PG8_SA(b, h) + aoff + m * 2048 + k * 1024); } while (0)
; #define PG8_LDB(dst, b, h) do { _Pragma("unroll") for (int n = 0; n < 2; ++n) _Pragma("unroll") for (int k = 0; k < 2; ++k) dst[n][k] = *(const PG8_LAS bf16x8*)(lds + PG8_SB(b, h) + boff + n * 2048 + k * 1024); } while (0)
; #define PG8_MMA(ai, bj, At, Bt) do { __builtin_amdgcn_s_setprio(1); _Pragma("unroll") for (int m = 0; m < 4; ++m) _Pragma("unroll") for (int n = 0; n < 2; ++n) _Pragma("unroll") for (int k = 0; k < 2; ++k) \
;         acc[ai][bj][m][n] = __builtin_amdgcn_mfma_f32_16x16x32_bf16(Bt[n][k], At[m][k], acc[ai][bj][m][n], 0, 0, 0); __builtin_amdgcn_s_setprio(0); } while (0)
; #define PG8_WAIT_V(n) asm volatile("s_waitcnt vmcnt(" #n ")" ::: "memory")
; #define PG8_WAIT_L(n) asm volatile("s_waitcnt lgkmcnt(" #n ")" ::: "memory")
; #define PG8_BAR __builtin_amdgcn_s_barrier()
; #define PG8_SCHED __builtin_amdgcn_sched_barrier(0)
; template <class Epi, class Sched, bool ALIGN_EPI = false, bool SP2 = false>
; __device__ __forceinline__ void gemm_phase(PG8_LAS unsigned char* lds, const Gemm g, const Sched& S, const Epi& E) {
;     ...
;             PG8_LDB(B0, 1, 0); PG8_LDB(B1, 1, 1); PG8_SCHED; PG8_LDA(At, 1, 0); PG8_STAGE(PG8_SA(0, 1), a2 + hstep, voffA);
;             PG8_WAIT_V(8); PG8_WAIT_L(0); PG8_BAR; PG8_MMA(0, 0, At, B0); PG8_MMA(0, 1, At, B1); PG8_BAR; PG8_SCHED;
;             PG8_LDA(At, 1, 1); PG8_STAGE(PG8_SB(1, 0), b3, voffB); PG8_STAGE(PG8_SB(1, 1), b3 + hstep, voffB); PG8_STAGE(PG8_SA(1, 0), a3, voffA);
;             PG8_WAIT_V(8); PG8_WAIT_L(0); PG8_BAR; PG8_MMA(1, 0, At, B0); PG8_MMA(1, 1, At, B1); PG8_BAR; PG8_SCHED;
	s_add_i32 s33, 0, 0x18000
	s_add_i32 s42, 0, 0x1c000
	ds_read_b128 v[130:133], v241 offset:32768
	ds_read_b128 v[134:137], v241 offset:33792
	ds_read_b128 v[138:141], v241 offset:34816
	ds_read_b128 v[142:145], v241 offset:35840
	ds_read_b128 v[146:149], v241 offset:49152
	ds_read_b128 v[150:153], v241 offset:50176
	ds_read_b128 v[172:175], v241 offset:51200
	ds_read_b128 v[176:179], v241 offset:52224
	s_add_u32 s28, s28, 0x100000
	s_addc_u32 s29, s29, 0
	s_mov_b32 m0, s40
	ds_read_b128 v[180:183], v185 offset:32768
	ds_read_b128 v[188:191], v185 offset:33792
	ds_read_b128 v[192:195], v185 offset:34816
	ds_read_b128 v[196:199], v185 offset:35840
	ds_read_b128 v[200:203], v185 offset:36864
	ds_read_b128 v[204:207], v185 offset:37888
	ds_read_b128 v[208:211], v185 offset:38912
	ds_read_b128 v[212:215], v185 offset:39936
	global_load_lds_dwordx4 v154, s[28:29]
	s_mov_b32 m0, s41
	s_nop 0
	global_load_lds_dwordx4 v158, s[28:29]
	s_waitcnt vmcnt(8)
	s_waitcnt lgkmcnt(0)
	s_barrier
	s_setprio 0
	s_waitcnt lgkmcnt(0)
	v_mfma_f32_16x16x32_bf16 v[114:117], v[130:133], v[180:183], v[114:117]
	v_mfma_f32_16x16x32_bf16 v[118:121], v[138:141], v[180:183], v[118:121]
	v_mfma_f32_16x16x32_bf16 v[106:109], v[130:133], v[192:195], v[106:109]
	v_mfma_f32_16x16x32_bf16 v[98:101], v[138:141], v[192:195], v[98:101]
	v_mfma_f32_16x16x32_bf16 v[90:93], v[130:133], v[200:203], v[90:93]
	v_mfma_f32_16x16x32_bf16 v[82:85], v[138:141], v[200:203], v[82:85]
	v_mfma_f32_16x16x32_bf16 v[74:77], v[130:133], v[208:211], v[74:77]
	v_mfma_f32_16x16x32_bf16 v[66:69], v[138:141], v[208:211], v[66:69]
	v_mfma_f32_16x16x32_bf16 v[114:117], v[134:137], v[188:191], v[114:117]
	v_mfma_f32_16x16x32_bf16 v[118:121], v[142:145], v[188:191], v[118:121]
	v_mfma_f32_16x16x32_bf16 v[106:109], v[134:137], v[196:199], v[106:109]
	v_mfma_f32_16x16x32_bf16 v[98:101], v[142:145], v[196:199], v[98:101]
	v_mfma_f32_16x16x32_bf16 v[90:93], v[134:137], v[204:207], v[90:93]
	v_mfma_f32_16x16x32_bf16 v[82:85], v[142:145], v[204:207], v[82:85]
	v_mfma_f32_16x16x32_bf16 v[74:77], v[134:137], v[212:215], v[74:77]
	v_mfma_f32_16x16x32_bf16 v[66:69], v[142:145], v[212:215], v[66:69]
	v_mfma_f32_16x16x32_bf16 v[122:125], v[146:149], v[180:183], v[122:125]
	v_mfma_f32_16x16x32_bf16 v[126:129], v[172:175], v[180:183], v[126:129]
	v_mfma_f32_16x16x32_bf16 v[110:113], v[146:149], v[192:195], v[110:113]
	v_mfma_f32_16x16x32_bf16 v[102:105], v[172:175], v[192:195], v[102:105]
	v_mfma_f32_16x16x32_bf16 v[94:97], v[146:149], v[200:203], v[94:97]
	v_mfma_f32_16x16x32_bf16 v[86:89], v[172:175], v[200:203], v[86:89]
	v_mfma_f32_16x16x32_bf16 v[78:81], v[146:149], v[208:211], v[78:81]
	v_mfma_f32_16x16x32_bf16 v[70:73], v[172:175], v[208:211], v[70:73]
	v_mfma_f32_16x16x32_bf16 v[122:125], v[150:153], v[188:191], v[122:125]
	v_mfma_f32_16x16x32_bf16 v[126:129], v[176:179], v[188:191], v[126:129]
	v_mfma_f32_16x16x32_bf16 v[110:113], v[150:153], v[196:199], v[110:113]
	v_mfma_f32_16x16x32_bf16 v[102:105], v[176:179], v[196:199], v[102:105]
	v_mfma_f32_16x16x32_bf16 v[94:97], v[150:153], v[204:207], v[94:97]
	v_mfma_f32_16x16x32_bf16 v[86:89], v[176:179], v[204:207], v[86:89]
	v_mfma_f32_16x16x32_bf16 v[78:81], v[150:153], v[212:215], v[78:81]
	v_mfma_f32_16x16x32_bf16 v[70:73], v[176:179], v[212:215], v[70:73]
	s_setprio 1
	s_barrier
	s_add_i32 s28, s33, s36
	s_add_i32 m0, s28, 0xffffff80
	ds_read_b128 v[180:183], v185 offset:49152
	ds_read_b128 v[188:191], v185 offset:50176
	ds_read_b128 v[192:195], v185 offset:51200
	ds_read_b128 v[196:199], v185 offset:52224
	ds_read_b128 v[200:203], v185 offset:53248
	ds_read_b128 v[204:207], v185 offset:54272
	ds_read_b128 v[208:211], v185 offset:55296
	ds_read_b128 v[212:215], v185 offset:56320
	global_load_lds_dwordx4 v156, s[24:25] offset:128
	s_add_i32 m0, s28, 0x1f80
	s_add_i32 s28, s42, s36
	global_load_lds_dwordx4 v160, s[24:25] offset:128
	s_add_u32 s24, s24, 0x100080
	s_addc_u32 s25, s25, 0
	s_mov_b32 m0, s28
	s_nop 0
	global_load_lds_dwordx4 v156, s[24:25]
	s_add_i32 m0, s28, 0x2000
	s_nop 0
	global_load_lds_dwordx4 v160, s[24:25]
	s_mov_b32 m0, s46
	s_nop 0
	global_load_lds_dwordx4 v154, s[100:101]
	s_mov_b32 m0, s47
	s_nop 0
	global_load_lds_dwordx4 v158, s[100:101]
	s_waitcnt vmcnt(8)
	s_waitcnt lgkmcnt(0)
	s_barrier
	s_setprio 0
	s_waitcnt lgkmcnt(0)
	v_mfma_f32_16x16x32_bf16 v[58:61], v[130:133], v[180:183], v[58:61]
	v_mfma_f32_16x16x32_bf16 v[54:57], v[138:141], v[180:183], v[54:57]
	v_mfma_f32_16x16x32_bf16 v[42:45], v[130:133], v[192:195], v[42:45]
	v_mfma_f32_16x16x32_bf16 v[34:37], v[138:141], v[192:195], v[34:37]
	v_mfma_f32_16x16x32_bf16 v[26:29], v[130:133], v[200:203], v[26:29]
	v_mfma_f32_16x16x32_bf16 v[18:21], v[138:141], v[200:203], v[18:21]
	v_mfma_f32_16x16x32_bf16 v[6:9], v[130:133], v[208:211], v[6:9]
	v_mfma_f32_16x16x32_bf16 v[2:5], v[138:141], v[208:211], v[2:5]
	v_mfma_f32_16x16x32_bf16 v[58:61], v[134:137], v[188:191], v[58:61]
	v_mfma_f32_16x16x32_bf16 v[54:57], v[142:145], v[188:191], v[54:57]
	v_mfma_f32_16x16x32_bf16 v[42:45], v[134:137], v[196:199], v[42:45]
	v_mfma_f32_16x16x32_bf16 v[34:37], v[142:145], v[196:199], v[34:37]
	v_mfma_f32_16x16x32_bf16 v[26:29], v[134:137], v[204:207], v[26:29]
	v_mfma_f32_16x16x32_bf16 v[18:21], v[142:145], v[204:207], v[18:21]
	v_mfma_f32_16x16x32_bf16 v[6:9], v[134:137], v[212:215], v[6:9]
	v_mfma_f32_16x16x32_bf16 v[2:5], v[142:145], v[212:215], v[2:5]
	v_mfma_f32_16x16x32_bf16 v[62:65], v[146:149], v[180:183], v[62:65]
	v_mfma_f32_16x16x32_bf16 v[50:53], v[172:175], v[180:183], v[50:53]
	v_mfma_f32_16x16x32_bf16 v[46:49], v[146:149], v[192:195], v[46:49]
	v_mfma_f32_16x16x32_bf16 v[38:41], v[172:175], v[192:195], v[38:41]
	v_mfma_f32_16x16x32_bf16 v[30:33], v[146:149], v[200:203], v[30:33]
	v_mfma_f32_16x16x32_bf16 v[22:25], v[172:175], v[200:203], v[22:25]
	v_mfma_f32_16x16x32_bf16 v[10:13], v[146:149], v[208:211], v[10:13]
	v_mfma_f32_16x16x32_bf16 v[14:17], v[172:175], v[208:211], v[14:17]
	v_mfma_f32_16x16x32_bf16 v[62:65], v[150:153], v[188:191], v[62:65]
	v_mfma_f32_16x16x32_bf16 v[50:53], v[176:179], v[188:191], v[50:53]
	v_mfma_f32_16x16x32_bf16 v[46:49], v[150:153], v[196:199], v[46:49]
	v_mfma_f32_16x16x32_bf16 v[38:41], v[176:179], v[196:199], v[38:41]
	v_mfma_f32_16x16x32_bf16 v[30:33], v[150:153], v[204:207], v[30:33]
	v_mfma_f32_16x16x32_bf16 v[22:25], v[176:179], v[204:207], v[22:25]
	v_mfma_f32_16x16x32_bf16 v[10:13], v[150:153], v[212:215], v[10:13]
	v_mfma_f32_16x16x32_bf16 v[14:17], v[176:179], v[212:215], v[14:17]
	s_setprio 1
	s_barrier
	s_add_i32 s68, s68, 2
	s_add_u32 s26, s26, 0x100
	s_addc_u32 s27, s27, 0
	s_add_u32 s66, s66, 0x100
	s_addc_u32 s67, s67, 0
	s_cmp_gt_u32 s68, 61
	s_cbranch_scc0 .LBB0_1039
	s_and_b64 vcc, exec, s[10:11]
	s_cbranch_vccz .LBB0_1042
	s_barrier

; #define PG8_STAGE(bufoff, gbase, voff) do { _Pragma("unroll") for (int _i = 0; _i < 2; ++_i) \
;         __builtin_amdgcn_global_load_lds((const unsigned*)((const char*)(gbase) + (voff)[_i]), (PG8_LAS unsigned*)(lds + (bufoff) + ldsw + _i * 8192), 16, 0, 0); } while (0)
; #define PG8_LDA(dst, b, h) do { _Pragma("unroll") for (int m = 0; m < 4; ++m) _Pragma("unroll") for (int k = 0; k < 2; ++k) dst[m][k] = *(const PG8_LAS bf16x8*)(lds + PG8_SA(b, h) + aoff + m * 2048 + k * 1024); } while (0)
; #define PG8_LDB(dst, b, h) do { _Pragma("unroll") for (int n = 0; n < 2; ++n) _Pragma("unroll") for (int k = 0; k < 2; ++k) dst[n][k] = *(const PG8_LAS bf16x8*)(lds + PG8_SB(b, h) + boff + n * 2048 + k * 1024); } while (0)
; #define PG8_MMA(ai, bj, At, Bt) do { __builtin_amdgcn_s_setprio(1); _Pragma("unroll") for (int m = 0; m < 4; ++m) _Pragma("unroll") for (int n = 0; n < 2; ++n) _Pragma("unroll") for (int k = 0; k < 2; ++k) \
;         acc[ai][bj][m][n] = __builtin_amdgcn_mfma_f32_16x16x32_bf16(Bt[n][k], At[m][k], acc[ai][bj][m][n], 0, 0, 0); __builtin_amdgcn_s_setprio(0); } while (0)
; #define PG8_WAIT_V(n) asm volatile("s_waitcnt vmcnt(" #n ")" ::: "memory")
; #define PG8_WAIT_L(n) asm volatile("s_waitcnt lgkmcnt(" #n ")" ::: "memory")
; template <class Epi, class Sched, bool ALIGN_EPI = false, bool SP2 = false>
; __device__ __forceinline__ void gemm_phase(PG8_LAS unsigned char* lds, const Gemm g, const Sched& S, const Epi& E) {
;     ...
;             const bool last = (t == nt - 2);
;             const char* a1 = cA + (size_t)(t + 1) * kstep;
;             const char* a2 = last ? nA : cA + (size_t)(t + 2) * kstep; const char* b2 = last ? nB : cB + (size_t)(t + 2) * kstep;
;             const char* a3 = a2 + kstep; const char* b3 = b2 + kstep;
;             if (last && has_next) S.a_ready(nxt);
;             if constexpr (SP2) {
;             PG8_LDB(B0, 0, 0); PG8_LDB(B1, 0, 1); PG8_SCHED; PG8_LDA(At, 0, 0); PG8_STAGE(PG8_SA(1, 1), a1 + hstep, voffA);
;             PG8_WAIT_V(8); PG8_WAIT_L(0); PG8_BAR; PG8_MMA(0, 0, At, B0); PG8_MMA(0, 1, At, B1); PG8_BAR; PG8_SCHED;
;             PG8_LDA(At, 0, 1); PG8_STAGE(PG8_SB(0, 0), b2, voffB); PG8_STAGE(PG8_SB(0, 1), b2 + hstep, voffB); PG8_STAGE(PG8_SA(0, 0), a2, voffA);
;             PG8_WAIT_V(8); PG8_WAIT_L(0); PG8_BAR; PG8_MMA(1, 0, At, B0); PG8_MMA(1, 1, At, B1); PG8_BAR; PG8_SCHED;
.LBB0_1126:
	ds_read_b128 v[160:163], v241 offset:0
	ds_read_b128 v[166:169], v241 offset:1024
	ds_read_b128 v[170:173], v241 offset:2048
	ds_read_b128 v[174:177], v241 offset:3072
	ds_read_b128 v[178:181], v241 offset:16384
	ds_read_b128 v[182:185], v241 offset:17408
	ds_read_b128 v[186:189], v241 offset:18432
	ds_read_b128 v[190:193], v241 offset:19456
	s_add_u32 s22, s24, 0xfff00080
	s_addc_u32 s23, s25, -1
	s_cmp_eq_u32 s68, 60
	s_cselect_b32 s27, s15, s23
	s_cselect_b32 s26, s64, s22
	s_cselect_b32 s23, s13, s67
	s_cselect_b32 s22, s65, s66
	s_add_i32 m0, s21, 0xc000
	ds_read_b128 v[194:197], v155
	ds_read_b128 v[198:201], v155 offset:1024
	ds_read_b128 v[202:205], v155 offset:2048
	ds_read_b128 v[206:209], v155 offset:3072
	ds_read_b128 v[210:213], v155 offset:4096
	ds_read_b128 v[214:217], v155 offset:5120
	ds_read_b128 v[218:221], v155 offset:6144
	ds_read_b128 v[222:225], v155 offset:7168
	global_load_lds_dwordx4 v138, s[24:25]
	s_add_i32 m0, s21, 0xe000
	s_nop 0
	global_load_lds_dwordx4 v140, s[24:25]
	s_waitcnt vmcnt(8)
	s_waitcnt lgkmcnt(0)
	s_barrier
	s_setprio 0
	s_waitcnt lgkmcnt(0)
	v_mfma_f32_16x16x32_bf16 v[122:125], v[160:163], v[194:197], v[122:125]
	v_mfma_f32_16x16x32_bf16 v[114:117], v[170:173], v[194:197], v[114:117]
	v_mfma_f32_16x16x32_bf16 v[106:109], v[160:163], v[202:205], v[106:109]
	v_mfma_f32_16x16x32_bf16 v[98:101], v[170:173], v[202:205], v[98:101]
	v_mfma_f32_16x16x32_bf16 v[90:93], v[160:163], v[210:213], v[90:93]
	v_mfma_f32_16x16x32_bf16 v[82:85], v[170:173], v[210:213], v[82:85]
	v_mfma_f32_16x16x32_bf16 v[74:77], v[160:163], v[218:221], v[74:77]
	v_mfma_f32_16x16x32_bf16 v[62:65], v[170:173], v[218:221], v[62:65]
	v_mfma_f32_16x16x32_bf16 v[122:125], v[166:169], v[198:201], v[122:125]
	v_mfma_f32_16x16x32_bf16 v[114:117], v[174:177], v[198:201], v[114:117]
	v_mfma_f32_16x16x32_bf16 v[106:109], v[166:169], v[206:209], v[106:109]
	v_mfma_f32_16x16x32_bf16 v[98:101], v[174:177], v[206:209], v[98:101]
	v_mfma_f32_16x16x32_bf16 v[90:93], v[166:169], v[214:217], v[90:93]
	v_mfma_f32_16x16x32_bf16 v[82:85], v[174:177], v[214:217], v[82:85]
	v_mfma_f32_16x16x32_bf16 v[74:77], v[166:169], v[222:225], v[74:77]
	v_mfma_f32_16x16x32_bf16 v[62:65], v[174:177], v[222:225], v[62:65]
	v_mfma_f32_16x16x32_bf16 v[126:129], v[178:181], v[194:197], v[126:129]
	v_mfma_f32_16x16x32_bf16 v[118:121], v[186:189], v[194:197], v[118:121]
	v_mfma_f32_16x16x32_bf16 v[110:113], v[178:181], v[202:205], v[110:113]
	v_mfma_f32_16x16x32_bf16 v[102:105], v[186:189], v[202:205], v[102:105]
	v_mfma_f32_16x16x32_bf16 v[94:97], v[178:181], v[210:213], v[94:97]
	v_mfma_f32_16x16x32_bf16 v[86:89], v[186:189], v[210:213], v[86:89]
	v_mfma_f32_16x16x32_bf16 v[78:81], v[178:181], v[218:221], v[78:81]
	v_mfma_f32_16x16x32_bf16 v[70:73], v[186:189], v[218:221], v[70:73]
	v_mfma_f32_16x16x32_bf16 v[126:129], v[182:185], v[198:201], v[126:129]
	v_mfma_f32_16x16x32_bf16 v[118:121], v[190:193], v[198:201], v[118:121]
	v_mfma_f32_16x16x32_bf16 v[110:113], v[182:185], v[206:209], v[110:113]
	v_mfma_f32_16x16x32_bf16 v[102:105], v[190:193], v[206:209], v[102:105]
	v_mfma_f32_16x16x32_bf16 v[94:97], v[182:185], v[214:217], v[94:97]
	v_mfma_f32_16x16x32_bf16 v[86:89], v[190:193], v[214:217], v[86:89]
	v_mfma_f32_16x16x32_bf16 v[78:81], v[182:185], v[222:225], v[78:81]
	v_mfma_f32_16x16x32_bf16 v[70:73], v[190:193], v[222:225], v[70:73]
	s_setprio 1
	s_barrier
	s_add_i32 s33, s52, s29
	s_mov_b32 m0, s33
	ds_read_b128 v[194:197], v155 offset:16384
	ds_read_b128 v[198:201], v155 offset:17408
	ds_read_b128 v[202:205], v155 offset:18432
	ds_read_b128 v[206:209], v155 offset:19456
	ds_read_b128 v[210:213], v155 offset:20480
	ds_read_b128 v[214:217], v155 offset:21504
	ds_read_b128 v[218:221], v155 offset:22528
	ds_read_b128 v[222:225], v155 offset:23552
	global_load_lds_dwordx4 v132, s[22:23]
	s_add_i32 m0, s33, 0x2000
	s_add_u32 s72, s22, 0x100000
	s_addc_u32 s73, s23, 0
	s_add_i32 s33, s53, s29
	global_load_lds_dwordx4 v136, s[22:23]
	s_mov_b32 m0, s33
	s_add_u32 s100, s26, 0x80
	s_addc_u32 s101, s27, 0
	global_load_lds_dwordx4 v132, s[72:73]
	s_add_i32 m0, s33, 0x2000
	s_nop 0
	global_load_lds_dwordx4 v136, s[72:73]
	s_mov_b32 m0, s21
	s_nop 0
	global_load_lds_dwordx4 v130, s[26:27]
	s_mov_b32 m0, s36
	s_nop 0
	global_load_lds_dwordx4 v134, s[26:27]
	s_waitcnt vmcnt(8)
	s_waitcnt lgkmcnt(0)
	s_barrier
	s_setprio 0
	s_waitcnt lgkmcnt(0)
	v_mfma_f32_16x16x32_bf16 v[58:61], v[160:163], v[194:197], v[58:61]
	v_mfma_f32_16x16x32_bf16 v[50:53], v[170:173], v[194:197], v[50:53]
	v_mfma_f32_16x16x32_bf16 v[42:45], v[160:163], v[202:205], v[42:45]
	v_mfma_f32_16x16x32_bf16 v[34:37], v[170:173], v[202:205], v[34:37]
	v_mfma_f32_16x16x32_bf16 v[26:29], v[160:163], v[210:213], v[26:29]
	v_mfma_f32_16x16x32_bf16 v[18:21], v[170:173], v[210:213], v[18:21]
	v_mfma_f32_16x16x32_bf16 v[10:13], v[160:163], v[218:221], v[10:13]
	v_mfma_f32_16x16x32_bf16 v[2:5], v[170:173], v[218:221], v[2:5]
	v_mfma_f32_16x16x32_bf16 v[58:61], v[166:169], v[198:201], v[58:61]
	v_mfma_f32_16x16x32_bf16 v[50:53], v[174:177], v[198:201], v[50:53]
	v_mfma_f32_16x16x32_bf16 v[42:45], v[166:169], v[206:209], v[42:45]
	v_mfma_f32_16x16x32_bf16 v[34:37], v[174:177], v[206:209], v[34:37]
	v_mfma_f32_16x16x32_bf16 v[26:29], v[166:169], v[214:217], v[26:29]
	v_mfma_f32_16x16x32_bf16 v[18:21], v[174:177], v[214:217], v[18:21]
	v_mfma_f32_16x16x32_bf16 v[10:13], v[166:169], v[222:225], v[10:13]
	v_mfma_f32_16x16x32_bf16 v[2:5], v[174:177], v[222:225], v[2:5]
	v_mfma_f32_16x16x32_bf16 v[66:69], v[178:181], v[194:197], v[66:69]
	v_mfma_f32_16x16x32_bf16 v[54:57], v[186:189], v[194:197], v[54:57]
	v_mfma_f32_16x16x32_bf16 v[46:49], v[178:181], v[202:205], v[46:49]
	v_mfma_f32_16x16x32_bf16 v[38:41], v[186:189], v[202:205], v[38:41]
	v_mfma_f32_16x16x32_bf16 v[30:33], v[178:181], v[210:213], v[30:33]
	v_mfma_f32_16x16x32_bf16 v[22:25], v[186:189], v[210:213], v[22:25]
	v_mfma_f32_16x16x32_bf16 v[14:17], v[178:181], v[218:221], v[14:17]
	v_mfma_f32_16x16x32_bf16 v[6:9], v[186:189], v[218:221], v[6:9]
	v_mfma_f32_16x16x32_bf16 v[66:69], v[182:185], v[198:201], v[66:69]
	v_mfma_f32_16x16x32_bf16 v[54:57], v[190:193], v[198:201], v[54:57]
	v_mfma_f32_16x16x32_bf16 v[46:49], v[182:185], v[206:209], v[46:49]
	v_mfma_f32_16x16x32_bf16 v[38:41], v[190:193], v[206:209], v[38:41]
	v_mfma_f32_16x16x32_bf16 v[30:33], v[182:185], v[214:217], v[30:33]
	v_mfma_f32_16x16x32_bf16 v[22:25], v[190:193], v[214:217], v[22:25]
	v_mfma_f32_16x16x32_bf16 v[14:17], v[182:185], v[222:225], v[14:17]
	v_mfma_f32_16x16x32_bf16 v[6:9], v[190:193], v[222:225], v[6:9]
	s_setprio 1
	s_barrier
; #define PG8_STAGE(bufoff, gbase, voff) do { _Pragma("unroll") for (int _i = 0; _i < 2; ++_i) \
;         __builtin_amdgcn_global_load_lds((const unsigned*)((const char*)(gbase) + (voff)[_i]), (PG8_LAS unsigned*)(lds + (bufoff) + ldsw + _i * 8192), 16, 0, 0); } while (0)
; #define PG8_LDA(dst, b, h) do { _Pragma("unroll") for (int m = 0; m < 4; ++m) _Pragma("unroll") for (int k = 0; k < 2; ++k) dst[m][k] = *(const PG8_LAS bf16x8*)(lds + PG8_SA(b, h) + aoff + m * 2048 + k * 1024); } while (0)
; #define PG8_LDB(dst, b, h) do { _Pragma("unroll") for (int n = 0; n < 2; ++n) _Pragma("unroll") for (int k = 0; k < 2; ++k) dst[n][k] = *(const PG8_LAS bf16x8*)(lds + PG8_SB(b, h) + boff + n * 2048 + k * 1024); } while (0)
; #define PG8_MMA(ai, bj, At, Bt) do { __builtin_amdgcn_s_setprio(1); _Pragma("unroll") for (int m = 0; m < 4; ++m) _Pragma("unroll") for (int n = 0; n < 2; ++n) _Pragma("unroll") for (int k = 0; k < 2; ++k) \
;         acc[ai][bj][m][n] = __builtin_amdgcn_mfma_f32_16x16x32_bf16(Bt[n][k], At[m][k], acc[ai][bj][m][n], 0, 0, 0); __builtin_amdgcn_s_setprio(0); } while (0)
; #define PG8_WAIT_V(n) asm volatile("s_waitcnt vmcnt(" #n ")" ::: "memory")
; #define PG8_WAIT_L(n) asm volatile("s_waitcnt lgkmcnt(" #n ")" ::: "memory")
; #define PG8_BAR __builtin_amdgcn_s_barrier()
; #define PG8_SCHED __builtin_amdgcn_sched_barrier(0)
; template <class Epi, class Sched, bool ALIGN_EPI = false, bool SP2 = false>
; __device__ __forceinline__ void gemm_phase(PG8_LAS unsigned char* lds, const Gemm g, const Sched& S, const Epi& E) {
;     ...
;             PG8_LDB(B0, 1, 0); PG8_LDB(B1, 1, 1); PG8_SCHED; PG8_LDA(At, 1, 0); PG8_STAGE(PG8_SA(0, 1), a2 + hstep, voffA);
;             PG8_WAIT_V(8); PG8_WAIT_L(0); PG8_BAR; PG8_MMA(0, 0, At, B0); PG8_MMA(0, 1, At, B1); PG8_BAR; PG8_SCHED;
;             PG8_LDA(At, 1, 1); PG8_STAGE(PG8_SB(1, 0), b3, voffB); PG8_STAGE(PG8_SB(1, 1), b3 + hstep, voffB); PG8_STAGE(PG8_SA(1, 0), a3, voffA);
;             PG8_WAIT_V(8); PG8_WAIT_L(0); PG8_BAR; PG8_MMA(1, 0, At, B0); PG8_MMA(1, 1, At, B1); PG8_BAR; PG8_SCHED;
	s_add_i32 s33, 0, 0x18000
	s_add_i32 s42, 0, 0x1c000
	ds_read_b128 v[160:163], v241 offset:32768
	ds_read_b128 v[166:169], v241 offset:33792
	ds_read_b128 v[170:173], v241 offset:34816
	ds_read_b128 v[174:177], v241 offset:35840
	ds_read_b128 v[178:181], v241 offset:49152
	ds_read_b128 v[182:185], v241 offset:50176
	ds_read_b128 v[186:189], v241 offset:51200
	ds_read_b128 v[190:193], v241 offset:52224
	s_add_u32 s26, s26, 0x100000
	s_addc_u32 s27, s27, 0
	s_mov_b32 m0, s37
	ds_read_b128 v[194:197], v155 offset:32768
	ds_read_b128 v[198:201], v155 offset:33792
	ds_read_b128 v[202:205], v155 offset:34816
	ds_read_b128 v[206:209], v155 offset:35840
	ds_read_b128 v[210:213], v155 offset:36864
	ds_read_b128 v[214:217], v155 offset:37888
	ds_read_b128 v[218:221], v155 offset:38912
	ds_read_b128 v[222:225], v155 offset:39936
	global_load_lds_dwordx4 v130, s[26:27]
	s_mov_b32 m0, s40
	s_nop 0
	global_load_lds_dwordx4 v134, s[26:27]
	s_waitcnt vmcnt(8)
	s_waitcnt lgkmcnt(0)
	s_barrier
	s_setprio 0
	s_waitcnt lgkmcnt(0)
	v_mfma_f32_16x16x32_bf16 v[122:125], v[160:163], v[194:197], v[122:125]
	v_mfma_f32_16x16x32_bf16 v[114:117], v[170:173], v[194:197], v[114:117]
	v_mfma_f32_16x16x32_bf16 v[106:109], v[160:163], v[202:205], v[106:109]
	v_mfma_f32_16x16x32_bf16 v[98:101], v[170:173], v[202:205], v[98:101]
	v_mfma_f32_16x16x32_bf16 v[90:93], v[160:163], v[210:213], v[90:93]
	v_mfma_f32_16x16x32_bf16 v[82:85], v[170:173], v[210:213], v[82:85]
	v_mfma_f32_16x16x32_bf16 v[74:77], v[160:163], v[218:221], v[74:77]
	v_mfma_f32_16x16x32_bf16 v[62:65], v[170:173], v[218:221], v[62:65]
	v_mfma_f32_16x16x32_bf16 v[122:125], v[166:169], v[198:201], v[122:125]
	v_mfma_f32_16x16x32_bf16 v[114:117], v[174:177], v[198:201], v[114:117]
	v_mfma_f32_16x16x32_bf16 v[106:109], v[166:169], v[206:209], v[106:109]
	v_mfma_f32_16x16x32_bf16 v[98:101], v[174:177], v[206:209], v[98:101]
	v_mfma_f32_16x16x32_bf16 v[90:93], v[166:169], v[214:217], v[90:93]
	v_mfma_f32_16x16x32_bf16 v[82:85], v[174:177], v[214:217], v[82:85]
	v_mfma_f32_16x16x32_bf16 v[74:77], v[166:169], v[222:225], v[74:77]
	v_mfma_f32_16x16x32_bf16 v[62:65], v[174:177], v[222:225], v[62:65]
	v_mfma_f32_16x16x32_bf16 v[126:129], v[178:181], v[194:197], v[126:129]
	v_mfma_f32_16x16x32_bf16 v[118:121], v[186:189], v[194:197], v[118:121]
	v_mfma_f32_16x16x32_bf16 v[110:113], v[178:181], v[202:205], v[110:113]
	v_mfma_f32_16x16x32_bf16 v[102:105], v[186:189], v[202:205], v[102:105]
	v_mfma_f32_16x16x32_bf16 v[94:97], v[178:181], v[210:213], v[94:97]
	v_mfma_f32_16x16x32_bf16 v[86:89], v[186:189], v[210:213], v[86:89]
	v_mfma_f32_16x16x32_bf16 v[78:81], v[178:181], v[218:221], v[78:81]
	v_mfma_f32_16x16x32_bf16 v[70:73], v[186:189], v[218:221], v[70:73]
	v_mfma_f32_16x16x32_bf16 v[126:129], v[182:185], v[198:201], v[126:129]
	v_mfma_f32_16x16x32_bf16 v[118:121], v[190:193], v[198:201], v[118:121]
	v_mfma_f32_16x16x32_bf16 v[110:113], v[182:185], v[206:209], v[110:113]
	v_mfma_f32_16x16x32_bf16 v[102:105], v[190:193], v[206:209], v[102:105]
	v_mfma_f32_16x16x32_bf16 v[94:97], v[182:185], v[214:217], v[94:97]
	v_mfma_f32_16x16x32_bf16 v[86:89], v[190:193], v[214:217], v[86:89]
	v_mfma_f32_16x16x32_bf16 v[78:81], v[182:185], v[222:225], v[78:81]
	v_mfma_f32_16x16x32_bf16 v[70:73], v[190:193], v[222:225], v[70:73]
	s_setprio 1
	s_barrier
	s_add_i32 s26, s33, s29
	s_add_i32 m0, s26, 0xffffff80
	ds_read_b128 v[194:197], v155 offset:49152
	ds_read_b128 v[198:201], v155 offset:50176
	ds_read_b128 v[202:205], v155 offset:51200
	ds_read_b128 v[206:209], v155 offset:52224
	ds_read_b128 v[210:213], v155 offset:53248
	ds_read_b128 v[214:217], v155 offset:54272
	ds_read_b128 v[218:221], v155 offset:55296
	ds_read_b128 v[222:225], v155 offset:56320
	global_load_lds_dwordx4 v132, s[22:23] offset:128
	s_add_i32 m0, s26, 0x1f80
	s_add_i32 s26, s42, s29
	global_load_lds_dwordx4 v136, s[22:23] offset:128
	s_add_u32 s22, s22, 0x100080
	s_addc_u32 s23, s23, 0
	s_mov_b32 m0, s26
	s_nop 0
	global_load_lds_dwordx4 v132, s[22:23]
	s_add_i32 m0, s26, 0x2000
	s_nop 0
	global_load_lds_dwordx4 v136, s[22:23]
	s_mov_b32 m0, s46
	s_nop 0
	global_load_lds_dwordx4 v130, s[100:101]
	s_mov_b32 m0, s47
	s_nop 0
	global_load_lds_dwordx4 v134, s[100:101]
	s_waitcnt vmcnt(8)
	s_waitcnt lgkmcnt(0)
	s_barrier
	s_setprio 0
	s_waitcnt lgkmcnt(0)
	v_mfma_f32_16x16x32_bf16 v[58:61], v[160:163], v[194:197], v[58:61]
	v_mfma_f32_16x16x32_bf16 v[50:53], v[170:173], v[194:197], v[50:53]
	v_mfma_f32_16x16x32_bf16 v[42:45], v[160:163], v[202:205], v[42:45]
	v_mfma_f32_16x16x32_bf16 v[34:37], v[170:173], v[202:205], v[34:37]
	v_mfma_f32_16x16x32_bf16 v[26:29], v[160:163], v[210:213], v[26:29]
	v_mfma_f32_16x16x32_bf16 v[18:21], v[170:173], v[210:213], v[18:21]
	v_mfma_f32_16x16x32_bf16 v[10:13], v[160:163], v[218:221], v[10:13]
	v_mfma_f32_16x16x32_bf16 v[2:5], v[170:173], v[218:221], v[2:5]
	v_mfma_f32_16x16x32_bf16 v[58:61], v[166:169], v[198:201], v[58:61]
	v_mfma_f32_16x16x32_bf16 v[50:53], v[174:177], v[198:201], v[50:53]
	v_mfma_f32_16x16x32_bf16 v[42:45], v[166:169], v[206:209], v[42:45]
	v_mfma_f32_16x16x32_bf16 v[34:37], v[174:177], v[206:209], v[34:37]
	v_mfma_f32_16x16x32_bf16 v[26:29], v[166:169], v[214:217], v[26:29]
	v_mfma_f32_16x16x32_bf16 v[18:21], v[174:177], v[214:217], v[18:21]
	v_mfma_f32_16x16x32_bf16 v[10:13], v[166:169], v[222:225], v[10:13]
	v_mfma_f32_16x16x32_bf16 v[2:5], v[174:177], v[222:225], v[2:5]
	v_mfma_f32_16x16x32_bf16 v[66:69], v[178:181], v[194:197], v[66:69]
	v_mfma_f32_16x16x32_bf16 v[54:57], v[186:189], v[194:197], v[54:57]
	v_mfma_f32_16x16x32_bf16 v[46:49], v[178:181], v[202:205], v[46:49]
	v_mfma_f32_16x16x32_bf16 v[38:41], v[186:189], v[202:205], v[38:41]
	v_mfma_f32_16x16x32_bf16 v[30:33], v[178:181], v[210:213], v[30:33]
	v_mfma_f32_16x16x32_bf16 v[22:25], v[186:189], v[210:213], v[22:25]
	v_mfma_f32_16x16x32_bf16 v[14:17], v[178:181], v[218:221], v[14:17]
	v_mfma_f32_16x16x32_bf16 v[6:9], v[186:189], v[218:221], v[6:9]
	v_mfma_f32_16x16x32_bf16 v[66:69], v[182:185], v[198:201], v[66:69]
	v_mfma_f32_16x16x32_bf16 v[54:57], v[190:193], v[198:201], v[54:57]
	v_mfma_f32_16x16x32_bf16 v[46:49], v[182:185], v[206:209], v[46:49]
	v_mfma_f32_16x16x32_bf16 v[38:41], v[190:193], v[206:209], v[38:41]
	v_mfma_f32_16x16x32_bf16 v[30:33], v[182:185], v[214:217], v[30:33]
	v_mfma_f32_16x16x32_bf16 v[22:25], v[190:193], v[214:217], v[22:25]
	v_mfma_f32_16x16x32_bf16 v[14:17], v[182:185], v[222:225], v[14:17]
	v_mfma_f32_16x16x32_bf16 v[6:9], v[190:193], v[222:225], v[6:9]
	s_setprio 1
	s_barrier
	s_add_i32 s68, s68, 2
	s_add_u32 s24, s24, 0x100
	s_addc_u32 s25, s25, 0
	s_add_u32 s66, s66, 0x100
	s_addc_u32 s67, s67, 0
	s_cmp_gt_u32 s68, 61
	s_cbranch_scc0 .LBB0_1126
	s_and_b64 vcc, exec, s[8:9]
	s_cbranch_vccz .LBB0_1129
	s_barrier

; #define PG8_STAGE(bufoff, gbase, voff) do { _Pragma("unroll") for (int _i = 0; _i < 2; ++_i) \
;         __builtin_amdgcn_global_load_lds((const unsigned*)((const char*)(gbase) + (voff)[_i]), (PG8_LAS unsigned*)(lds + (bufoff) + ldsw + _i * 8192), 16, 0, 0); } while (0)
; #define PG8_LDA(dst, b, h) do { _Pragma("unroll") for (int m = 0; m < 4; ++m) _Pragma("unroll") for (int k = 0; k < 2; ++k) dst[m][k] = *(const PG8_LAS bf16x8*)(lds + PG8_SA(b, h) + aoff + m * 2048 + k * 1024); } while (0)
; #define PG8_LDB(dst, b, h) do { _Pragma("unroll") for (int n = 0; n < 2; ++n) _Pragma("unroll") for (int k = 0; k < 2; ++k) dst[n][k] = *(const PG8_LAS bf16x8*)(lds + PG8_SB(b, h) + boff + n * 2048 + k * 1024); } while (0)
; #define PG8_MMA(ai, bj, At, Bt) do { __builtin_amdgcn_s_setprio(1); _Pragma("unroll") for (int m = 0; m < 4; ++m) _Pragma("unroll") for (int n = 0; n < 2; ++n) _Pragma("unroll") for (int k = 0; k < 2; ++k) \
;         acc[ai][bj][m][n] = __builtin_amdgcn_mfma_f32_16x16x32_bf16(Bt[n][k], At[m][k], acc[ai][bj][m][n], 0, 0, 0); __builtin_amdgcn_s_setprio(0); } while (0)
; #define PG8_WAIT_V(n) asm volatile("s_waitcnt vmcnt(" #n ")" ::: "memory")
; #define PG8_WAIT_L(n) asm volatile("s_waitcnt lgkmcnt(" #n ")" ::: "memory")
; template <class Epi, class Sched, bool ALIGN_EPI = false, bool SP2 = false>
; __device__ __forceinline__ void gemm_phase(PG8_LAS unsigned char* lds, const Gemm g, const Sched& S, const Epi& E) {
;     ...
;             const bool last = (t == nt - 2);
;             const char* a1 = cA + (size_t)(t + 1) * kstep;
;             const char* a2 = last ? nA : cA + (size_t)(t + 2) * kstep; const char* b2 = last ? nB : cB + (size_t)(t + 2) * kstep;
;             const char* a3 = a2 + kstep; const char* b3 = b2 + kstep;
;             if (last && has_next) S.a_ready(nxt);
;             if constexpr (SP2) {
;             PG8_LDB(B0, 0, 0); PG8_LDB(B1, 0, 1); PG8_SCHED; PG8_LDA(At, 0, 0); PG8_STAGE(PG8_SA(1, 1), a1 + hstep, voffA);
;             PG8_WAIT_V(8); PG8_WAIT_L(0); PG8_BAR; PG8_MMA(0, 0, At, B0); PG8_MMA(0, 1, At, B1); PG8_BAR; PG8_SCHED;
;             PG8_LDA(At, 0, 1); PG8_STAGE(PG8_SB(0, 0), b2, voffB); PG8_STAGE(PG8_SB(0, 1), b2 + hstep, voffB); PG8_STAGE(PG8_SA(0, 0), a2, voffA);
;             PG8_WAIT_V(8); PG8_WAIT_L(0); PG8_BAR; PG8_MMA(1, 0, At, B0); PG8_MMA(1, 1, At, B1); PG8_BAR; PG8_SCHED;
.LBB0_1245:
	ds_read_b128 v[130:133], v241 offset:0
	ds_read_b128 v[134:137], v241 offset:1024
	ds_read_b128 v[138:141], v241 offset:2048
	ds_read_b128 v[142:145], v241 offset:3072
	ds_read_b128 v[146:149], v241 offset:16384
	ds_read_b128 v[150:153], v241 offset:17408
	ds_read_b128 v[172:175], v241 offset:18432
	ds_read_b128 v[176:179], v241 offset:19456
	s_add_u32 s16, s18, 0xffd50080
	s_addc_u32 s17, s19, -1
	s_cmpk_eq_i32 s64, 0xa8
	s_cselect_b32 s21, s5, s17
	s_cselect_b32 s20, s4, s16
	s_cselect_b32 s17, s15, s63
	s_cselect_b32 s16, s14, s62
	s_add_i32 m0, s25, 0xc000
	ds_read_b128 v[180:183], v185
	ds_read_b128 v[188:191], v185 offset:1024
	ds_read_b128 v[192:195], v185 offset:2048
	ds_read_b128 v[196:199], v185 offset:3072
	ds_read_b128 v[200:203], v185 offset:4096
	ds_read_b128 v[204:207], v185 offset:5120
	ds_read_b128 v[208:211], v185 offset:6144
	ds_read_b128 v[212:215], v185 offset:7168
	global_load_lds_dwordx4 v162, s[18:19]
	s_add_i32 m0, s25, 0xe000
	s_nop 0
	global_load_lds_dwordx4 v166, s[18:19]
	s_waitcnt vmcnt(8)
	s_waitcnt lgkmcnt(0)
	s_barrier
	s_setprio 0
	s_waitcnt lgkmcnt(0)
	v_mfma_f32_16x16x32_bf16 v[114:117], v[130:133], v[180:183], v[114:117]
	v_mfma_f32_16x16x32_bf16 v[118:121], v[138:141], v[180:183], v[118:121]
	v_mfma_f32_16x16x32_bf16 v[106:109], v[130:133], v[192:195], v[106:109]
	v_mfma_f32_16x16x32_bf16 v[98:101], v[138:141], v[192:195], v[98:101]
	v_mfma_f32_16x16x32_bf16 v[90:93], v[130:133], v[200:203], v[90:93]
	v_mfma_f32_16x16x32_bf16 v[82:85], v[138:141], v[200:203], v[82:85]
	v_mfma_f32_16x16x32_bf16 v[74:77], v[130:133], v[208:211], v[74:77]
	v_mfma_f32_16x16x32_bf16 v[66:69], v[138:141], v[208:211], v[66:69]
	v_mfma_f32_16x16x32_bf16 v[114:117], v[134:137], v[188:191], v[114:117]
	v_mfma_f32_16x16x32_bf16 v[118:121], v[142:145], v[188:191], v[118:121]
	v_mfma_f32_16x16x32_bf16 v[106:109], v[134:137], v[196:199], v[106:109]
	v_mfma_f32_16x16x32_bf16 v[98:101], v[142:145], v[196:199], v[98:101]
	v_mfma_f32_16x16x32_bf16 v[90:93], v[134:137], v[204:207], v[90:93]
	v_mfma_f32_16x16x32_bf16 v[82:85], v[142:145], v[204:207], v[82:85]
	v_mfma_f32_16x16x32_bf16 v[74:77], v[134:137], v[212:215], v[74:77]
	v_mfma_f32_16x16x32_bf16 v[66:69], v[142:145], v[212:215], v[66:69]
	v_mfma_f32_16x16x32_bf16 v[122:125], v[146:149], v[180:183], v[122:125]
	v_mfma_f32_16x16x32_bf16 v[126:129], v[172:175], v[180:183], v[126:129]
	v_mfma_f32_16x16x32_bf16 v[110:113], v[146:149], v[192:195], v[110:113]
	v_mfma_f32_16x16x32_bf16 v[102:105], v[172:175], v[192:195], v[102:105]
	v_mfma_f32_16x16x32_bf16 v[94:97], v[146:149], v[200:203], v[94:97]
	v_mfma_f32_16x16x32_bf16 v[86:89], v[172:175], v[200:203], v[86:89]
	v_mfma_f32_16x16x32_bf16 v[78:81], v[146:149], v[208:211], v[78:81]
	v_mfma_f32_16x16x32_bf16 v[70:73], v[172:175], v[208:211], v[70:73]
	v_mfma_f32_16x16x32_bf16 v[122:125], v[150:153], v[188:191], v[122:125]
	v_mfma_f32_16x16x32_bf16 v[126:129], v[176:179], v[188:191], v[126:129]
	v_mfma_f32_16x16x32_bf16 v[110:113], v[150:153], v[196:199], v[110:113]
	v_mfma_f32_16x16x32_bf16 v[102:105], v[176:179], v[196:199], v[102:105]
	v_mfma_f32_16x16x32_bf16 v[94:97], v[150:153], v[204:207], v[94:97]
	v_mfma_f32_16x16x32_bf16 v[86:89], v[176:179], v[204:207], v[86:89]
	v_mfma_f32_16x16x32_bf16 v[78:81], v[150:153], v[212:215], v[78:81]
	v_mfma_f32_16x16x32_bf16 v[70:73], v[176:179], v[212:215], v[70:73]
	s_setprio 1
	s_barrier
	s_add_i32 s33, s40, s24
	s_mov_b32 m0, s33
	ds_read_b128 v[180:183], v185 offset:16384
	ds_read_b128 v[188:191], v185 offset:17408
	ds_read_b128 v[192:195], v185 offset:18432
	ds_read_b128 v[196:199], v185 offset:19456
	ds_read_b128 v[200:203], v185 offset:20480
	ds_read_b128 v[204:207], v185 offset:21504
	ds_read_b128 v[208:211], v185 offset:22528
	ds_read_b128 v[212:215], v185 offset:23552
	global_load_lds_dwordx4 v156, s[16:17]
	s_add_i32 m0, s33, 0x2000
	s_add_u32 s66, s16, 0x2b0000
	s_addc_u32 s67, s17, 0
	s_add_i32 s33, s41, s24
	global_load_lds_dwordx4 v160, s[16:17]
	s_mov_b32 m0, s33
	s_add_u32 s100, s20, 0x80
	s_addc_u32 s101, s21, 0
	global_load_lds_dwordx4 v156, s[66:67]
	s_add_i32 m0, s33, 0x2000
	s_nop 0
	global_load_lds_dwordx4 v160, s[66:67]
	s_mov_b32 m0, s25
	s_nop 0
	global_load_lds_dwordx4 v154, s[20:21]
	s_mov_b32 m0, s26
	s_nop 0
	global_load_lds_dwordx4 v158, s[20:21]
	s_waitcnt vmcnt(8)
	s_waitcnt lgkmcnt(0)
	s_barrier
	s_setprio 0
	s_waitcnt lgkmcnt(0)
	v_mfma_f32_16x16x32_bf16 v[58:61], v[130:133], v[180:183], v[58:61]
	v_mfma_f32_16x16x32_bf16 v[54:57], v[138:141], v[180:183], v[54:57]
	v_mfma_f32_16x16x32_bf16 v[42:45], v[130:133], v[192:195], v[42:45]
	v_mfma_f32_16x16x32_bf16 v[34:37], v[138:141], v[192:195], v[34:37]
	v_mfma_f32_16x16x32_bf16 v[26:29], v[130:133], v[200:203], v[26:29]
	v_mfma_f32_16x16x32_bf16 v[18:21], v[138:141], v[200:203], v[18:21]
	v_mfma_f32_16x16x32_bf16 v[6:9], v[130:133], v[208:211], v[6:9]
	v_mfma_f32_16x16x32_bf16 v[2:5], v[138:141], v[208:211], v[2:5]
	v_mfma_f32_16x16x32_bf16 v[58:61], v[134:137], v[188:191], v[58:61]
	v_mfma_f32_16x16x32_bf16 v[54:57], v[142:145], v[188:191], v[54:57]
	v_mfma_f32_16x16x32_bf16 v[42:45], v[134:137], v[196:199], v[42:45]
	v_mfma_f32_16x16x32_bf16 v[34:37], v[142:145], v[196:199], v[34:37]
	v_mfma_f32_16x16x32_bf16 v[26:29], v[134:137], v[204:207], v[26:29]
	v_mfma_f32_16x16x32_bf16 v[18:21], v[142:145], v[204:207], v[18:21]
	v_mfma_f32_16x16x32_bf16 v[6:9], v[134:137], v[212:215], v[6:9]
	v_mfma_f32_16x16x32_bf16 v[2:5], v[142:145], v[212:215], v[2:5]
	v_mfma_f32_16x16x32_bf16 v[62:65], v[146:149], v[180:183], v[62:65]
	v_mfma_f32_16x16x32_bf16 v[50:53], v[172:175], v[180:183], v[50:53]
	v_mfma_f32_16x16x32_bf16 v[46:49], v[146:149], v[192:195], v[46:49]
	v_mfma_f32_16x16x32_bf16 v[38:41], v[172:175], v[192:195], v[38:41]
	v_mfma_f32_16x16x32_bf16 v[30:33], v[146:149], v[200:203], v[30:33]
	v_mfma_f32_16x16x32_bf16 v[22:25], v[172:175], v[200:203], v[22:25]
	v_mfma_f32_16x16x32_bf16 v[10:13], v[146:149], v[208:211], v[10:13]
	v_mfma_f32_16x16x32_bf16 v[14:17], v[172:175], v[208:211], v[14:17]
	v_mfma_f32_16x16x32_bf16 v[62:65], v[150:153], v[188:191], v[62:65]
	v_mfma_f32_16x16x32_bf16 v[50:53], v[176:179], v[188:191], v[50:53]
	v_mfma_f32_16x16x32_bf16 v[46:49], v[150:153], v[196:199], v[46:49]
	v_mfma_f32_16x16x32_bf16 v[38:41], v[176:179], v[196:199], v[38:41]
	v_mfma_f32_16x16x32_bf16 v[30:33], v[150:153], v[204:207], v[30:33]
	v_mfma_f32_16x16x32_bf16 v[22:25], v[176:179], v[204:207], v[22:25]
	v_mfma_f32_16x16x32_bf16 v[10:13], v[150:153], v[212:215], v[10:13]
	v_mfma_f32_16x16x32_bf16 v[14:17], v[176:179], v[212:215], v[14:17]
	s_setprio 1
	s_barrier
; #define PG8_STAGE(bufoff, gbase, voff) do { _Pragma("unroll") for (int _i = 0; _i < 2; ++_i) \
;         __builtin_amdgcn_global_load_lds((const unsigned*)((const char*)(gbase) + (voff)[_i]), (PG8_LAS unsigned*)(lds + (bufoff) + ldsw + _i * 8192), 16, 0, 0); } while (0)
; #define PG8_LDA(dst, b, h) do { _Pragma("unroll") for (int m = 0; m < 4; ++m) _Pragma("unroll") for (int k = 0; k < 2; ++k) dst[m][k] = *(const PG8_LAS bf16x8*)(lds + PG8_SA(b, h) + aoff + m * 2048 + k * 1024); } while (0)
; #define PG8_LDB(dst, b, h) do { _Pragma("unroll") for (int n = 0; n < 2; ++n) _Pragma("unroll") for (int k = 0; k < 2; ++k) dst[n][k] = *(const PG8_LAS bf16x8*)(lds + PG8_SB(b, h) + boff + n * 2048 + k * 1024); } while (0)
; #define PG8_MMA(ai, bj, At, Bt) do { __builtin_amdgcn_s_setprio(1); _Pragma("unroll") for (int m = 0; m < 4; ++m) _Pragma("unroll") for (int n = 0; n < 2; ++n) _Pragma("unroll") for (int k = 0; k < 2; ++k) \
;         acc[ai][bj][m][n] = __builtin_amdgcn_mfma_f32_16x16x32_bf16(Bt[n][k], At[m][k], acc[ai][bj][m][n], 0, 0, 0); __builtin_amdgcn_s_setprio(0); } while (0)
; #define PG8_WAIT_V(n) asm volatile("s_waitcnt vmcnt(" #n ")" ::: "memory")
; #define PG8_WAIT_L(n) asm volatile("s_waitcnt lgkmcnt(" #n ")" ::: "memory")
; #define PG8_BAR __builtin_amdgcn_s_barrier()
; #define PG8_SCHED __builtin_amdgcn_sched_barrier(0)
; template <class Epi, class Sched, bool ALIGN_EPI = false, bool SP2 = false>
; __device__ __forceinline__ void gemm_phase(PG8_LAS unsigned char* lds, const Gemm g, const Sched& S, const Epi& E) {
;     ...
;             PG8_LDB(B0, 1, 0); PG8_LDB(B1, 1, 1); PG8_SCHED; PG8_LDA(At, 1, 0); PG8_STAGE(PG8_SA(0, 1), a2 + hstep, voffA);
;             PG8_WAIT_V(8); PG8_WAIT_L(0); PG8_BAR; PG8_MMA(0, 0, At, B0); PG8_MMA(0, 1, At, B1); PG8_BAR; PG8_SCHED;
;             PG8_LDA(At, 1, 1); PG8_STAGE(PG8_SB(1, 0), b3, voffB); PG8_STAGE(PG8_SB(1, 1), b3 + hstep, voffB); PG8_STAGE(PG8_SA(1, 0), a3, voffA);
;             PG8_WAIT_V(8); PG8_WAIT_L(0); PG8_BAR; PG8_MMA(1, 0, At, B0); PG8_MMA(1, 1, At, B1); PG8_BAR; PG8_SCHED;
	s_add_i32 s33, 0, 0x18000
	s_add_i32 s42, 0, 0x1c000
	ds_read_b128 v[130:133], v241 offset:32768
	ds_read_b128 v[134:137], v241 offset:33792
	ds_read_b128 v[138:141], v241 offset:34816
	ds_read_b128 v[142:145], v241 offset:35840
	ds_read_b128 v[146:149], v241 offset:49152
	ds_read_b128 v[150:153], v241 offset:50176
	ds_read_b128 v[172:175], v241 offset:51200
	ds_read_b128 v[176:179], v241 offset:52224
	s_add_u32 s20, s20, 0x2b0000
	s_addc_u32 s21, s21, 0
	s_mov_b32 m0, s27
	ds_read_b128 v[180:183], v185 offset:32768
	ds_read_b128 v[188:191], v185 offset:33792
	ds_read_b128 v[192:195], v185 offset:34816
	ds_read_b128 v[196:199], v185 offset:35840
	ds_read_b128 v[200:203], v185 offset:36864
	ds_read_b128 v[204:207], v185 offset:37888
	ds_read_b128 v[208:211], v185 offset:38912
	ds_read_b128 v[212:215], v185 offset:39936
	global_load_lds_dwordx4 v154, s[20:21]
	s_mov_b32 m0, s28
	s_nop 0
	global_load_lds_dwordx4 v158, s[20:21]
	s_waitcnt vmcnt(8)
	s_waitcnt lgkmcnt(0)
	s_barrier
	s_setprio 0
	s_waitcnt lgkmcnt(0)
	v_mfma_f32_16x16x32_bf16 v[114:117], v[130:133], v[180:183], v[114:117]
	v_mfma_f32_16x16x32_bf16 v[118:121], v[138:141], v[180:183], v[118:121]
	v_mfma_f32_16x16x32_bf16 v[106:109], v[130:133], v[192:195], v[106:109]
	v_mfma_f32_16x16x32_bf16 v[98:101], v[138:141], v[192:195], v[98:101]
	v_mfma_f32_16x16x32_bf16 v[90:93], v[130:133], v[200:203], v[90:93]
	v_mfma_f32_16x16x32_bf16 v[82:85], v[138:141], v[200:203], v[82:85]
	v_mfma_f32_16x16x32_bf16 v[74:77], v[130:133], v[208:211], v[74:77]
	v_mfma_f32_16x16x32_bf16 v[66:69], v[138:141], v[208:211], v[66:69]
	v_mfma_f32_16x16x32_bf16 v[114:117], v[134:137], v[188:191], v[114:117]
	v_mfma_f32_16x16x32_bf16 v[118:121], v[142:145], v[188:191], v[118:121]
	v_mfma_f32_16x16x32_bf16 v[106:109], v[134:137], v[196:199], v[106:109]
	v_mfma_f32_16x16x32_bf16 v[98:101], v[142:145], v[196:199], v[98:101]
	v_mfma_f32_16x16x32_bf16 v[90:93], v[134:137], v[204:207], v[90:93]
	v_mfma_f32_16x16x32_bf16 v[82:85], v[142:145], v[204:207], v[82:85]
	v_mfma_f32_16x16x32_bf16 v[74:77], v[134:137], v[212:215], v[74:77]
	v_mfma_f32_16x16x32_bf16 v[66:69], v[142:145], v[212:215], v[66:69]
	v_mfma_f32_16x16x32_bf16 v[122:125], v[146:149], v[180:183], v[122:125]
	v_mfma_f32_16x16x32_bf16 v[126:129], v[172:175], v[180:183], v[126:129]
	v_mfma_f32_16x16x32_bf16 v[110:113], v[146:149], v[192:195], v[110:113]
	v_mfma_f32_16x16x32_bf16 v[102:105], v[172:175], v[192:195], v[102:105]
	v_mfma_f32_16x16x32_bf16 v[94:97], v[146:149], v[200:203], v[94:97]
	v_mfma_f32_16x16x32_bf16 v[86:89], v[172:175], v[200:203], v[86:89]
	v_mfma_f32_16x16x32_bf16 v[78:81], v[146:149], v[208:211], v[78:81]
	v_mfma_f32_16x16x32_bf16 v[70:73], v[172:175], v[208:211], v[70:73]
	v_mfma_f32_16x16x32_bf16 v[122:125], v[150:153], v[188:191], v[122:125]
	v_mfma_f32_16x16x32_bf16 v[126:129], v[176:179], v[188:191], v[126:129]
	v_mfma_f32_16x16x32_bf16 v[110:113], v[150:153], v[196:199], v[110:113]
	v_mfma_f32_16x16x32_bf16 v[102:105], v[176:179], v[196:199], v[102:105]
	v_mfma_f32_16x16x32_bf16 v[94:97], v[150:153], v[204:207], v[94:97]
	v_mfma_f32_16x16x32_bf16 v[86:89], v[176:179], v[204:207], v[86:89]
	v_mfma_f32_16x16x32_bf16 v[78:81], v[150:153], v[212:215], v[78:81]
	v_mfma_f32_16x16x32_bf16 v[70:73], v[176:179], v[212:215], v[70:73]
	s_setprio 1
	s_barrier
	s_add_i32 s20, s33, s24
	s_add_i32 m0, s20, 0xffffff80
	ds_read_b128 v[180:183], v185 offset:49152
	ds_read_b128 v[188:191], v185 offset:50176
	ds_read_b128 v[192:195], v185 offset:51200
	ds_read_b128 v[196:199], v185 offset:52224
	ds_read_b128 v[200:203], v185 offset:53248
	ds_read_b128 v[204:207], v185 offset:54272
	ds_read_b128 v[208:211], v185 offset:55296
	ds_read_b128 v[212:215], v185 offset:56320
	global_load_lds_dwordx4 v156, s[16:17] offset:128
	s_add_i32 m0, s20, 0x1f80
	s_add_i32 s20, s42, s24
	global_load_lds_dwordx4 v160, s[16:17] offset:128
	s_add_u32 s16, s16, 0x2b0080
	s_addc_u32 s17, s17, 0
	s_mov_b32 m0, s20
	s_nop 0
	global_load_lds_dwordx4 v156, s[16:17]
	s_add_i32 m0, s20, 0x2000
	s_nop 0
	global_load_lds_dwordx4 v160, s[16:17]
	s_mov_b32 m0, s34
	s_nop 0
	global_load_lds_dwordx4 v154, s[100:101]
	s_mov_b32 m0, s35
	s_nop 0
	global_load_lds_dwordx4 v158, s[100:101]
	s_waitcnt vmcnt(8)
	s_waitcnt lgkmcnt(0)
	s_barrier
	s_setprio 0
	s_waitcnt lgkmcnt(0)
	v_mfma_f32_16x16x32_bf16 v[58:61], v[130:133], v[180:183], v[58:61]
	v_mfma_f32_16x16x32_bf16 v[54:57], v[138:141], v[180:183], v[54:57]
	v_mfma_f32_16x16x32_bf16 v[42:45], v[130:133], v[192:195], v[42:45]
	v_mfma_f32_16x16x32_bf16 v[34:37], v[138:141], v[192:195], v[34:37]
	v_mfma_f32_16x16x32_bf16 v[26:29], v[130:133], v[200:203], v[26:29]
	v_mfma_f32_16x16x32_bf16 v[18:21], v[138:141], v[200:203], v[18:21]
	v_mfma_f32_16x16x32_bf16 v[6:9], v[130:133], v[208:211], v[6:9]
	v_mfma_f32_16x16x32_bf16 v[2:5], v[138:141], v[208:211], v[2:5]
	v_mfma_f32_16x16x32_bf16 v[58:61], v[134:137], v[188:191], v[58:61]
	v_mfma_f32_16x16x32_bf16 v[54:57], v[142:145], v[188:191], v[54:57]
	v_mfma_f32_16x16x32_bf16 v[42:45], v[134:137], v[196:199], v[42:45]
	v_mfma_f32_16x16x32_bf16 v[34:37], v[142:145], v[196:199], v[34:37]
	v_mfma_f32_16x16x32_bf16 v[26:29], v[134:137], v[204:207], v[26:29]
	v_mfma_f32_16x16x32_bf16 v[18:21], v[142:145], v[204:207], v[18:21]
	v_mfma_f32_16x16x32_bf16 v[6:9], v[134:137], v[212:215], v[6:9]
	v_mfma_f32_16x16x32_bf16 v[2:5], v[142:145], v[212:215], v[2:5]
	v_mfma_f32_16x16x32_bf16 v[62:65], v[146:149], v[180:183], v[62:65]
	v_mfma_f32_16x16x32_bf16 v[50:53], v[172:175], v[180:183], v[50:53]
	v_mfma_f32_16x16x32_bf16 v[46:49], v[146:149], v[192:195], v[46:49]
	v_mfma_f32_16x16x32_bf16 v[38:41], v[172:175], v[192:195], v[38:41]
	v_mfma_f32_16x16x32_bf16 v[30:33], v[146:149], v[200:203], v[30:33]
	v_mfma_f32_16x16x32_bf16 v[22:25], v[172:175], v[200:203], v[22:25]
	v_mfma_f32_16x16x32_bf16 v[10:13], v[146:149], v[208:211], v[10:13]
	v_mfma_f32_16x16x32_bf16 v[14:17], v[172:175], v[208:211], v[14:17]
	v_mfma_f32_16x16x32_bf16 v[62:65], v[150:153], v[188:191], v[62:65]
	v_mfma_f32_16x16x32_bf16 v[50:53], v[176:179], v[188:191], v[50:53]
	v_mfma_f32_16x16x32_bf16 v[46:49], v[150:153], v[196:199], v[46:49]
	v_mfma_f32_16x16x32_bf16 v[38:41], v[176:179], v[196:199], v[38:41]
	v_mfma_f32_16x16x32_bf16 v[30:33], v[150:153], v[204:207], v[30:33]
	v_mfma_f32_16x16x32_bf16 v[22:25], v[176:179], v[204:207], v[22:25]
	v_mfma_f32_16x16x32_bf16 v[10:13], v[150:153], v[212:215], v[10:13]
	v_mfma_f32_16x16x32_bf16 v[14:17], v[176:179], v[212:215], v[14:17]
	s_setprio 1
	s_barrier
	s_add_i32 s64, s64, 2
	s_add_u32 s18, s18, 0x100
	s_addc_u32 s19, s19, 0
	s_add_u32 s62, s62, 0x100
	s_addc_u32 s63, s63, 0
	s_cmpk_gt_u32 s64, 0xa9
	s_cbranch_scc0 .LBB0_1245
	s_and_b64 vcc, exec, s[12:13]
	s_cbranch_vccz .LBB0_1248
	s_barrier

; #define PG8_STAGE(bufoff, gbase, voff) do { _Pragma("unroll") for (int _i = 0; _i < 2; ++_i) \
;         __builtin_amdgcn_global_load_lds((const unsigned*)((const char*)(gbase) + (voff)[_i]), (PG8_LAS unsigned*)(lds + (bufoff) + ldsw + _i * 8192), 16, 0, 0); } while (0)
; #define PG8_LDA(dst, b, h) do { _Pragma("unroll") for (int m = 0; m < 4; ++m) _Pragma("unroll") for (int k = 0; k < 2; ++k) dst[m][k] = *(const PG8_LAS bf16x8*)(lds + PG8_SA(b, h) + aoff + m * 2048 + k * 1024); } while (0)
; #define PG8_LDB(dst, b, h) do { _Pragma("unroll") for (int n = 0; n < 2; ++n) _Pragma("unroll") for (int k = 0; k < 2; ++k) dst[n][k] = *(const PG8_LAS bf16x8*)(lds + PG8_SB(b, h) + boff + n * 2048 + k * 1024); } while (0)
; #define PG8_MMA(ai, bj, At, Bt) do { __builtin_amdgcn_s_setprio(1); _Pragma("unroll") for (int m = 0; m < 4; ++m) _Pragma("unroll") for (int n = 0; n < 2; ++n) _Pragma("unroll") for (int k = 0; k < 2; ++k) \
;         acc[ai][bj][m][n] = __builtin_amdgcn_mfma_f32_16x16x32_bf16(Bt[n][k], At[m][k], acc[ai][bj][m][n], 0, 0, 0); __builtin_amdgcn_s_setprio(0); } while (0)
; #define PG8_WAIT_V(n) asm volatile("s_waitcnt vmcnt(" #n ")" ::: "memory")
; #define PG8_WAIT_L(n) asm volatile("s_waitcnt lgkmcnt(" #n ")" ::: "memory")
; template <class Epi, class Sched, bool ALIGN_EPI = false, bool SP2 = false>
; __device__ __forceinline__ void gemm_phase(PG8_LAS unsigned char* lds, const Gemm g, const Sched& S, const Epi& E) {
;     ...
;             const bool last = (t == nt - 2);
;             const char* a1 = cA + (size_t)(t + 1) * kstep;
;             const char* a2 = last ? nA : cA + (size_t)(t + 2) * kstep; const char* b2 = last ? nB : cB + (size_t)(t + 2) * kstep;
;             const char* a3 = a2 + kstep; const char* b3 = b2 + kstep;
;             if (last && has_next) S.a_ready(nxt);
;             if constexpr (SP2) {
;             PG8_LDB(B0, 0, 0); PG8_LDB(B1, 0, 1); PG8_SCHED; PG8_LDA(At, 0, 0); PG8_STAGE(PG8_SA(1, 1), a1 + hstep, voffA);
;             PG8_WAIT_V(8); PG8_WAIT_L(0); PG8_BAR; PG8_MMA(0, 0, At, B0); PG8_MMA(0, 1, At, B1); PG8_BAR; PG8_SCHED;
;             PG8_LDA(At, 0, 1); PG8_STAGE(PG8_SB(0, 0), b2, voffB); PG8_STAGE(PG8_SB(0, 1), b2 + hstep, voffB); PG8_STAGE(PG8_SA(0, 0), a2, voffA);
;             PG8_WAIT_V(8); PG8_WAIT_L(0); PG8_BAR; PG8_MMA(1, 0, At, B0); PG8_MMA(1, 1, At, B1); PG8_BAR; PG8_SCHED;
.LBB0_1332:
	ds_read_b128 v[148:151], v241 offset:0
	ds_read_b128 v[156:159], v241 offset:1024
	ds_read_b128 v[166:169], v241 offset:2048
	ds_read_b128 v[170:173], v241 offset:3072
	ds_read_b128 v[174:177], v241 offset:16384
	ds_read_b128 v[178:181], v241 offset:17408
	ds_read_b128 v[182:185], v241 offset:18432
	ds_read_b128 v[186:189], v241 offset:19456
	s_add_u32 s20, s22, 0xfff00080
	s_addc_u32 s21, s23, -1
	s_cmp_eq_u32 s67, 60
	s_cselect_b32 s25, s13, s21
	s_cselect_b32 s24, s63, s20
	s_cselect_b32 s21, s11, s66
	s_cselect_b32 s20, s64, s65
	s_add_i32 m0, s19, 0xc000
	ds_read_b128 v[190:193], v155
	ds_read_b128 v[194:197], v155 offset:1024
	ds_read_b128 v[198:201], v155 offset:2048
	ds_read_b128 v[202:205], v155 offset:3072
	ds_read_b128 v[206:209], v155 offset:4096
	ds_read_b128 v[210:213], v155 offset:5120
	ds_read_b128 v[214:217], v155 offset:6144
	ds_read_b128 v[218:221], v155 offset:7168
	global_load_lds_dwordx4 v138, s[22:23]
	s_add_i32 m0, s19, 0xe000
	s_nop 0
	global_load_lds_dwordx4 v140, s[22:23]
	s_waitcnt vmcnt(8)
	s_waitcnt lgkmcnt(0)
	s_barrier
	s_setprio 0
	s_waitcnt lgkmcnt(0)
	v_mfma_f32_16x16x32_bf16 v[118:121], v[148:151], v[190:193], v[118:121]
	v_mfma_f32_16x16x32_bf16 v[114:117], v[166:169], v[190:193], v[114:117]
	v_mfma_f32_16x16x32_bf16 v[102:105], v[148:151], v[198:201], v[102:105]
	v_mfma_f32_16x16x32_bf16 v[98:101], v[166:169], v[198:201], v[98:101]
	v_mfma_f32_16x16x32_bf16 v[86:89], v[148:151], v[206:209], v[86:89]
	v_mfma_f32_16x16x32_bf16 v[82:85], v[166:169], v[206:209], v[82:85]
	v_mfma_f32_16x16x32_bf16 v[70:73], v[148:151], v[214:217], v[70:73]
	v_mfma_f32_16x16x32_bf16 v[66:69], v[166:169], v[214:217], v[66:69]
	v_mfma_f32_16x16x32_bf16 v[118:121], v[156:159], v[194:197], v[118:121]
	v_mfma_f32_16x16x32_bf16 v[114:117], v[170:173], v[194:197], v[114:117]
	v_mfma_f32_16x16x32_bf16 v[102:105], v[156:159], v[202:205], v[102:105]
	v_mfma_f32_16x16x32_bf16 v[98:101], v[170:173], v[202:205], v[98:101]
	v_mfma_f32_16x16x32_bf16 v[86:89], v[156:159], v[210:213], v[86:89]
	v_mfma_f32_16x16x32_bf16 v[82:85], v[170:173], v[210:213], v[82:85]
	v_mfma_f32_16x16x32_bf16 v[70:73], v[156:159], v[218:221], v[70:73]
	v_mfma_f32_16x16x32_bf16 v[66:69], v[170:173], v[218:221], v[66:69]
	v_mfma_f32_16x16x32_bf16 v[126:129], v[174:177], v[190:193], v[126:129]
	v_mfma_f32_16x16x32_bf16 v[122:125], v[182:185], v[190:193], v[122:125]
	v_mfma_f32_16x16x32_bf16 v[110:113], v[174:177], v[198:201], v[110:113]
	v_mfma_f32_16x16x32_bf16 v[106:109], v[182:185], v[198:201], v[106:109]
	v_mfma_f32_16x16x32_bf16 v[94:97], v[174:177], v[206:209], v[94:97]
	v_mfma_f32_16x16x32_bf16 v[90:93], v[182:185], v[206:209], v[90:93]
	v_mfma_f32_16x16x32_bf16 v[78:81], v[174:177], v[214:217], v[78:81]
	v_mfma_f32_16x16x32_bf16 v[74:77], v[182:185], v[214:217], v[74:77]
	v_mfma_f32_16x16x32_bf16 v[126:129], v[178:181], v[194:197], v[126:129]
	v_mfma_f32_16x16x32_bf16 v[122:125], v[186:189], v[194:197], v[122:125]
	v_mfma_f32_16x16x32_bf16 v[110:113], v[178:181], v[202:205], v[110:113]
	v_mfma_f32_16x16x32_bf16 v[106:109], v[186:189], v[202:205], v[106:109]
	v_mfma_f32_16x16x32_bf16 v[94:97], v[178:181], v[210:213], v[94:97]
	v_mfma_f32_16x16x32_bf16 v[90:93], v[186:189], v[210:213], v[90:93]
	v_mfma_f32_16x16x32_bf16 v[78:81], v[178:181], v[218:221], v[78:81]
	v_mfma_f32_16x16x32_bf16 v[74:77], v[186:189], v[218:221], v[74:77]
	s_setprio 1
	s_barrier
	s_add_i32 s33, s47, s28
	s_mov_b32 m0, s33
	ds_read_b128 v[190:193], v155 offset:16384
	ds_read_b128 v[194:197], v155 offset:17408
	ds_read_b128 v[198:201], v155 offset:18432
	ds_read_b128 v[202:205], v155 offset:19456
	ds_read_b128 v[206:209], v155 offset:20480
	ds_read_b128 v[210:213], v155 offset:21504
	ds_read_b128 v[214:217], v155 offset:22528
	ds_read_b128 v[218:221], v155 offset:23552
	global_load_lds_dwordx4 v132, s[20:21]
	s_add_i32 m0, s33, 0x2000
	s_add_u32 s68, s20, 0x100000
	s_addc_u32 s69, s21, 0
	s_add_i32 s33, s52, s28
	global_load_lds_dwordx4 v136, s[20:21]
	s_mov_b32 m0, s33
	s_add_u32 s100, s24, 0x80
	s_addc_u32 s101, s25, 0
	global_load_lds_dwordx4 v132, s[68:69]
	s_add_i32 m0, s33, 0x2000
	s_nop 0
	global_load_lds_dwordx4 v136, s[68:69]
	s_mov_b32 m0, s19
	s_nop 0
	global_load_lds_dwordx4 v130, s[24:25]
	s_mov_b32 m0, s35
	s_nop 0
	global_load_lds_dwordx4 v134, s[24:25]
	s_waitcnt vmcnt(8)
	s_waitcnt lgkmcnt(0)
	s_barrier
	s_setprio 0
	s_waitcnt lgkmcnt(0)
	v_mfma_f32_16x16x32_bf16 v[54:57], v[148:151], v[190:193], v[54:57]
	v_mfma_f32_16x16x32_bf16 v[50:53], v[166:169], v[190:193], v[50:53]
	v_mfma_f32_16x16x32_bf16 v[38:41], v[148:151], v[198:201], v[38:41]
	v_mfma_f32_16x16x32_bf16 v[34:37], v[166:169], v[198:201], v[34:37]
	v_mfma_f32_16x16x32_bf16 v[22:25], v[148:151], v[206:209], v[22:25]
	v_mfma_f32_16x16x32_bf16 v[18:21], v[166:169], v[206:209], v[18:21]
	v_mfma_f32_16x16x32_bf16 v[6:9], v[148:151], v[214:217], v[6:9]
	v_mfma_f32_16x16x32_bf16 v[2:5], v[166:169], v[214:217], v[2:5]
	v_mfma_f32_16x16x32_bf16 v[54:57], v[156:159], v[194:197], v[54:57]
	v_mfma_f32_16x16x32_bf16 v[50:53], v[170:173], v[194:197], v[50:53]
	v_mfma_f32_16x16x32_bf16 v[38:41], v[156:159], v[202:205], v[38:41]
	v_mfma_f32_16x16x32_bf16 v[34:37], v[170:173], v[202:205], v[34:37]
	v_mfma_f32_16x16x32_bf16 v[22:25], v[156:159], v[210:213], v[22:25]
	v_mfma_f32_16x16x32_bf16 v[18:21], v[170:173], v[210:213], v[18:21]
	v_mfma_f32_16x16x32_bf16 v[6:9], v[156:159], v[218:221], v[6:9]
	v_mfma_f32_16x16x32_bf16 v[2:5], v[170:173], v[218:221], v[2:5]
	v_mfma_f32_16x16x32_bf16 v[62:65], v[174:177], v[190:193], v[62:65]
	v_mfma_f32_16x16x32_bf16 v[58:61], v[182:185], v[190:193], v[58:61]
	v_mfma_f32_16x16x32_bf16 v[46:49], v[174:177], v[198:201], v[46:49]
	v_mfma_f32_16x16x32_bf16 v[42:45], v[182:185], v[198:201], v[42:45]
	v_mfma_f32_16x16x32_bf16 v[30:33], v[174:177], v[206:209], v[30:33]
	v_mfma_f32_16x16x32_bf16 v[26:29], v[182:185], v[206:209], v[26:29]
	v_mfma_f32_16x16x32_bf16 v[10:13], v[174:177], v[214:217], v[10:13]
	v_mfma_f32_16x16x32_bf16 v[14:17], v[182:185], v[214:217], v[14:17]
	v_mfma_f32_16x16x32_bf16 v[62:65], v[178:181], v[194:197], v[62:65]
	v_mfma_f32_16x16x32_bf16 v[58:61], v[186:189], v[194:197], v[58:61]
	v_mfma_f32_16x16x32_bf16 v[46:49], v[178:181], v[202:205], v[46:49]
	v_mfma_f32_16x16x32_bf16 v[42:45], v[186:189], v[202:205], v[42:45]
	v_mfma_f32_16x16x32_bf16 v[30:33], v[178:181], v[210:213], v[30:33]
	v_mfma_f32_16x16x32_bf16 v[26:29], v[186:189], v[210:213], v[26:29]
	v_mfma_f32_16x16x32_bf16 v[10:13], v[178:181], v[218:221], v[10:13]
	v_mfma_f32_16x16x32_bf16 v[14:17], v[186:189], v[218:221], v[14:17]
	s_setprio 1
	s_barrier
; #define PG8_STAGE(bufoff, gbase, voff) do { _Pragma("unroll") for (int _i = 0; _i < 2; ++_i) \
;         __builtin_amdgcn_global_load_lds((const unsigned*)((const char*)(gbase) + (voff)[_i]), (PG8_LAS unsigned*)(lds + (bufoff) + ldsw + _i * 8192), 16, 0, 0); } while (0)
; #define PG8_LDA(dst, b, h) do { _Pragma("unroll") for (int m = 0; m < 4; ++m) _Pragma("unroll") for (int k = 0; k < 2; ++k) dst[m][k] = *(const PG8_LAS bf16x8*)(lds + PG8_SA(b, h) + aoff + m * 2048 + k * 1024); } while (0)
; #define PG8_LDB(dst, b, h) do { _Pragma("unroll") for (int n = 0; n < 2; ++n) _Pragma("unroll") for (int k = 0; k < 2; ++k) dst[n][k] = *(const PG8_LAS bf16x8*)(lds + PG8_SB(b, h) + boff + n * 2048 + k * 1024); } while (0)
; #define PG8_MMA(ai, bj, At, Bt) do { __builtin_amdgcn_s_setprio(1); _Pragma("unroll") for (int m = 0; m < 4; ++m) _Pragma("unroll") for (int n = 0; n < 2; ++n) _Pragma("unroll") for (int k = 0; k < 2; ++k) \
;         acc[ai][bj][m][n] = __builtin_amdgcn_mfma_f32_16x16x32_bf16(Bt[n][k], At[m][k], acc[ai][bj][m][n], 0, 0, 0); __builtin_amdgcn_s_setprio(0); } while (0)
; #define PG8_WAIT_V(n) asm volatile("s_waitcnt vmcnt(" #n ")" ::: "memory")
; #define PG8_WAIT_L(n) asm volatile("s_waitcnt lgkmcnt(" #n ")" ::: "memory")
; #define PG8_BAR __builtin_amdgcn_s_barrier()
; #define PG8_SCHED __builtin_amdgcn_sched_barrier(0)
; template <class Epi, class Sched, bool ALIGN_EPI = false, bool SP2 = false>
; __device__ __forceinline__ void gemm_phase(PG8_LAS unsigned char* lds, const Gemm g, const Sched& S, const Epi& E) {
;     ...
;             PG8_LDB(B0, 1, 0); PG8_LDB(B1, 1, 1); PG8_SCHED; PG8_LDA(At, 1, 0); PG8_STAGE(PG8_SA(0, 1), a2 + hstep, voffA);
;             PG8_WAIT_V(8); PG8_WAIT_L(0); PG8_BAR; PG8_MMA(0, 0, At, B0); PG8_MMA(0, 1, At, B1); PG8_BAR; PG8_SCHED;
;             PG8_LDA(At, 1, 1); PG8_STAGE(PG8_SB(1, 0), b3, voffB); PG8_STAGE(PG8_SB(1, 1), b3 + hstep, voffB); PG8_STAGE(PG8_SA(1, 0), a3, voffA);
;             PG8_WAIT_V(8); PG8_WAIT_L(0); PG8_BAR; PG8_MMA(1, 0, At, B0); PG8_MMA(1, 1, At, B1); PG8_BAR; PG8_SCHED;
	s_add_i32 s33, 0, 0x18000
	s_add_i32 s42, 0, 0x1c000
	ds_read_b128 v[148:151], v241 offset:32768
	ds_read_b128 v[156:159], v241 offset:33792
	ds_read_b128 v[166:169], v241 offset:34816
	ds_read_b128 v[170:173], v241 offset:35840
	ds_read_b128 v[174:177], v241 offset:49152
	ds_read_b128 v[178:181], v241 offset:50176
	ds_read_b128 v[182:185], v241 offset:51200
	ds_read_b128 v[186:189], v241 offset:52224
	s_add_u32 s24, s24, 0x100000
	s_addc_u32 s25, s25, 0
	s_mov_b32 m0, s36
	ds_read_b128 v[190:193], v155 offset:32768
	ds_read_b128 v[194:197], v155 offset:33792
	ds_read_b128 v[198:201], v155 offset:34816
	ds_read_b128 v[202:205], v155 offset:35840
	ds_read_b128 v[206:209], v155 offset:36864
	ds_read_b128 v[210:213], v155 offset:37888
	ds_read_b128 v[214:217], v155 offset:38912
	ds_read_b128 v[218:221], v155 offset:39936
	global_load_lds_dwordx4 v130, s[24:25]
	s_mov_b32 m0, s37
	s_nop 0
	global_load_lds_dwordx4 v134, s[24:25]
	s_waitcnt vmcnt(8)
	s_waitcnt lgkmcnt(0)
	s_barrier
	s_setprio 0
	s_waitcnt lgkmcnt(0)
	v_mfma_f32_16x16x32_bf16 v[118:121], v[148:151], v[190:193], v[118:121]
	v_mfma_f32_16x16x32_bf16 v[114:117], v[166:169], v[190:193], v[114:117]
	v_mfma_f32_16x16x32_bf16 v[102:105], v[148:151], v[198:201], v[102:105]
	v_mfma_f32_16x16x32_bf16 v[98:101], v[166:169], v[198:201], v[98:101]
	v_mfma_f32_16x16x32_bf16 v[86:89], v[148:151], v[206:209], v[86:89]
	v_mfma_f32_16x16x32_bf16 v[82:85], v[166:169], v[206:209], v[82:85]
	v_mfma_f32_16x16x32_bf16 v[70:73], v[148:151], v[214:217], v[70:73]
	v_mfma_f32_16x16x32_bf16 v[66:69], v[166:169], v[214:217], v[66:69]
	v_mfma_f32_16x16x32_bf16 v[118:121], v[156:159], v[194:197], v[118:121]
	v_mfma_f32_16x16x32_bf16 v[114:117], v[170:173], v[194:197], v[114:117]
	v_mfma_f32_16x16x32_bf16 v[102:105], v[156:159], v[202:205], v[102:105]
	v_mfma_f32_16x16x32_bf16 v[98:101], v[170:173], v[202:205], v[98:101]
	v_mfma_f32_16x16x32_bf16 v[86:89], v[156:159], v[210:213], v[86:89]
	v_mfma_f32_16x16x32_bf16 v[82:85], v[170:173], v[210:213], v[82:85]
	v_mfma_f32_16x16x32_bf16 v[70:73], v[156:159], v[218:221], v[70:73]
	v_mfma_f32_16x16x32_bf16 v[66:69], v[170:173], v[218:221], v[66:69]
	v_mfma_f32_16x16x32_bf16 v[126:129], v[174:177], v[190:193], v[126:129]
	v_mfma_f32_16x16x32_bf16 v[122:125], v[182:185], v[190:193], v[122:125]
	v_mfma_f32_16x16x32_bf16 v[110:113], v[174:177], v[198:201], v[110:113]
	v_mfma_f32_16x16x32_bf16 v[106:109], v[182:185], v[198:201], v[106:109]
	v_mfma_f32_16x16x32_bf16 v[94:97], v[174:177], v[206:209], v[94:97]
	v_mfma_f32_16x16x32_bf16 v[90:93], v[182:185], v[206:209], v[90:93]
	v_mfma_f32_16x16x32_bf16 v[78:81], v[174:177], v[214:217], v[78:81]
	v_mfma_f32_16x16x32_bf16 v[74:77], v[182:185], v[214:217], v[74:77]
	v_mfma_f32_16x16x32_bf16 v[126:129], v[178:181], v[194:197], v[126:129]
	v_mfma_f32_16x16x32_bf16 v[122:125], v[186:189], v[194:197], v[122:125]
	v_mfma_f32_16x16x32_bf16 v[110:113], v[178:181], v[202:205], v[110:113]
	v_mfma_f32_16x16x32_bf16 v[106:109], v[186:189], v[202:205], v[106:109]
	v_mfma_f32_16x16x32_bf16 v[94:97], v[178:181], v[210:213], v[94:97]
	v_mfma_f32_16x16x32_bf16 v[90:93], v[186:189], v[210:213], v[90:93]
	v_mfma_f32_16x16x32_bf16 v[78:81], v[178:181], v[218:221], v[78:81]
	v_mfma_f32_16x16x32_bf16 v[74:77], v[186:189], v[218:221], v[74:77]
	s_setprio 1
	s_barrier
	s_add_i32 s24, s33, s28
	s_add_i32 m0, s24, 0xffffff80
	ds_read_b128 v[190:193], v155 offset:49152
	ds_read_b128 v[194:197], v155 offset:50176
	ds_read_b128 v[198:201], v155 offset:51200
	ds_read_b128 v[202:205], v155 offset:52224
	ds_read_b128 v[206:209], v155 offset:53248
	ds_read_b128 v[210:213], v155 offset:54272
	ds_read_b128 v[214:217], v155 offset:55296
	ds_read_b128 v[218:221], v155 offset:56320
	global_load_lds_dwordx4 v132, s[20:21] offset:128
	s_add_i32 m0, s24, 0x1f80
	s_add_i32 s24, s42, s28
	global_load_lds_dwordx4 v136, s[20:21] offset:128
	s_add_u32 s20, s20, 0x100080
	s_addc_u32 s21, s21, 0
	s_mov_b32 m0, s24
	s_nop 0
	global_load_lds_dwordx4 v132, s[20:21]
	s_add_i32 m0, s24, 0x2000
	s_nop 0
	global_load_lds_dwordx4 v136, s[20:21]
	s_mov_b32 m0, s43
	s_nop 0
	global_load_lds_dwordx4 v130, s[100:101]
	s_mov_b32 m0, s46
	s_nop 0
	global_load_lds_dwordx4 v134, s[100:101]
	s_waitcnt vmcnt(8)
	s_waitcnt lgkmcnt(0)
	s_barrier
	s_setprio 0
	s_waitcnt lgkmcnt(0)
	v_mfma_f32_16x16x32_bf16 v[54:57], v[148:151], v[190:193], v[54:57]
	v_mfma_f32_16x16x32_bf16 v[50:53], v[166:169], v[190:193], v[50:53]
	v_mfma_f32_16x16x32_bf16 v[38:41], v[148:151], v[198:201], v[38:41]
	v_mfma_f32_16x16x32_bf16 v[34:37], v[166:169], v[198:201], v[34:37]
	v_mfma_f32_16x16x32_bf16 v[22:25], v[148:151], v[206:209], v[22:25]
	v_mfma_f32_16x16x32_bf16 v[18:21], v[166:169], v[206:209], v[18:21]
	v_mfma_f32_16x16x32_bf16 v[6:9], v[148:151], v[214:217], v[6:9]
	v_mfma_f32_16x16x32_bf16 v[2:5], v[166:169], v[214:217], v[2:5]
	v_mfma_f32_16x16x32_bf16 v[54:57], v[156:159], v[194:197], v[54:57]
	v_mfma_f32_16x16x32_bf16 v[50:53], v[170:173], v[194:197], v[50:53]
	v_mfma_f32_16x16x32_bf16 v[38:41], v[156:159], v[202:205], v[38:41]
	v_mfma_f32_16x16x32_bf16 v[34:37], v[170:173], v[202:205], v[34:37]
	v_mfma_f32_16x16x32_bf16 v[22:25], v[156:159], v[210:213], v[22:25]
	v_mfma_f32_16x16x32_bf16 v[18:21], v[170:173], v[210:213], v[18:21]
	v_mfma_f32_16x16x32_bf16 v[6:9], v[156:159], v[218:221], v[6:9]
	v_mfma_f32_16x16x32_bf16 v[2:5], v[170:173], v[218:221], v[2:5]
	v_mfma_f32_16x16x32_bf16 v[62:65], v[174:177], v[190:193], v[62:65]
	v_mfma_f32_16x16x32_bf16 v[58:61], v[182:185], v[190:193], v[58:61]
	v_mfma_f32_16x16x32_bf16 v[46:49], v[174:177], v[198:201], v[46:49]
	v_mfma_f32_16x16x32_bf16 v[42:45], v[182:185], v[198:201], v[42:45]
	v_mfma_f32_16x16x32_bf16 v[30:33], v[174:177], v[206:209], v[30:33]
	v_mfma_f32_16x16x32_bf16 v[26:29], v[182:185], v[206:209], v[26:29]
	v_mfma_f32_16x16x32_bf16 v[10:13], v[174:177], v[214:217], v[10:13]
	v_mfma_f32_16x16x32_bf16 v[14:17], v[182:185], v[214:217], v[14:17]
	v_mfma_f32_16x16x32_bf16 v[62:65], v[178:181], v[194:197], v[62:65]
	v_mfma_f32_16x16x32_bf16 v[58:61], v[186:189], v[194:197], v[58:61]
	v_mfma_f32_16x16x32_bf16 v[46:49], v[178:181], v[202:205], v[46:49]
	v_mfma_f32_16x16x32_bf16 v[42:45], v[186:189], v[202:205], v[42:45]
	v_mfma_f32_16x16x32_bf16 v[30:33], v[178:181], v[210:213], v[30:33]
	v_mfma_f32_16x16x32_bf16 v[26:29], v[186:189], v[210:213], v[26:29]
	v_mfma_f32_16x16x32_bf16 v[10:13], v[178:181], v[218:221], v[10:13]
	v_mfma_f32_16x16x32_bf16 v[14:17], v[186:189], v[218:221], v[14:17]
	s_setprio 1
	s_barrier
	s_add_i32 s67, s67, 2
	s_add_u32 s22, s22, 0x100
	s_addc_u32 s23, s23, 0
	s_add_u32 s65, s65, 0x100
	s_addc_u32 s66, s66, 0
	s_cmp_gt_u32 s67, 61
	s_cbranch_scc0 .LBB0_1332
	s_and_b64 vcc, exec, s[8:9]
	s_cbranch_vccz .LBB0_1335
	s_barrier

; #define PG8_STAGE(bufoff, gbase, voff) do { _Pragma("unroll") for (int _i = 0; _i < 2; ++_i) \
;         __builtin_amdgcn_global_load_lds((const unsigned*)((const char*)(gbase) + (voff)[_i]), (PG8_LAS unsigned*)(lds + (bufoff) + ldsw + _i * 8192), 16, 0, 0); } while (0)
; #define PG8_LDA(dst, b, h) do { _Pragma("unroll") for (int m = 0; m < 4; ++m) _Pragma("unroll") for (int k = 0; k < 2; ++k) dst[m][k] = *(const PG8_LAS bf16x8*)(lds + PG8_SA(b, h) + aoff + m * 2048 + k * 1024); } while (0)
; #define PG8_LDB(dst, b, h) do { _Pragma("unroll") for (int n = 0; n < 2; ++n) _Pragma("unroll") for (int k = 0; k < 2; ++k) dst[n][k] = *(const PG8_LAS bf16x8*)(lds + PG8_SB(b, h) + boff + n * 2048 + k * 1024); } while (0)
; #define PG8_MMA(ai, bj, At, Bt) do { __builtin_amdgcn_s_setprio(1); _Pragma("unroll") for (int m = 0; m < 4; ++m) _Pragma("unroll") for (int n = 0; n < 2; ++n) _Pragma("unroll") for (int k = 0; k < 2; ++k) \
;         acc[ai][bj][m][n] = __builtin_amdgcn_mfma_f32_16x16x32_bf16(Bt[n][k], At[m][k], acc[ai][bj][m][n], 0, 0, 0); __builtin_amdgcn_s_setprio(0); } while (0)
; #define PG8_WAIT_V(n) asm volatile("s_waitcnt vmcnt(" #n ")" ::: "memory")
; #define PG8_WAIT_L(n) asm volatile("s_waitcnt lgkmcnt(" #n ")" ::: "memory")
; template <class Epi, class Sched, bool ALIGN_EPI = false, bool SP2 = false>
; __device__ __forceinline__ void gemm_phase(PG8_LAS unsigned char* lds, const Gemm g, const Sched& S, const Epi& E) {
;     ...
;             const bool last = (t == nt - 2);
;             const char* a1 = cA + (size_t)(t + 1) * kstep;
;             const char* a2 = last ? nA : cA + (size_t)(t + 2) * kstep; const char* b2 = last ? nB : cB + (size_t)(t + 2) * kstep;
;             const char* a3 = a2 + kstep; const char* b3 = b2 + kstep;
;             if (last && has_next) S.a_ready(nxt);
;             if constexpr (SP2) {
;             PG8_LDB(B0, 0, 0); PG8_LDB(B1, 0, 1); PG8_SCHED; PG8_LDA(At, 0, 0); PG8_STAGE(PG8_SA(1, 1), a1 + hstep, voffA);
;             PG8_WAIT_V(8); PG8_WAIT_L(0); PG8_BAR; PG8_MMA(0, 0, At, B0); PG8_MMA(0, 1, At, B1); PG8_BAR; PG8_SCHED;
;             PG8_LDA(At, 0, 1); PG8_STAGE(PG8_SB(0, 0), b2, voffB); PG8_STAGE(PG8_SB(0, 1), b2 + hstep, voffB); PG8_STAGE(PG8_SA(0, 0), a2, voffA);
;             PG8_WAIT_V(8); PG8_WAIT_L(0); PG8_BAR; PG8_MMA(1, 0, At, B0); PG8_MMA(1, 1, At, B1); PG8_BAR; PG8_SCHED;
.LBB0_1595:
	ds_read_b128 v[130:133], v241 offset:0
	ds_read_b128 v[134:137], v241 offset:1024
	ds_read_b128 v[138:141], v241 offset:2048
	ds_read_b128 v[142:145], v241 offset:3072
	ds_read_b128 v[146:149], v241 offset:16384
	ds_read_b128 v[150:153], v241 offset:17408
	ds_read_b128 v[172:175], v241 offset:18432
	ds_read_b128 v[176:179], v241 offset:19456
	s_add_u32 s24, s26, 0xfff00080
	s_addc_u32 s25, s27, -1
	s_cmp_eq_u32 s62, 60
	s_cselect_b32 s29, s15, s25
	s_cselect_b32 s28, s21, s24
	s_cselect_b32 s25, s13, s53
	s_cselect_b32 s24, s51, s52
	s_add_i32 m0, s23, 0xc000
	ds_read_b128 v[180:183], v185
	ds_read_b128 v[188:191], v185 offset:1024
	ds_read_b128 v[192:195], v185 offset:2048
	ds_read_b128 v[196:199], v185 offset:3072
	ds_read_b128 v[200:203], v185 offset:4096
	ds_read_b128 v[204:207], v185 offset:5120
	ds_read_b128 v[208:211], v185 offset:6144
	ds_read_b128 v[212:215], v185 offset:7168
	global_load_lds_dwordx4 v162, s[26:27]
	s_add_i32 m0, s23, 0xe000
	s_nop 0
	global_load_lds_dwordx4 v166, s[26:27]
	s_waitcnt vmcnt(8)
	s_waitcnt lgkmcnt(0)
	s_barrier
	s_setprio 0
	s_waitcnt lgkmcnt(0)
	v_mfma_f32_16x16x32_bf16 v[114:117], v[130:133], v[180:183], v[114:117]
	v_mfma_f32_16x16x32_bf16 v[118:121], v[138:141], v[180:183], v[118:121]
	v_mfma_f32_16x16x32_bf16 v[106:109], v[130:133], v[192:195], v[106:109]
	v_mfma_f32_16x16x32_bf16 v[98:101], v[138:141], v[192:195], v[98:101]
	v_mfma_f32_16x16x32_bf16 v[90:93], v[130:133], v[200:203], v[90:93]
	v_mfma_f32_16x16x32_bf16 v[82:85], v[138:141], v[200:203], v[82:85]
	v_mfma_f32_16x16x32_bf16 v[74:77], v[130:133], v[208:211], v[74:77]
	v_mfma_f32_16x16x32_bf16 v[66:69], v[138:141], v[208:211], v[66:69]
	v_mfma_f32_16x16x32_bf16 v[114:117], v[134:137], v[188:191], v[114:117]
	v_mfma_f32_16x16x32_bf16 v[118:121], v[142:145], v[188:191], v[118:121]
	v_mfma_f32_16x16x32_bf16 v[106:109], v[134:137], v[196:199], v[106:109]
	v_mfma_f32_16x16x32_bf16 v[98:101], v[142:145], v[196:199], v[98:101]
	v_mfma_f32_16x16x32_bf16 v[90:93], v[134:137], v[204:207], v[90:93]
	v_mfma_f32_16x16x32_bf16 v[82:85], v[142:145], v[204:207], v[82:85]
	v_mfma_f32_16x16x32_bf16 v[74:77], v[134:137], v[212:215], v[74:77]
	v_mfma_f32_16x16x32_bf16 v[66:69], v[142:145], v[212:215], v[66:69]
	v_mfma_f32_16x16x32_bf16 v[122:125], v[146:149], v[180:183], v[122:125]
	v_mfma_f32_16x16x32_bf16 v[126:129], v[172:175], v[180:183], v[126:129]
	v_mfma_f32_16x16x32_bf16 v[110:113], v[146:149], v[192:195], v[110:113]
	v_mfma_f32_16x16x32_bf16 v[102:105], v[172:175], v[192:195], v[102:105]
	v_mfma_f32_16x16x32_bf16 v[94:97], v[146:149], v[200:203], v[94:97]
	v_mfma_f32_16x16x32_bf16 v[86:89], v[172:175], v[200:203], v[86:89]
	v_mfma_f32_16x16x32_bf16 v[78:81], v[146:149], v[208:211], v[78:81]
	v_mfma_f32_16x16x32_bf16 v[70:73], v[172:175], v[208:211], v[70:73]
	v_mfma_f32_16x16x32_bf16 v[122:125], v[150:153], v[188:191], v[122:125]
	v_mfma_f32_16x16x32_bf16 v[126:129], v[176:179], v[188:191], v[126:129]
	v_mfma_f32_16x16x32_bf16 v[110:113], v[150:153], v[196:199], v[110:113]
	v_mfma_f32_16x16x32_bf16 v[102:105], v[176:179], v[196:199], v[102:105]
	v_mfma_f32_16x16x32_bf16 v[94:97], v[150:153], v[204:207], v[94:97]
	v_mfma_f32_16x16x32_bf16 v[86:89], v[176:179], v[204:207], v[86:89]
	v_mfma_f32_16x16x32_bf16 v[78:81], v[150:153], v[212:215], v[78:81]
	v_mfma_f32_16x16x32_bf16 v[70:73], v[176:179], v[212:215], v[70:73]
	s_setprio 1
	s_barrier
	s_add_i32 s33, s48, s36
	s_mov_b32 m0, s33
	ds_read_b128 v[180:183], v185 offset:16384
	ds_read_b128 v[188:191], v185 offset:17408
	ds_read_b128 v[192:195], v185 offset:18432
	ds_read_b128 v[196:199], v185 offset:19456
	ds_read_b128 v[200:203], v185 offset:20480
	ds_read_b128 v[204:207], v185 offset:21504
	ds_read_b128 v[208:211], v185 offset:22528
	ds_read_b128 v[212:215], v185 offset:23552
	global_load_lds_dwordx4 v156, s[24:25]
	s_add_i32 m0, s33, 0x2000
	s_add_u32 s64, s24, 0x100000
	s_addc_u32 s65, s25, 0
	s_add_i32 s33, s49, s36
	global_load_lds_dwordx4 v160, s[24:25]
	s_mov_b32 m0, s33
	s_add_u32 s100, s28, 0x80
	s_addc_u32 s101, s29, 0
	global_load_lds_dwordx4 v156, s[64:65]
	s_add_i32 m0, s33, 0x2000
	s_nop 0
	global_load_lds_dwordx4 v160, s[64:65]
	s_mov_b32 m0, s23
	s_nop 0
	global_load_lds_dwordx4 v154, s[28:29]
	s_mov_b32 m0, s37
	s_nop 0
	global_load_lds_dwordx4 v158, s[28:29]
	s_waitcnt vmcnt(8)
	s_waitcnt lgkmcnt(0)
	s_barrier
	s_setprio 0
	s_waitcnt lgkmcnt(0)
	v_mfma_f32_16x16x32_bf16 v[58:61], v[130:133], v[180:183], v[58:61]
	v_mfma_f32_16x16x32_bf16 v[54:57], v[138:141], v[180:183], v[54:57]
	v_mfma_f32_16x16x32_bf16 v[42:45], v[130:133], v[192:195], v[42:45]
	v_mfma_f32_16x16x32_bf16 v[34:37], v[138:141], v[192:195], v[34:37]
	v_mfma_f32_16x16x32_bf16 v[26:29], v[130:133], v[200:203], v[26:29]
	v_mfma_f32_16x16x32_bf16 v[18:21], v[138:141], v[200:203], v[18:21]
	v_mfma_f32_16x16x32_bf16 v[6:9], v[130:133], v[208:211], v[6:9]
	v_mfma_f32_16x16x32_bf16 v[2:5], v[138:141], v[208:211], v[2:5]
	v_mfma_f32_16x16x32_bf16 v[58:61], v[134:137], v[188:191], v[58:61]
	v_mfma_f32_16x16x32_bf16 v[54:57], v[142:145], v[188:191], v[54:57]
	v_mfma_f32_16x16x32_bf16 v[42:45], v[134:137], v[196:199], v[42:45]
	v_mfma_f32_16x16x32_bf16 v[34:37], v[142:145], v[196:199], v[34:37]
	v_mfma_f32_16x16x32_bf16 v[26:29], v[134:137], v[204:207], v[26:29]
	v_mfma_f32_16x16x32_bf16 v[18:21], v[142:145], v[204:207], v[18:21]
	v_mfma_f32_16x16x32_bf16 v[6:9], v[134:137], v[212:215], v[6:9]
	v_mfma_f32_16x16x32_bf16 v[2:5], v[142:145], v[212:215], v[2:5]
	v_mfma_f32_16x16x32_bf16 v[62:65], v[146:149], v[180:183], v[62:65]
	v_mfma_f32_16x16x32_bf16 v[50:53], v[172:175], v[180:183], v[50:53]
	v_mfma_f32_16x16x32_bf16 v[46:49], v[146:149], v[192:195], v[46:49]
	v_mfma_f32_16x16x32_bf16 v[38:41], v[172:175], v[192:195], v[38:41]
	v_mfma_f32_16x16x32_bf16 v[30:33], v[146:149], v[200:203], v[30:33]
	v_mfma_f32_16x16x32_bf16 v[22:25], v[172:175], v[200:203], v[22:25]
	v_mfma_f32_16x16x32_bf16 v[10:13], v[146:149], v[208:211], v[10:13]
	v_mfma_f32_16x16x32_bf16 v[14:17], v[172:175], v[208:211], v[14:17]
	v_mfma_f32_16x16x32_bf16 v[62:65], v[150:153], v[188:191], v[62:65]
	v_mfma_f32_16x16x32_bf16 v[50:53], v[176:179], v[188:191], v[50:53]
	v_mfma_f32_16x16x32_bf16 v[46:49], v[150:153], v[196:199], v[46:49]
	v_mfma_f32_16x16x32_bf16 v[38:41], v[176:179], v[196:199], v[38:41]
	v_mfma_f32_16x16x32_bf16 v[30:33], v[150:153], v[204:207], v[30:33]
	v_mfma_f32_16x16x32_bf16 v[22:25], v[176:179], v[204:207], v[22:25]
	v_mfma_f32_16x16x32_bf16 v[10:13], v[150:153], v[212:215], v[10:13]
	v_mfma_f32_16x16x32_bf16 v[14:17], v[176:179], v[212:215], v[14:17]
	s_setprio 1
	s_barrier
; #define PG8_STAGE(bufoff, gbase, voff) do { _Pragma("unroll") for (int _i = 0; _i < 2; ++_i) \
;         __builtin_amdgcn_global_load_lds((const unsigned*)((const char*)(gbase) + (voff)[_i]), (PG8_LAS unsigned*)(lds + (bufoff) + ldsw + _i * 8192), 16, 0, 0); } while (0)
; #define PG8_LDA(dst, b, h) do { _Pragma("unroll") for (int m = 0; m < 4; ++m) _Pragma("unroll") for (int k = 0; k < 2; ++k) dst[m][k] = *(const PG8_LAS bf16x8*)(lds + PG8_SA(b, h) + aoff + m * 2048 + k * 1024); } while (0)
; #define PG8_LDB(dst, b, h) do { _Pragma("unroll") for (int n = 0; n < 2; ++n) _Pragma("unroll") for (int k = 0; k < 2; ++k) dst[n][k] = *(const PG8_LAS bf16x8*)(lds + PG8_SB(b, h) + boff + n * 2048 + k * 1024); } while (0)
; #define PG8_MMA(ai, bj, At, Bt) do { __builtin_amdgcn_s_setprio(1); _Pragma("unroll") for (int m = 0; m < 4; ++m) _Pragma("unroll") for (int n = 0; n < 2; ++n) _Pragma("unroll") for (int k = 0; k < 2; ++k) \
;         acc[ai][bj][m][n] = __builtin_amdgcn_mfma_f32_16x16x32_bf16(Bt[n][k], At[m][k], acc[ai][bj][m][n], 0, 0, 0); __builtin_amdgcn_s_setprio(0); } while (0)
; #define PG8_WAIT_V(n) asm volatile("s_waitcnt vmcnt(" #n ")" ::: "memory")
; #define PG8_WAIT_L(n) asm volatile("s_waitcnt lgkmcnt(" #n ")" ::: "memory")
; #define PG8_BAR __builtin_amdgcn_s_barrier()
; #define PG8_SCHED __builtin_amdgcn_sched_barrier(0)
; template <class Epi, class Sched, bool ALIGN_EPI = false, bool SP2 = false>
; __device__ __forceinline__ void gemm_phase(PG8_LAS unsigned char* lds, const Gemm g, const Sched& S, const Epi& E) {
;     ...
;             PG8_LDB(B0, 1, 0); PG8_LDB(B1, 1, 1); PG8_SCHED; PG8_LDA(At, 1, 0); PG8_STAGE(PG8_SA(0, 1), a2 + hstep, voffA);
;             PG8_WAIT_V(8); PG8_WAIT_L(0); PG8_BAR; PG8_MMA(0, 0, At, B0); PG8_MMA(0, 1, At, B1); PG8_BAR; PG8_SCHED;
;             PG8_LDA(At, 1, 1); PG8_STAGE(PG8_SB(1, 0), b3, voffB); PG8_STAGE(PG8_SB(1, 1), b3 + hstep, voffB); PG8_STAGE(PG8_SA(1, 0), a3, voffA);
;             PG8_WAIT_V(8); PG8_WAIT_L(0); PG8_BAR; PG8_MMA(1, 0, At, B0); PG8_MMA(1, 1, At, B1); PG8_BAR; PG8_SCHED;
	s_add_i32 s33, 0, 0x18000
	s_add_i32 s42, 0, 0x1c000
	ds_read_b128 v[130:133], v241 offset:32768
	ds_read_b128 v[134:137], v241 offset:33792
	ds_read_b128 v[138:141], v241 offset:34816
	ds_read_b128 v[142:145], v241 offset:35840
	ds_read_b128 v[146:149], v241 offset:49152
	ds_read_b128 v[150:153], v241 offset:50176
	ds_read_b128 v[172:175], v241 offset:51200
	ds_read_b128 v[176:179], v241 offset:52224
	s_add_u32 s28, s28, 0x100000
	s_addc_u32 s29, s29, 0
	s_mov_b32 m0, s40
	ds_read_b128 v[180:183], v185 offset:32768
	ds_read_b128 v[188:191], v185 offset:33792
	ds_read_b128 v[192:195], v185 offset:34816
	ds_read_b128 v[196:199], v185 offset:35840
	ds_read_b128 v[200:203], v185 offset:36864
	ds_read_b128 v[204:207], v185 offset:37888
	ds_read_b128 v[208:211], v185 offset:38912
	ds_read_b128 v[212:215], v185 offset:39936
	global_load_lds_dwordx4 v154, s[28:29]
	s_mov_b32 m0, s41
	s_nop 0
	global_load_lds_dwordx4 v158, s[28:29]
	s_waitcnt vmcnt(8)
	s_waitcnt lgkmcnt(0)
	s_barrier
	s_setprio 0
	s_waitcnt lgkmcnt(0)
	v_mfma_f32_16x16x32_bf16 v[114:117], v[130:133], v[180:183], v[114:117]
	v_mfma_f32_16x16x32_bf16 v[118:121], v[138:141], v[180:183], v[118:121]
	v_mfma_f32_16x16x32_bf16 v[106:109], v[130:133], v[192:195], v[106:109]
	v_mfma_f32_16x16x32_bf16 v[98:101], v[138:141], v[192:195], v[98:101]
	v_mfma_f32_16x16x32_bf16 v[90:93], v[130:133], v[200:203], v[90:93]
	v_mfma_f32_16x16x32_bf16 v[82:85], v[138:141], v[200:203], v[82:85]
	v_mfma_f32_16x16x32_bf16 v[74:77], v[130:133], v[208:211], v[74:77]
	v_mfma_f32_16x16x32_bf16 v[66:69], v[138:141], v[208:211], v[66:69]
	v_mfma_f32_16x16x32_bf16 v[114:117], v[134:137], v[188:191], v[114:117]
	v_mfma_f32_16x16x32_bf16 v[118:121], v[142:145], v[188:191], v[118:121]
	v_mfma_f32_16x16x32_bf16 v[106:109], v[134:137], v[196:199], v[106:109]
	v_mfma_f32_16x16x32_bf16 v[98:101], v[142:145], v[196:199], v[98:101]
	v_mfma_f32_16x16x32_bf16 v[90:93], v[134:137], v[204:207], v[90:93]
	v_mfma_f32_16x16x32_bf16 v[82:85], v[142:145], v[204:207], v[82:85]
	v_mfma_f32_16x16x32_bf16 v[74:77], v[134:137], v[212:215], v[74:77]
	v_mfma_f32_16x16x32_bf16 v[66:69], v[142:145], v[212:215], v[66:69]
	v_mfma_f32_16x16x32_bf16 v[122:125], v[146:149], v[180:183], v[122:125]
	v_mfma_f32_16x16x32_bf16 v[126:129], v[172:175], v[180:183], v[126:129]
	v_mfma_f32_16x16x32_bf16 v[110:113], v[146:149], v[192:195], v[110:113]
	v_mfma_f32_16x16x32_bf16 v[102:105], v[172:175], v[192:195], v[102:105]
	v_mfma_f32_16x16x32_bf16 v[94:97], v[146:149], v[200:203], v[94:97]
	v_mfma_f32_16x16x32_bf16 v[86:89], v[172:175], v[200:203], v[86:89]
	v_mfma_f32_16x16x32_bf16 v[78:81], v[146:149], v[208:211], v[78:81]
	v_mfma_f32_16x16x32_bf16 v[70:73], v[172:175], v[208:211], v[70:73]
	v_mfma_f32_16x16x32_bf16 v[122:125], v[150:153], v[188:191], v[122:125]
	v_mfma_f32_16x16x32_bf16 v[126:129], v[176:179], v[188:191], v[126:129]
	v_mfma_f32_16x16x32_bf16 v[110:113], v[150:153], v[196:199], v[110:113]
	v_mfma_f32_16x16x32_bf16 v[102:105], v[176:179], v[196:199], v[102:105]
	v_mfma_f32_16x16x32_bf16 v[94:97], v[150:153], v[204:207], v[94:97]
	v_mfma_f32_16x16x32_bf16 v[86:89], v[176:179], v[204:207], v[86:89]
	v_mfma_f32_16x16x32_bf16 v[78:81], v[150:153], v[212:215], v[78:81]
	v_mfma_f32_16x16x32_bf16 v[70:73], v[176:179], v[212:215], v[70:73]
	s_setprio 1
	s_barrier
	s_add_i32 s28, s33, s36
	s_add_i32 m0, s28, 0xffffff80
	ds_read_b128 v[180:183], v185 offset:49152
	ds_read_b128 v[188:191], v185 offset:50176
	ds_read_b128 v[192:195], v185 offset:51200
	ds_read_b128 v[196:199], v185 offset:52224
	ds_read_b128 v[200:203], v185 offset:53248
	ds_read_b128 v[204:207], v185 offset:54272
	ds_read_b128 v[208:211], v185 offset:55296
	ds_read_b128 v[212:215], v185 offset:56320
	global_load_lds_dwordx4 v156, s[24:25] offset:128
	s_add_i32 m0, s28, 0x1f80
	s_add_i32 s28, s42, s36
	global_load_lds_dwordx4 v160, s[24:25] offset:128
	s_add_u32 s24, s24, 0x100080
	s_addc_u32 s25, s25, 0
	s_mov_b32 m0, s28
	s_nop 0
	global_load_lds_dwordx4 v156, s[24:25]
	s_add_i32 m0, s28, 0x2000
	s_nop 0
	global_load_lds_dwordx4 v160, s[24:25]
	s_mov_b32 m0, s44
	s_nop 0
	global_load_lds_dwordx4 v154, s[100:101]
	s_mov_b32 m0, s45
	s_nop 0
	global_load_lds_dwordx4 v158, s[100:101]
	s_waitcnt vmcnt(8)
	s_waitcnt lgkmcnt(0)
	s_barrier
	s_setprio 0
	s_waitcnt lgkmcnt(0)
	v_mfma_f32_16x16x32_bf16 v[58:61], v[130:133], v[180:183], v[58:61]
	v_mfma_f32_16x16x32_bf16 v[54:57], v[138:141], v[180:183], v[54:57]
	v_mfma_f32_16x16x32_bf16 v[42:45], v[130:133], v[192:195], v[42:45]
	v_mfma_f32_16x16x32_bf16 v[34:37], v[138:141], v[192:195], v[34:37]
	v_mfma_f32_16x16x32_bf16 v[26:29], v[130:133], v[200:203], v[26:29]
	v_mfma_f32_16x16x32_bf16 v[18:21], v[138:141], v[200:203], v[18:21]
	v_mfma_f32_16x16x32_bf16 v[6:9], v[130:133], v[208:211], v[6:9]
	v_mfma_f32_16x16x32_bf16 v[2:5], v[138:141], v[208:211], v[2:5]
	v_mfma_f32_16x16x32_bf16 v[58:61], v[134:137], v[188:191], v[58:61]
	v_mfma_f32_16x16x32_bf16 v[54:57], v[142:145], v[188:191], v[54:57]
	v_mfma_f32_16x16x32_bf16 v[42:45], v[134:137], v[196:199], v[42:45]
	v_mfma_f32_16x16x32_bf16 v[34:37], v[142:145], v[196:199], v[34:37]
	v_mfma_f32_16x16x32_bf16 v[26:29], v[134:137], v[204:207], v[26:29]
	v_mfma_f32_16x16x32_bf16 v[18:21], v[142:145], v[204:207], v[18:21]
	v_mfma_f32_16x16x32_bf16 v[6:9], v[134:137], v[212:215], v[6:9]
	v_mfma_f32_16x16x32_bf16 v[2:5], v[142:145], v[212:215], v[2:5]
	v_mfma_f32_16x16x32_bf16 v[62:65], v[146:149], v[180:183], v[62:65]
	v_mfma_f32_16x16x32_bf16 v[50:53], v[172:175], v[180:183], v[50:53]
	v_mfma_f32_16x16x32_bf16 v[46:49], v[146:149], v[192:195], v[46:49]
	v_mfma_f32_16x16x32_bf16 v[38:41], v[172:175], v[192:195], v[38:41]
	v_mfma_f32_16x16x32_bf16 v[30:33], v[146:149], v[200:203], v[30:33]
	v_mfma_f32_16x16x32_bf16 v[22:25], v[172:175], v[200:203], v[22:25]
	v_mfma_f32_16x16x32_bf16 v[10:13], v[146:149], v[208:211], v[10:13]
	v_mfma_f32_16x16x32_bf16 v[14:17], v[172:175], v[208:211], v[14:17]
	v_mfma_f32_16x16x32_bf16 v[62:65], v[150:153], v[188:191], v[62:65]
	v_mfma_f32_16x16x32_bf16 v[50:53], v[176:179], v[188:191], v[50:53]
	v_mfma_f32_16x16x32_bf16 v[46:49], v[150:153], v[196:199], v[46:49]
	v_mfma_f32_16x16x32_bf16 v[38:41], v[176:179], v[196:199], v[38:41]
	v_mfma_f32_16x16x32_bf16 v[30:33], v[150:153], v[204:207], v[30:33]
	v_mfma_f32_16x16x32_bf16 v[22:25], v[176:179], v[204:207], v[22:25]
	v_mfma_f32_16x16x32_bf16 v[10:13], v[150:153], v[212:215], v[10:13]
	v_mfma_f32_16x16x32_bf16 v[14:17], v[176:179], v[212:215], v[14:17]
	s_setprio 1
	s_barrier
	s_add_i32 s62, s62, 2
	s_add_u32 s26, s26, 0x100
	s_addc_u32 s27, s27, 0
	s_add_u32 s52, s52, 0x100
	s_addc_u32 s53, s53, 0
	s_cmp_gt_u32 s62, 61
	s_cbranch_scc0 .LBB0_1595
	s_and_b64 vcc, exec, s[10:11]
	s_cbranch_vccz .LBB0_1598
	s_barrier

; #define PG8_STAGE(bufoff, gbase, voff) do { _Pragma("unroll") for (int _i = 0; _i < 2; ++_i) \
;         __builtin_amdgcn_global_load_lds((const unsigned*)((const char*)(gbase) + (voff)[_i]), (PG8_LAS unsigned*)(lds + (bufoff) + ldsw + _i * 8192), 16, 0, 0); } while (0)
; #define PG8_LDA(dst, b, h) do { _Pragma("unroll") for (int m = 0; m < 4; ++m) _Pragma("unroll") for (int k = 0; k < 2; ++k) dst[m][k] = *(const PG8_LAS bf16x8*)(lds + PG8_SA(b, h) + aoff + m * 2048 + k * 1024); } while (0)
; #define PG8_LDB(dst, b, h) do { _Pragma("unroll") for (int n = 0; n < 2; ++n) _Pragma("unroll") for (int k = 0; k < 2; ++k) dst[n][k] = *(const PG8_LAS bf16x8*)(lds + PG8_SB(b, h) + boff + n * 2048 + k * 1024); } while (0)
; #define PG8_MMA(ai, bj, At, Bt) do { __builtin_amdgcn_s_setprio(1); _Pragma("unroll") for (int m = 0; m < 4; ++m) _Pragma("unroll") for (int n = 0; n < 2; ++n) _Pragma("unroll") for (int k = 0; k < 2; ++k) \
;         acc[ai][bj][m][n] = __builtin_amdgcn_mfma_f32_16x16x32_bf16(Bt[n][k], At[m][k], acc[ai][bj][m][n], 0, 0, 0); __builtin_amdgcn_s_setprio(0); } while (0)
; #define PG8_WAIT_V(n) asm volatile("s_waitcnt vmcnt(" #n ")" ::: "memory")
; #define PG8_WAIT_L(n) asm volatile("s_waitcnt lgkmcnt(" #n ")" ::: "memory")
; template <class Epi, class Sched, bool ALIGN_EPI = false, bool SP2 = false>
; __device__ __forceinline__ void gemm_phase(PG8_LAS unsigned char* lds, const Gemm g, const Sched& S, const Epi& E) {
;     ...
;             const bool last = (t == nt - 2);
;             const char* a1 = cA + (size_t)(t + 1) * kstep;
;             const char* a2 = last ? nA : cA + (size_t)(t + 2) * kstep; const char* b2 = last ? nB : cB + (size_t)(t + 2) * kstep;
;             const char* a3 = a2 + kstep; const char* b3 = b2 + kstep;
;             if (last && has_next) S.a_ready(nxt);
;             if constexpr (SP2) {
;             PG8_LDB(B0, 0, 0); PG8_LDB(B1, 0, 1); PG8_SCHED; PG8_LDA(At, 0, 0); PG8_STAGE(PG8_SA(1, 1), a1 + hstep, voffA);
;             PG8_WAIT_V(8); PG8_WAIT_L(0); PG8_BAR; PG8_MMA(0, 0, At, B0); PG8_MMA(0, 1, At, B1); PG8_BAR; PG8_SCHED;
;             PG8_LDA(At, 0, 1); PG8_STAGE(PG8_SB(0, 0), b2, voffB); PG8_STAGE(PG8_SB(0, 1), b2 + hstep, voffB); PG8_STAGE(PG8_SA(0, 0), a2, voffA);
;             PG8_WAIT_V(8); PG8_WAIT_L(0); PG8_BAR; PG8_MMA(1, 0, At, B0); PG8_MMA(1, 1, At, B1); PG8_BAR; PG8_SCHED;
.LBB0_1681:
	ds_read_b128 v[160:163], v241 offset:0
	ds_read_b128 v[166:169], v241 offset:1024
	ds_read_b128 v[170:173], v241 offset:2048
	ds_read_b128 v[174:177], v241 offset:3072
	ds_read_b128 v[178:181], v241 offset:16384
	ds_read_b128 v[182:185], v241 offset:17408
	ds_read_b128 v[186:189], v241 offset:18432
	ds_read_b128 v[190:193], v241 offset:19456
	s_add_u32 s22, s24, 0xfff00080
	s_addc_u32 s23, s25, -1
	s_cmp_eq_u32 s52, 60
	s_cselect_b32 s27, s15, s23
	s_cselect_b32 s26, s48, s22
	s_cselect_b32 s23, s13, s51
	s_cselect_b32 s22, s49, s50
	s_add_i32 m0, s21, 0xc000
	ds_read_b128 v[194:197], v155
	ds_read_b128 v[198:201], v155 offset:1024
	ds_read_b128 v[202:205], v155 offset:2048
	ds_read_b128 v[206:209], v155 offset:3072
	ds_read_b128 v[210:213], v155 offset:4096
	ds_read_b128 v[214:217], v155 offset:5120
	ds_read_b128 v[218:221], v155 offset:6144
	ds_read_b128 v[222:225], v155 offset:7168
	global_load_lds_dwordx4 v138, s[24:25]
	s_add_i32 m0, s21, 0xe000
	s_nop 0
	global_load_lds_dwordx4 v140, s[24:25]
	s_waitcnt vmcnt(8)
	s_waitcnt lgkmcnt(0)
	s_barrier
	s_setprio 0
	s_waitcnt lgkmcnt(0)
	v_mfma_f32_16x16x32_bf16 v[122:125], v[160:163], v[194:197], v[122:125]
	v_mfma_f32_16x16x32_bf16 v[114:117], v[170:173], v[194:197], v[114:117]
	v_mfma_f32_16x16x32_bf16 v[106:109], v[160:163], v[202:205], v[106:109]
	v_mfma_f32_16x16x32_bf16 v[98:101], v[170:173], v[202:205], v[98:101]
	v_mfma_f32_16x16x32_bf16 v[90:93], v[160:163], v[210:213], v[90:93]
	v_mfma_f32_16x16x32_bf16 v[82:85], v[170:173], v[210:213], v[82:85]
	v_mfma_f32_16x16x32_bf16 v[74:77], v[160:163], v[218:221], v[74:77]
	v_mfma_f32_16x16x32_bf16 v[62:65], v[170:173], v[218:221], v[62:65]
	v_mfma_f32_16x16x32_bf16 v[122:125], v[166:169], v[198:201], v[122:125]
	v_mfma_f32_16x16x32_bf16 v[114:117], v[174:177], v[198:201], v[114:117]
	v_mfma_f32_16x16x32_bf16 v[106:109], v[166:169], v[206:209], v[106:109]
	v_mfma_f32_16x16x32_bf16 v[98:101], v[174:177], v[206:209], v[98:101]
	v_mfma_f32_16x16x32_bf16 v[90:93], v[166:169], v[214:217], v[90:93]
	v_mfma_f32_16x16x32_bf16 v[82:85], v[174:177], v[214:217], v[82:85]
	v_mfma_f32_16x16x32_bf16 v[74:77], v[166:169], v[222:225], v[74:77]
	v_mfma_f32_16x16x32_bf16 v[62:65], v[174:177], v[222:225], v[62:65]
	v_mfma_f32_16x16x32_bf16 v[126:129], v[178:181], v[194:197], v[126:129]
	v_mfma_f32_16x16x32_bf16 v[118:121], v[186:189], v[194:197], v[118:121]
	v_mfma_f32_16x16x32_bf16 v[110:113], v[178:181], v[202:205], v[110:113]
	v_mfma_f32_16x16x32_bf16 v[102:105], v[186:189], v[202:205], v[102:105]
	v_mfma_f32_16x16x32_bf16 v[94:97], v[178:181], v[210:213], v[94:97]
	v_mfma_f32_16x16x32_bf16 v[86:89], v[186:189], v[210:213], v[86:89]
	v_mfma_f32_16x16x32_bf16 v[78:81], v[178:181], v[218:221], v[78:81]
	v_mfma_f32_16x16x32_bf16 v[70:73], v[186:189], v[218:221], v[70:73]
	v_mfma_f32_16x16x32_bf16 v[126:129], v[182:185], v[198:201], v[126:129]
	v_mfma_f32_16x16x32_bf16 v[118:121], v[190:193], v[198:201], v[118:121]
	v_mfma_f32_16x16x32_bf16 v[110:113], v[182:185], v[206:209], v[110:113]
	v_mfma_f32_16x16x32_bf16 v[102:105], v[190:193], v[206:209], v[102:105]
	v_mfma_f32_16x16x32_bf16 v[94:97], v[182:185], v[214:217], v[94:97]
	v_mfma_f32_16x16x32_bf16 v[86:89], v[190:193], v[214:217], v[86:89]
	v_mfma_f32_16x16x32_bf16 v[78:81], v[182:185], v[222:225], v[78:81]
	v_mfma_f32_16x16x32_bf16 v[70:73], v[190:193], v[222:225], v[70:73]
	s_setprio 1
	s_barrier
	s_add_i32 s33, s44, s29
	s_mov_b32 m0, s33
	ds_read_b128 v[194:197], v155 offset:16384
	ds_read_b128 v[198:201], v155 offset:17408
	ds_read_b128 v[202:205], v155 offset:18432
	ds_read_b128 v[206:209], v155 offset:19456
	ds_read_b128 v[210:213], v155 offset:20480
	ds_read_b128 v[214:217], v155 offset:21504
	ds_read_b128 v[218:221], v155 offset:22528
	ds_read_b128 v[222:225], v155 offset:23552
	global_load_lds_dwordx4 v132, s[22:23]
	s_add_i32 m0, s33, 0x2000
	s_add_u32 s62, s22, 0x100000
	s_addc_u32 s63, s23, 0
	s_add_i32 s33, s45, s29
	global_load_lds_dwordx4 v136, s[22:23]
	s_mov_b32 m0, s33
	s_add_u32 s100, s26, 0x80
	s_addc_u32 s101, s27, 0
	global_load_lds_dwordx4 v132, s[62:63]
	s_add_i32 m0, s33, 0x2000
	s_nop 0
	global_load_lds_dwordx4 v136, s[62:63]
	s_mov_b32 m0, s21
	s_nop 0
	global_load_lds_dwordx4 v130, s[26:27]
	s_mov_b32 m0, s34
	s_nop 0
	global_load_lds_dwordx4 v134, s[26:27]
	s_waitcnt vmcnt(8)
	s_waitcnt lgkmcnt(0)
	s_barrier
	s_setprio 0
	s_waitcnt lgkmcnt(0)
	v_mfma_f32_16x16x32_bf16 v[58:61], v[160:163], v[194:197], v[58:61]
	v_mfma_f32_16x16x32_bf16 v[50:53], v[170:173], v[194:197], v[50:53]
	v_mfma_f32_16x16x32_bf16 v[42:45], v[160:163], v[202:205], v[42:45]
	v_mfma_f32_16x16x32_bf16 v[34:37], v[170:173], v[202:205], v[34:37]
	v_mfma_f32_16x16x32_bf16 v[26:29], v[160:163], v[210:213], v[26:29]
	v_mfma_f32_16x16x32_bf16 v[18:21], v[170:173], v[210:213], v[18:21]
	v_mfma_f32_16x16x32_bf16 v[10:13], v[160:163], v[218:221], v[10:13]
	v_mfma_f32_16x16x32_bf16 v[2:5], v[170:173], v[218:221], v[2:5]
	v_mfma_f32_16x16x32_bf16 v[58:61], v[166:169], v[198:201], v[58:61]
	v_mfma_f32_16x16x32_bf16 v[50:53], v[174:177], v[198:201], v[50:53]
	v_mfma_f32_16x16x32_bf16 v[42:45], v[166:169], v[206:209], v[42:45]
	v_mfma_f32_16x16x32_bf16 v[34:37], v[174:177], v[206:209], v[34:37]
	v_mfma_f32_16x16x32_bf16 v[26:29], v[166:169], v[214:217], v[26:29]
	v_mfma_f32_16x16x32_bf16 v[18:21], v[174:177], v[214:217], v[18:21]
	v_mfma_f32_16x16x32_bf16 v[10:13], v[166:169], v[222:225], v[10:13]
	v_mfma_f32_16x16x32_bf16 v[2:5], v[174:177], v[222:225], v[2:5]
	v_mfma_f32_16x16x32_bf16 v[66:69], v[178:181], v[194:197], v[66:69]
	v_mfma_f32_16x16x32_bf16 v[54:57], v[186:189], v[194:197], v[54:57]
	v_mfma_f32_16x16x32_bf16 v[46:49], v[178:181], v[202:205], v[46:49]
	v_mfma_f32_16x16x32_bf16 v[38:41], v[186:189], v[202:205], v[38:41]
	v_mfma_f32_16x16x32_bf16 v[30:33], v[178:181], v[210:213], v[30:33]
	v_mfma_f32_16x16x32_bf16 v[22:25], v[186:189], v[210:213], v[22:25]
	v_mfma_f32_16x16x32_bf16 v[14:17], v[178:181], v[218:221], v[14:17]
	v_mfma_f32_16x16x32_bf16 v[6:9], v[186:189], v[218:221], v[6:9]
	v_mfma_f32_16x16x32_bf16 v[66:69], v[182:185], v[198:201], v[66:69]
	v_mfma_f32_16x16x32_bf16 v[54:57], v[190:193], v[198:201], v[54:57]
	v_mfma_f32_16x16x32_bf16 v[46:49], v[182:185], v[206:209], v[46:49]
	v_mfma_f32_16x16x32_bf16 v[38:41], v[190:193], v[206:209], v[38:41]
	v_mfma_f32_16x16x32_bf16 v[30:33], v[182:185], v[214:217], v[30:33]
	v_mfma_f32_16x16x32_bf16 v[22:25], v[190:193], v[214:217], v[22:25]
	v_mfma_f32_16x16x32_bf16 v[14:17], v[182:185], v[222:225], v[14:17]
	v_mfma_f32_16x16x32_bf16 v[6:9], v[190:193], v[222:225], v[6:9]
	s_setprio 1
	s_barrier
; #define PG8_STAGE(bufoff, gbase, voff) do { _Pragma("unroll") for (int _i = 0; _i < 2; ++_i) \
;         __builtin_amdgcn_global_load_lds((const unsigned*)((const char*)(gbase) + (voff)[_i]), (PG8_LAS unsigned*)(lds + (bufoff) + ldsw + _i * 8192), 16, 0, 0); } while (0)
; #define PG8_LDA(dst, b, h) do { _Pragma("unroll") for (int m = 0; m < 4; ++m) _Pragma("unroll") for (int k = 0; k < 2; ++k) dst[m][k] = *(const PG8_LAS bf16x8*)(lds + PG8_SA(b, h) + aoff + m * 2048 + k * 1024); } while (0)
; #define PG8_LDB(dst, b, h) do { _Pragma("unroll") for (int n = 0; n < 2; ++n) _Pragma("unroll") for (int k = 0; k < 2; ++k) dst[n][k] = *(const PG8_LAS bf16x8*)(lds + PG8_SB(b, h) + boff + n * 2048 + k * 1024); } while (0)
; #define PG8_MMA(ai, bj, At, Bt) do { __builtin_amdgcn_s_setprio(1); _Pragma("unroll") for (int m = 0; m < 4; ++m) _Pragma("unroll") for (int n = 0; n < 2; ++n) _Pragma("unroll") for (int k = 0; k < 2; ++k) \
;         acc[ai][bj][m][n] = __builtin_amdgcn_mfma_f32_16x16x32_bf16(Bt[n][k], At[m][k], acc[ai][bj][m][n], 0, 0, 0); __builtin_amdgcn_s_setprio(0); } while (0)
; #define PG8_WAIT_V(n) asm volatile("s_waitcnt vmcnt(" #n ")" ::: "memory")
; #define PG8_WAIT_L(n) asm volatile("s_waitcnt lgkmcnt(" #n ")" ::: "memory")
; #define PG8_BAR __builtin_amdgcn_s_barrier()
; #define PG8_SCHED __builtin_amdgcn_sched_barrier(0)
; template <class Epi, class Sched, bool ALIGN_EPI = false, bool SP2 = false>
; __device__ __forceinline__ void gemm_phase(PG8_LAS unsigned char* lds, const Gemm g, const Sched& S, const Epi& E) {
;     ...
;             PG8_LDB(B0, 1, 0); PG8_LDB(B1, 1, 1); PG8_SCHED; PG8_LDA(At, 1, 0); PG8_STAGE(PG8_SA(0, 1), a2 + hstep, voffA);
;             PG8_WAIT_V(8); PG8_WAIT_L(0); PG8_BAR; PG8_MMA(0, 0, At, B0); PG8_MMA(0, 1, At, B1); PG8_BAR; PG8_SCHED;
;             PG8_LDA(At, 1, 1); PG8_STAGE(PG8_SB(1, 0), b3, voffB); PG8_STAGE(PG8_SB(1, 1), b3 + hstep, voffB); PG8_STAGE(PG8_SA(1, 0), a3, voffA);
;             PG8_WAIT_V(8); PG8_WAIT_L(0); PG8_BAR; PG8_MMA(1, 0, At, B0); PG8_MMA(1, 1, At, B1); PG8_BAR; PG8_SCHED;
	s_add_i32 s33, 0, 0x18000
	s_add_i32 s42, 0, 0x1c000
	ds_read_b128 v[160:163], v241 offset:32768
	ds_read_b128 v[166:169], v241 offset:33792
	ds_read_b128 v[170:173], v241 offset:34816
	ds_read_b128 v[174:177], v241 offset:35840
	ds_read_b128 v[178:181], v241 offset:49152
	ds_read_b128 v[182:185], v241 offset:50176
	ds_read_b128 v[186:189], v241 offset:51200
	ds_read_b128 v[190:193], v241 offset:52224
	s_add_u32 s26, s26, 0x100000
	s_addc_u32 s27, s27, 0
	s_mov_b32 m0, s35
	ds_read_b128 v[194:197], v155 offset:32768
	ds_read_b128 v[198:201], v155 offset:33792
	ds_read_b128 v[202:205], v155 offset:34816
	ds_read_b128 v[206:209], v155 offset:35840
	ds_read_b128 v[210:213], v155 offset:36864
	ds_read_b128 v[214:217], v155 offset:37888
	ds_read_b128 v[218:221], v155 offset:38912
	ds_read_b128 v[222:225], v155 offset:39936
	global_load_lds_dwordx4 v130, s[26:27]
	s_mov_b32 m0, s36
	s_nop 0
	global_load_lds_dwordx4 v134, s[26:27]
	s_waitcnt vmcnt(8)
	s_waitcnt lgkmcnt(0)
	s_barrier
	s_setprio 0
	s_waitcnt lgkmcnt(0)
	v_mfma_f32_16x16x32_bf16 v[122:125], v[160:163], v[194:197], v[122:125]
	v_mfma_f32_16x16x32_bf16 v[114:117], v[170:173], v[194:197], v[114:117]
	v_mfma_f32_16x16x32_bf16 v[106:109], v[160:163], v[202:205], v[106:109]
	v_mfma_f32_16x16x32_bf16 v[98:101], v[170:173], v[202:205], v[98:101]
	v_mfma_f32_16x16x32_bf16 v[90:93], v[160:163], v[210:213], v[90:93]
	v_mfma_f32_16x16x32_bf16 v[82:85], v[170:173], v[210:213], v[82:85]
	v_mfma_f32_16x16x32_bf16 v[74:77], v[160:163], v[218:221], v[74:77]
	v_mfma_f32_16x16x32_bf16 v[62:65], v[170:173], v[218:221], v[62:65]
	v_mfma_f32_16x16x32_bf16 v[122:125], v[166:169], v[198:201], v[122:125]
	v_mfma_f32_16x16x32_bf16 v[114:117], v[174:177], v[198:201], v[114:117]
	v_mfma_f32_16x16x32_bf16 v[106:109], v[166:169], v[206:209], v[106:109]
	v_mfma_f32_16x16x32_bf16 v[98:101], v[174:177], v[206:209], v[98:101]
	v_mfma_f32_16x16x32_bf16 v[90:93], v[166:169], v[214:217], v[90:93]
	v_mfma_f32_16x16x32_bf16 v[82:85], v[174:177], v[214:217], v[82:85]
	v_mfma_f32_16x16x32_bf16 v[74:77], v[166:169], v[222:225], v[74:77]
	v_mfma_f32_16x16x32_bf16 v[62:65], v[174:177], v[222:225], v[62:65]
	v_mfma_f32_16x16x32_bf16 v[126:129], v[178:181], v[194:197], v[126:129]
	v_mfma_f32_16x16x32_bf16 v[118:121], v[186:189], v[194:197], v[118:121]
	v_mfma_f32_16x16x32_bf16 v[110:113], v[178:181], v[202:205], v[110:113]
	v_mfma_f32_16x16x32_bf16 v[102:105], v[186:189], v[202:205], v[102:105]
	v_mfma_f32_16x16x32_bf16 v[94:97], v[178:181], v[210:213], v[94:97]
	v_mfma_f32_16x16x32_bf16 v[86:89], v[186:189], v[210:213], v[86:89]
	v_mfma_f32_16x16x32_bf16 v[78:81], v[178:181], v[218:221], v[78:81]
	v_mfma_f32_16x16x32_bf16 v[70:73], v[186:189], v[218:221], v[70:73]
	v_mfma_f32_16x16x32_bf16 v[126:129], v[182:185], v[198:201], v[126:129]
	v_mfma_f32_16x16x32_bf16 v[118:121], v[190:193], v[198:201], v[118:121]
	v_mfma_f32_16x16x32_bf16 v[110:113], v[182:185], v[206:209], v[110:113]
	v_mfma_f32_16x16x32_bf16 v[102:105], v[190:193], v[206:209], v[102:105]
	v_mfma_f32_16x16x32_bf16 v[94:97], v[182:185], v[214:217], v[94:97]
	v_mfma_f32_16x16x32_bf16 v[86:89], v[190:193], v[214:217], v[86:89]
	v_mfma_f32_16x16x32_bf16 v[78:81], v[182:185], v[222:225], v[78:81]
	v_mfma_f32_16x16x32_bf16 v[70:73], v[190:193], v[222:225], v[70:73]
	s_setprio 1
	s_barrier
	s_add_i32 s26, s33, s29
	s_add_i32 m0, s26, 0xffffff80
	ds_read_b128 v[194:197], v155 offset:49152
	ds_read_b128 v[198:201], v155 offset:50176
	ds_read_b128 v[202:205], v155 offset:51200
	ds_read_b128 v[206:209], v155 offset:52224
	ds_read_b128 v[210:213], v155 offset:53248
	ds_read_b128 v[214:217], v155 offset:54272
	ds_read_b128 v[218:221], v155 offset:55296
	ds_read_b128 v[222:225], v155 offset:56320
	global_load_lds_dwordx4 v132, s[22:23] offset:128
	s_add_i32 m0, s26, 0x1f80
	s_add_i32 s26, s42, s29
	global_load_lds_dwordx4 v136, s[22:23] offset:128
	s_add_u32 s22, s22, 0x100080
	s_addc_u32 s23, s23, 0
	s_mov_b32 m0, s26
	s_nop 0
	global_load_lds_dwordx4 v132, s[22:23]
	s_add_i32 m0, s26, 0x2000
	s_nop 0
	global_load_lds_dwordx4 v136, s[22:23]
	s_mov_b32 m0, s41
	s_nop 0
	global_load_lds_dwordx4 v130, s[100:101]
	s_mov_b32 m0, s43
	s_nop 0
	global_load_lds_dwordx4 v134, s[100:101]
	s_waitcnt vmcnt(8)
	s_waitcnt lgkmcnt(0)
	s_barrier
	s_setprio 0
	s_waitcnt lgkmcnt(0)
	v_mfma_f32_16x16x32_bf16 v[58:61], v[160:163], v[194:197], v[58:61]
	v_mfma_f32_16x16x32_bf16 v[50:53], v[170:173], v[194:197], v[50:53]
	v_mfma_f32_16x16x32_bf16 v[42:45], v[160:163], v[202:205], v[42:45]
	v_mfma_f32_16x16x32_bf16 v[34:37], v[170:173], v[202:205], v[34:37]
	v_mfma_f32_16x16x32_bf16 v[26:29], v[160:163], v[210:213], v[26:29]
	v_mfma_f32_16x16x32_bf16 v[18:21], v[170:173], v[210:213], v[18:21]
	v_mfma_f32_16x16x32_bf16 v[10:13], v[160:163], v[218:221], v[10:13]
	v_mfma_f32_16x16x32_bf16 v[2:5], v[170:173], v[218:221], v[2:5]
	v_mfma_f32_16x16x32_bf16 v[58:61], v[166:169], v[198:201], v[58:61]
	v_mfma_f32_16x16x32_bf16 v[50:53], v[174:177], v[198:201], v[50:53]
	v_mfma_f32_16x16x32_bf16 v[42:45], v[166:169], v[206:209], v[42:45]
	v_mfma_f32_16x16x32_bf16 v[34:37], v[174:177], v[206:209], v[34:37]
	v_mfma_f32_16x16x32_bf16 v[26:29], v[166:169], v[214:217], v[26:29]
	v_mfma_f32_16x16x32_bf16 v[18:21], v[174:177], v[214:217], v[18:21]
	v_mfma_f32_16x16x32_bf16 v[10:13], v[166:169], v[222:225], v[10:13]
	v_mfma_f32_16x16x32_bf16 v[2:5], v[174:177], v[222:225], v[2:5]
	v_mfma_f32_16x16x32_bf16 v[66:69], v[178:181], v[194:197], v[66:69]
	v_mfma_f32_16x16x32_bf16 v[54:57], v[186:189], v[194:197], v[54:57]
	v_mfma_f32_16x16x32_bf16 v[46:49], v[178:181], v[202:205], v[46:49]
	v_mfma_f32_16x16x32_bf16 v[38:41], v[186:189], v[202:205], v[38:41]
	v_mfma_f32_16x16x32_bf16 v[30:33], v[178:181], v[210:213], v[30:33]
	v_mfma_f32_16x16x32_bf16 v[22:25], v[186:189], v[210:213], v[22:25]
	v_mfma_f32_16x16x32_bf16 v[14:17], v[178:181], v[218:221], v[14:17]
	v_mfma_f32_16x16x32_bf16 v[6:9], v[186:189], v[218:221], v[6:9]
	v_mfma_f32_16x16x32_bf16 v[66:69], v[182:185], v[198:201], v[66:69]
	v_mfma_f32_16x16x32_bf16 v[54:57], v[190:193], v[198:201], v[54:57]
	v_mfma_f32_16x16x32_bf16 v[46:49], v[182:185], v[206:209], v[46:49]
	v_mfma_f32_16x16x32_bf16 v[38:41], v[190:193], v[206:209], v[38:41]
	v_mfma_f32_16x16x32_bf16 v[30:33], v[182:185], v[214:217], v[30:33]
	v_mfma_f32_16x16x32_bf16 v[22:25], v[190:193], v[214:217], v[22:25]
	v_mfma_f32_16x16x32_bf16 v[14:17], v[182:185], v[222:225], v[14:17]
	v_mfma_f32_16x16x32_bf16 v[6:9], v[190:193], v[222:225], v[6:9]
	s_setprio 1
	s_barrier
	s_add_i32 s52, s52, 2
	s_add_u32 s24, s24, 0x100
	s_addc_u32 s25, s25, 0
	s_add_u32 s50, s50, 0x100
	s_addc_u32 s51, s51, 0
	s_cmp_gt_u32 s52, 61
	s_cbranch_scc0 .LBB0_1681
	s_and_b64 vcc, exec, s[8:9]
	s_cbranch_vccz .LBB0_1684
	s_barrier

; #define PG8_STAGE(bufoff, gbase, voff) do { _Pragma("unroll") for (int _i = 0; _i < 2; ++_i) \
;         __builtin_amdgcn_global_load_lds((const unsigned*)((const char*)(gbase) + (voff)[_i]), (PG8_LAS unsigned*)(lds + (bufoff) + ldsw + _i * 8192), 16, 0, 0); } while (0)
; #define PG8_LDA(dst, b, h) do { _Pragma("unroll") for (int m = 0; m < 4; ++m) _Pragma("unroll") for (int k = 0; k < 2; ++k) dst[m][k] = *(const PG8_LAS bf16x8*)(lds + PG8_SA(b, h) + aoff + m * 2048 + k * 1024); } while (0)
; #define PG8_LDB(dst, b, h) do { _Pragma("unroll") for (int n = 0; n < 2; ++n) _Pragma("unroll") for (int k = 0; k < 2; ++k) dst[n][k] = *(const PG8_LAS bf16x8*)(lds + PG8_SB(b, h) + boff + n * 2048 + k * 1024); } while (0)
; #define PG8_MMA(ai, bj, At, Bt) do { __builtin_amdgcn_s_setprio(1); _Pragma("unroll") for (int m = 0; m < 4; ++m) _Pragma("unroll") for (int n = 0; n < 2; ++n) _Pragma("unroll") for (int k = 0; k < 2; ++k) \
;         acc[ai][bj][m][n] = __builtin_amdgcn_mfma_f32_16x16x32_bf16(Bt[n][k], At[m][k], acc[ai][bj][m][n], 0, 0, 0); __builtin_amdgcn_s_setprio(0); } while (0)
; #define PG8_WAIT_V(n) asm volatile("s_waitcnt vmcnt(" #n ")" ::: "memory")
; #define PG8_WAIT_L(n) asm volatile("s_waitcnt lgkmcnt(" #n ")" ::: "memory")
; template <class Epi, class Sched, bool ALIGN_EPI = false, bool SP2 = false>
; __device__ __forceinline__ void gemm_phase(PG8_LAS unsigned char* lds, const Gemm g, const Sched& S, const Epi& E) {
;     ...
;             const bool last = (t == nt - 2);
;             const char* a1 = cA + (size_t)(t + 1) * kstep;
;             const char* a2 = last ? nA : cA + (size_t)(t + 2) * kstep; const char* b2 = last ? nB : cB + (size_t)(t + 2) * kstep;
;             const char* a3 = a2 + kstep; const char* b3 = b2 + kstep;
;             if (last && has_next) S.a_ready(nxt);
;             if constexpr (SP2) {
;             PG8_LDB(B0, 0, 0); PG8_LDB(B1, 0, 1); PG8_SCHED; PG8_LDA(At, 0, 0); PG8_STAGE(PG8_SA(1, 1), a1 + hstep, voffA);
;             PG8_WAIT_V(8); PG8_WAIT_L(0); PG8_BAR; PG8_MMA(0, 0, At, B0); PG8_MMA(0, 1, At, B1); PG8_BAR; PG8_SCHED;
;             PG8_LDA(At, 0, 1); PG8_STAGE(PG8_SB(0, 0), b2, voffB); PG8_STAGE(PG8_SB(0, 1), b2 + hstep, voffB); PG8_STAGE(PG8_SA(0, 0), a2, voffA);
;             PG8_WAIT_V(8); PG8_WAIT_L(0); PG8_BAR; PG8_MMA(1, 0, At, B0); PG8_MMA(1, 1, At, B1); PG8_BAR; PG8_SCHED;
.LBB0_1801:
	ds_read_b128 v[130:133], v241 offset:0
	ds_read_b128 v[134:137], v241 offset:1024
	ds_read_b128 v[138:141], v241 offset:2048
	ds_read_b128 v[142:145], v241 offset:3072
	ds_read_b128 v[146:149], v241 offset:16384
	ds_read_b128 v[150:153], v241 offset:17408
	ds_read_b128 v[170:173], v241 offset:18432
	ds_read_b128 v[174:177], v241 offset:19456
	s_add_u32 s16, s18, 0xffd50080
	s_addc_u32 s17, s19, -1
	s_cmpk_eq_i32 s48, 0xa8
	s_cselect_b32 s21, s5, s17
	s_cselect_b32 s20, s4, s16
	s_cselect_b32 s17, s15, s47
	s_cselect_b32 s16, s14, s46
	s_add_i32 m0, s25, 0xc000
	ds_read_b128 v[178:181], v184
	ds_read_b128 v[186:189], v184 offset:1024
	ds_read_b128 v[190:193], v184 offset:2048
	ds_read_b128 v[194:197], v184 offset:3072
	ds_read_b128 v[198:201], v184 offset:4096
	ds_read_b128 v[202:205], v184 offset:5120
	ds_read_b128 v[206:209], v184 offset:6144
	ds_read_b128 v[210:213], v184 offset:7168
	global_load_lds_dwordx4 v0, s[18:19]
	s_add_i32 m0, s25, 0xe000
	s_nop 0
	global_load_lds_dwordx4 v162, s[18:19]
	s_waitcnt vmcnt(8)
	s_waitcnt lgkmcnt(0)
	s_barrier
	s_setprio 0
	s_waitcnt lgkmcnt(0)
	v_mfma_f32_16x16x32_bf16 v[114:117], v[130:133], v[178:181], v[114:117]
	v_mfma_f32_16x16x32_bf16 v[118:121], v[138:141], v[178:181], v[118:121]
	v_mfma_f32_16x16x32_bf16 v[106:109], v[130:133], v[190:193], v[106:109]
	v_mfma_f32_16x16x32_bf16 v[98:101], v[138:141], v[190:193], v[98:101]
	v_mfma_f32_16x16x32_bf16 v[90:93], v[130:133], v[198:201], v[90:93]
	v_mfma_f32_16x16x32_bf16 v[82:85], v[138:141], v[198:201], v[82:85]
	v_mfma_f32_16x16x32_bf16 v[74:77], v[130:133], v[206:209], v[74:77]
	v_mfma_f32_16x16x32_bf16 v[66:69], v[138:141], v[206:209], v[66:69]
	v_mfma_f32_16x16x32_bf16 v[114:117], v[134:137], v[186:189], v[114:117]
	v_mfma_f32_16x16x32_bf16 v[118:121], v[142:145], v[186:189], v[118:121]
	v_mfma_f32_16x16x32_bf16 v[106:109], v[134:137], v[194:197], v[106:109]
	v_mfma_f32_16x16x32_bf16 v[98:101], v[142:145], v[194:197], v[98:101]
	v_mfma_f32_16x16x32_bf16 v[90:93], v[134:137], v[202:205], v[90:93]
	v_mfma_f32_16x16x32_bf16 v[82:85], v[142:145], v[202:205], v[82:85]
	v_mfma_f32_16x16x32_bf16 v[74:77], v[134:137], v[210:213], v[74:77]
	v_mfma_f32_16x16x32_bf16 v[66:69], v[142:145], v[210:213], v[66:69]
	v_mfma_f32_16x16x32_bf16 v[122:125], v[146:149], v[178:181], v[122:125]
	v_mfma_f32_16x16x32_bf16 v[126:129], v[170:173], v[178:181], v[126:129]
	v_mfma_f32_16x16x32_bf16 v[110:113], v[146:149], v[190:193], v[110:113]
	v_mfma_f32_16x16x32_bf16 v[102:105], v[170:173], v[190:193], v[102:105]
	v_mfma_f32_16x16x32_bf16 v[94:97], v[146:149], v[198:201], v[94:97]
	v_mfma_f32_16x16x32_bf16 v[86:89], v[170:173], v[198:201], v[86:89]
	v_mfma_f32_16x16x32_bf16 v[78:81], v[146:149], v[206:209], v[78:81]
	v_mfma_f32_16x16x32_bf16 v[70:73], v[170:173], v[206:209], v[70:73]
	v_mfma_f32_16x16x32_bf16 v[122:125], v[150:153], v[186:189], v[122:125]
	v_mfma_f32_16x16x32_bf16 v[126:129], v[174:177], v[186:189], v[126:129]
	v_mfma_f32_16x16x32_bf16 v[110:113], v[150:153], v[194:197], v[110:113]
	v_mfma_f32_16x16x32_bf16 v[102:105], v[174:177], v[194:197], v[102:105]
	v_mfma_f32_16x16x32_bf16 v[94:97], v[150:153], v[202:205], v[94:97]
	v_mfma_f32_16x16x32_bf16 v[86:89], v[174:177], v[202:205], v[86:89]
	v_mfma_f32_16x16x32_bf16 v[78:81], v[150:153], v[210:213], v[78:81]
	v_mfma_f32_16x16x32_bf16 v[70:73], v[174:177], v[210:213], v[70:73]
	s_setprio 1
	s_barrier
	s_add_i32 s33, s36, s24
	s_mov_b32 m0, s33
	ds_read_b128 v[178:181], v184 offset:16384
	ds_read_b128 v[186:189], v184 offset:17408
	ds_read_b128 v[190:193], v184 offset:18432
	ds_read_b128 v[194:197], v184 offset:19456
	ds_read_b128 v[198:201], v184 offset:20480
	ds_read_b128 v[202:205], v184 offset:21504
	ds_read_b128 v[206:209], v184 offset:22528
	ds_read_b128 v[210:213], v184 offset:23552
	global_load_lds_dwordx4 v156, s[16:17]
	s_add_i32 m0, s33, 0x2000
	s_add_u32 s50, s16, 0x2b0000
	s_addc_u32 s51, s17, 0
	s_add_i32 s33, s37, s24
	global_load_lds_dwordx4 v160, s[16:17]
	s_mov_b32 m0, s33
	s_add_u32 s100, s20, 0x80
	s_addc_u32 s101, s21, 0
	global_load_lds_dwordx4 v156, s[50:51]
	s_add_i32 m0, s33, 0x2000
	s_nop 0
	global_load_lds_dwordx4 v160, s[50:51]
	s_mov_b32 m0, s25
	s_nop 0
	global_load_lds_dwordx4 v154, s[20:21]
	s_mov_b32 m0, s26
	s_nop 0
	global_load_lds_dwordx4 v158, s[20:21]
	s_waitcnt vmcnt(8)
	s_waitcnt lgkmcnt(0)
	s_barrier
	s_setprio 0
	s_waitcnt lgkmcnt(0)
	v_mfma_f32_16x16x32_bf16 v[58:61], v[130:133], v[178:181], v[58:61]
	v_mfma_f32_16x16x32_bf16 v[54:57], v[138:141], v[178:181], v[54:57]
	v_mfma_f32_16x16x32_bf16 v[42:45], v[130:133], v[190:193], v[42:45]
	v_mfma_f32_16x16x32_bf16 v[34:37], v[138:141], v[190:193], v[34:37]
	v_mfma_f32_16x16x32_bf16 v[26:29], v[130:133], v[198:201], v[26:29]
	v_mfma_f32_16x16x32_bf16 v[18:21], v[138:141], v[198:201], v[18:21]
	v_mfma_f32_16x16x32_bf16 v[6:9], v[130:133], v[206:209], v[6:9]
	v_mfma_f32_16x16x32_bf16 v[2:5], v[138:141], v[206:209], v[2:5]
	v_mfma_f32_16x16x32_bf16 v[58:61], v[134:137], v[186:189], v[58:61]
	v_mfma_f32_16x16x32_bf16 v[54:57], v[142:145], v[186:189], v[54:57]
	v_mfma_f32_16x16x32_bf16 v[42:45], v[134:137], v[194:197], v[42:45]
	v_mfma_f32_16x16x32_bf16 v[34:37], v[142:145], v[194:197], v[34:37]
	v_mfma_f32_16x16x32_bf16 v[26:29], v[134:137], v[202:205], v[26:29]
	v_mfma_f32_16x16x32_bf16 v[18:21], v[142:145], v[202:205], v[18:21]
	v_mfma_f32_16x16x32_bf16 v[6:9], v[134:137], v[210:213], v[6:9]
	v_mfma_f32_16x16x32_bf16 v[2:5], v[142:145], v[210:213], v[2:5]
	v_mfma_f32_16x16x32_bf16 v[62:65], v[146:149], v[178:181], v[62:65]
	v_mfma_f32_16x16x32_bf16 v[50:53], v[170:173], v[178:181], v[50:53]
	v_mfma_f32_16x16x32_bf16 v[46:49], v[146:149], v[190:193], v[46:49]
	v_mfma_f32_16x16x32_bf16 v[38:41], v[170:173], v[190:193], v[38:41]
	v_mfma_f32_16x16x32_bf16 v[30:33], v[146:149], v[198:201], v[30:33]
	v_mfma_f32_16x16x32_bf16 v[22:25], v[170:173], v[198:201], v[22:25]
	v_mfma_f32_16x16x32_bf16 v[10:13], v[146:149], v[206:209], v[10:13]
	v_mfma_f32_16x16x32_bf16 v[14:17], v[170:173], v[206:209], v[14:17]
	v_mfma_f32_16x16x32_bf16 v[62:65], v[150:153], v[186:189], v[62:65]
	v_mfma_f32_16x16x32_bf16 v[50:53], v[174:177], v[186:189], v[50:53]
	v_mfma_f32_16x16x32_bf16 v[46:49], v[150:153], v[194:197], v[46:49]
	v_mfma_f32_16x16x32_bf16 v[38:41], v[174:177], v[194:197], v[38:41]
	v_mfma_f32_16x16x32_bf16 v[30:33], v[150:153], v[202:205], v[30:33]
	v_mfma_f32_16x16x32_bf16 v[22:25], v[174:177], v[202:205], v[22:25]
	v_mfma_f32_16x16x32_bf16 v[10:13], v[150:153], v[210:213], v[10:13]
	v_mfma_f32_16x16x32_bf16 v[14:17], v[174:177], v[210:213], v[14:17]
	s_setprio 1
	s_barrier
; #define PG8_STAGE(bufoff, gbase, voff) do { _Pragma("unroll") for (int _i = 0; _i < 2; ++_i) \
;         __builtin_amdgcn_global_load_lds((const unsigned*)((const char*)(gbase) + (voff)[_i]), (PG8_LAS unsigned*)(lds + (bufoff) + ldsw + _i * 8192), 16, 0, 0); } while (0)
; #define PG8_LDA(dst, b, h) do { _Pragma("unroll") for (int m = 0; m < 4; ++m) _Pragma("unroll") for (int k = 0; k < 2; ++k) dst[m][k] = *(const PG8_LAS bf16x8*)(lds + PG8_SA(b, h) + aoff + m * 2048 + k * 1024); } while (0)
; #define PG8_LDB(dst, b, h) do { _Pragma("unroll") for (int n = 0; n < 2; ++n) _Pragma("unroll") for (int k = 0; k < 2; ++k) dst[n][k] = *(const PG8_LAS bf16x8*)(lds + PG8_SB(b, h) + boff + n * 2048 + k * 1024); } while (0)
; #define PG8_MMA(ai, bj, At, Bt) do { __builtin_amdgcn_s_setprio(1); _Pragma("unroll") for (int m = 0; m < 4; ++m) _Pragma("unroll") for (int n = 0; n < 2; ++n) _Pragma("unroll") for (int k = 0; k < 2; ++k) \
;         acc[ai][bj][m][n] = __builtin_amdgcn_mfma_f32_16x16x32_bf16(Bt[n][k], At[m][k], acc[ai][bj][m][n], 0, 0, 0); __builtin_amdgcn_s_setprio(0); } while (0)
; #define PG8_WAIT_V(n) asm volatile("s_waitcnt vmcnt(" #n ")" ::: "memory")
; #define PG8_WAIT_L(n) asm volatile("s_waitcnt lgkmcnt(" #n ")" ::: "memory")
; #define PG8_BAR __builtin_amdgcn_s_barrier()
; #define PG8_SCHED __builtin_amdgcn_sched_barrier(0)
; template <class Epi, class Sched, bool ALIGN_EPI = false, bool SP2 = false>
; __device__ __forceinline__ void gemm_phase(PG8_LAS unsigned char* lds, const Gemm g, const Sched& S, const Epi& E) {
;     ...
;             PG8_LDB(B0, 1, 0); PG8_LDB(B1, 1, 1); PG8_SCHED; PG8_LDA(At, 1, 0); PG8_STAGE(PG8_SA(0, 1), a2 + hstep, voffA);
;             PG8_WAIT_V(8); PG8_WAIT_L(0); PG8_BAR; PG8_MMA(0, 0, At, B0); PG8_MMA(0, 1, At, B1); PG8_BAR; PG8_SCHED;
;             PG8_LDA(At, 1, 1); PG8_STAGE(PG8_SB(1, 0), b3, voffB); PG8_STAGE(PG8_SB(1, 1), b3 + hstep, voffB); PG8_STAGE(PG8_SA(1, 0), a3, voffA);
;             PG8_WAIT_V(8); PG8_WAIT_L(0); PG8_BAR; PG8_MMA(1, 0, At, B0); PG8_MMA(1, 1, At, B1); PG8_BAR; PG8_SCHED;
	s_add_i32 s33, 0, 0x18000
	s_add_i32 s42, 0, 0x1c000
	ds_read_b128 v[130:133], v241 offset:32768
	ds_read_b128 v[134:137], v241 offset:33792
	ds_read_b128 v[138:141], v241 offset:34816
	ds_read_b128 v[142:145], v241 offset:35840
	ds_read_b128 v[146:149], v241 offset:49152
	ds_read_b128 v[150:153], v241 offset:50176
	ds_read_b128 v[170:173], v241 offset:51200
	ds_read_b128 v[174:177], v241 offset:52224
	s_add_u32 s20, s20, 0x2b0000
	s_addc_u32 s21, s21, 0
	s_mov_b32 m0, s27
	ds_read_b128 v[178:181], v184 offset:32768
	ds_read_b128 v[186:189], v184 offset:33792
	ds_read_b128 v[190:193], v184 offset:34816
	ds_read_b128 v[194:197], v184 offset:35840
	ds_read_b128 v[198:201], v184 offset:36864
	ds_read_b128 v[202:205], v184 offset:37888
	ds_read_b128 v[206:209], v184 offset:38912
	ds_read_b128 v[210:213], v184 offset:39936
	global_load_lds_dwordx4 v154, s[20:21]
	s_mov_b32 m0, s28
	s_nop 0
	global_load_lds_dwordx4 v158, s[20:21]
	s_waitcnt vmcnt(8)
	s_waitcnt lgkmcnt(0)
	s_barrier
	s_setprio 0
	s_waitcnt lgkmcnt(0)
	v_mfma_f32_16x16x32_bf16 v[114:117], v[130:133], v[178:181], v[114:117]
	v_mfma_f32_16x16x32_bf16 v[118:121], v[138:141], v[178:181], v[118:121]
	v_mfma_f32_16x16x32_bf16 v[106:109], v[130:133], v[190:193], v[106:109]
	v_mfma_f32_16x16x32_bf16 v[98:101], v[138:141], v[190:193], v[98:101]
	v_mfma_f32_16x16x32_bf16 v[90:93], v[130:133], v[198:201], v[90:93]
	v_mfma_f32_16x16x32_bf16 v[82:85], v[138:141], v[198:201], v[82:85]
	v_mfma_f32_16x16x32_bf16 v[74:77], v[130:133], v[206:209], v[74:77]
	v_mfma_f32_16x16x32_bf16 v[66:69], v[138:141], v[206:209], v[66:69]
	v_mfma_f32_16x16x32_bf16 v[114:117], v[134:137], v[186:189], v[114:117]
	v_mfma_f32_16x16x32_bf16 v[118:121], v[142:145], v[186:189], v[118:121]
	v_mfma_f32_16x16x32_bf16 v[106:109], v[134:137], v[194:197], v[106:109]
	v_mfma_f32_16x16x32_bf16 v[98:101], v[142:145], v[194:197], v[98:101]
	v_mfma_f32_16x16x32_bf16 v[90:93], v[134:137], v[202:205], v[90:93]
	v_mfma_f32_16x16x32_bf16 v[82:85], v[142:145], v[202:205], v[82:85]
	v_mfma_f32_16x16x32_bf16 v[74:77], v[134:137], v[210:213], v[74:77]
	v_mfma_f32_16x16x32_bf16 v[66:69], v[142:145], v[210:213], v[66:69]
	v_mfma_f32_16x16x32_bf16 v[122:125], v[146:149], v[178:181], v[122:125]
	v_mfma_f32_16x16x32_bf16 v[126:129], v[170:173], v[178:181], v[126:129]
	v_mfma_f32_16x16x32_bf16 v[110:113], v[146:149], v[190:193], v[110:113]
	v_mfma_f32_16x16x32_bf16 v[102:105], v[170:173], v[190:193], v[102:105]
	v_mfma_f32_16x16x32_bf16 v[94:97], v[146:149], v[198:201], v[94:97]
	v_mfma_f32_16x16x32_bf16 v[86:89], v[170:173], v[198:201], v[86:89]
	v_mfma_f32_16x16x32_bf16 v[78:81], v[146:149], v[206:209], v[78:81]
	v_mfma_f32_16x16x32_bf16 v[70:73], v[170:173], v[206:209], v[70:73]
	v_mfma_f32_16x16x32_bf16 v[122:125], v[150:153], v[186:189], v[122:125]
	v_mfma_f32_16x16x32_bf16 v[126:129], v[174:177], v[186:189], v[126:129]
	v_mfma_f32_16x16x32_bf16 v[110:113], v[150:153], v[194:197], v[110:113]
	v_mfma_f32_16x16x32_bf16 v[102:105], v[174:177], v[194:197], v[102:105]
	v_mfma_f32_16x16x32_bf16 v[94:97], v[150:153], v[202:205], v[94:97]
	v_mfma_f32_16x16x32_bf16 v[86:89], v[174:177], v[202:205], v[86:89]
	v_mfma_f32_16x16x32_bf16 v[78:81], v[150:153], v[210:213], v[78:81]
	v_mfma_f32_16x16x32_bf16 v[70:73], v[174:177], v[210:213], v[70:73]
	s_setprio 1
	s_barrier
	s_add_i32 s20, s33, s24
	s_add_i32 m0, s20, 0xffffff80
	ds_read_b128 v[178:181], v184 offset:49152
	ds_read_b128 v[186:189], v184 offset:50176
	ds_read_b128 v[190:193], v184 offset:51200
	ds_read_b128 v[194:197], v184 offset:52224
	ds_read_b128 v[198:201], v184 offset:53248
	ds_read_b128 v[202:205], v184 offset:54272
	ds_read_b128 v[206:209], v184 offset:55296
	ds_read_b128 v[210:213], v184 offset:56320
	global_load_lds_dwordx4 v156, s[16:17] offset:128
	s_add_i32 m0, s20, 0x1f80
	s_add_i32 s20, s42, s24
	global_load_lds_dwordx4 v160, s[16:17] offset:128
	s_add_u32 s16, s16, 0x2b0080
	s_addc_u32 s17, s17, 0
	s_mov_b32 m0, s20
	s_nop 0
	global_load_lds_dwordx4 v156, s[16:17]
	s_add_i32 m0, s20, 0x2000
	s_nop 0
	global_load_lds_dwordx4 v160, s[16:17]
	s_mov_b32 m0, s30
	s_nop 0
	global_load_lds_dwordx4 v154, s[100:101]
	s_mov_b32 m0, s31
	s_nop 0
	global_load_lds_dwordx4 v158, s[100:101]
	s_waitcnt vmcnt(8)
	s_waitcnt lgkmcnt(0)
	s_barrier
	s_setprio 0
	s_waitcnt lgkmcnt(0)
	v_mfma_f32_16x16x32_bf16 v[58:61], v[130:133], v[178:181], v[58:61]
	v_mfma_f32_16x16x32_bf16 v[54:57], v[138:141], v[178:181], v[54:57]
	v_mfma_f32_16x16x32_bf16 v[42:45], v[130:133], v[190:193], v[42:45]
	v_mfma_f32_16x16x32_bf16 v[34:37], v[138:141], v[190:193], v[34:37]
	v_mfma_f32_16x16x32_bf16 v[26:29], v[130:133], v[198:201], v[26:29]
	v_mfma_f32_16x16x32_bf16 v[18:21], v[138:141], v[198:201], v[18:21]
	v_mfma_f32_16x16x32_bf16 v[6:9], v[130:133], v[206:209], v[6:9]
	v_mfma_f32_16x16x32_bf16 v[2:5], v[138:141], v[206:209], v[2:5]
	v_mfma_f32_16x16x32_bf16 v[58:61], v[134:137], v[186:189], v[58:61]
	v_mfma_f32_16x16x32_bf16 v[54:57], v[142:145], v[186:189], v[54:57]
	v_mfma_f32_16x16x32_bf16 v[42:45], v[134:137], v[194:197], v[42:45]
	v_mfma_f32_16x16x32_bf16 v[34:37], v[142:145], v[194:197], v[34:37]
	v_mfma_f32_16x16x32_bf16 v[26:29], v[134:137], v[202:205], v[26:29]
	v_mfma_f32_16x16x32_bf16 v[18:21], v[142:145], v[202:205], v[18:21]
	v_mfma_f32_16x16x32_bf16 v[6:9], v[134:137], v[210:213], v[6:9]
	v_mfma_f32_16x16x32_bf16 v[2:5], v[142:145], v[210:213], v[2:5]
	v_mfma_f32_16x16x32_bf16 v[62:65], v[146:149], v[178:181], v[62:65]
	v_mfma_f32_16x16x32_bf16 v[50:53], v[170:173], v[178:181], v[50:53]
	v_mfma_f32_16x16x32_bf16 v[46:49], v[146:149], v[190:193], v[46:49]
	v_mfma_f32_16x16x32_bf16 v[38:41], v[170:173], v[190:193], v[38:41]
	v_mfma_f32_16x16x32_bf16 v[30:33], v[146:149], v[198:201], v[30:33]
	v_mfma_f32_16x16x32_bf16 v[22:25], v[170:173], v[198:201], v[22:25]
	v_mfma_f32_16x16x32_bf16 v[10:13], v[146:149], v[206:209], v[10:13]
	v_mfma_f32_16x16x32_bf16 v[14:17], v[170:173], v[206:209], v[14:17]
	v_mfma_f32_16x16x32_bf16 v[62:65], v[150:153], v[186:189], v[62:65]
	v_mfma_f32_16x16x32_bf16 v[50:53], v[174:177], v[186:189], v[50:53]
	v_mfma_f32_16x16x32_bf16 v[46:49], v[150:153], v[194:197], v[46:49]
	v_mfma_f32_16x16x32_bf16 v[38:41], v[174:177], v[194:197], v[38:41]
	v_mfma_f32_16x16x32_bf16 v[30:33], v[150:153], v[202:205], v[30:33]
	v_mfma_f32_16x16x32_bf16 v[22:25], v[174:177], v[202:205], v[22:25]
	v_mfma_f32_16x16x32_bf16 v[10:13], v[150:153], v[210:213], v[10:13]
	v_mfma_f32_16x16x32_bf16 v[14:17], v[174:177], v[210:213], v[14:17]
	s_setprio 1
	s_barrier
	s_add_i32 s48, s48, 2
	s_add_u32 s18, s18, 0x100
	s_addc_u32 s19, s19, 0
	s_add_u32 s46, s46, 0x100
	s_addc_u32 s47, s47, 0
	s_cmpk_gt_u32 s48, 0xa9
	s_cbranch_scc0 .LBB0_1801
	s_and_b64 vcc, exec, s[12:13]
	s_cbranch_vccz .LBB0_1804
	s_barrier
